# GEMM loops: LDS-DMA global addresses via SGPR base + VGPR offset (no per-DMA 64-bit VALU add), code placement preserved with pads; attention per-section setprio + max3 tree
# baseline (speedup 1.0000x reference)
; #define PG8_STAGE(bufoff, gbase, voff) do { _Pragma("unroll") for (int _i = 0; _i < 2; ++_i) \
;         __builtin_amdgcn_global_load_lds((const unsigned*)((const char*)(gbase) + (voff)[_i]), (LAS unsigned*)(lds + (bufoff) + ldsw + _i * 8192), 16, 0, 0); } while (0)
; #define PG8_LDA(dst, b, h) do { _Pragma("unroll") for (int m = 0; m < 4; ++m) _Pragma("unroll") for (int k = 0; k < 2; ++k) dst[m][k] = *(const LAS bf16x8*)(lds + PG8_SA(b, h) + aoff + m * 2048 + k * 1024); } while (0)
; #define PG8_LDB(dst, b, h) do { _Pragma("unroll") for (int n = 0; n < 2; ++n) _Pragma("unroll") for (int k = 0; k < 2; ++k) dst[n][k] = *(const LAS bf16x8*)(lds + PG8_SB(b, h) + boff + n * 2048 + k * 1024); } while (0)
; #define PG8_MMA(ai, bj, At, Bt) do { __builtin_amdgcn_s_setprio(1); _Pragma("unroll") for (int m = 0; m < 4; ++m) _Pragma("unroll") for (int n = 0; n < 2; ++n) _Pragma("unroll") for (int k = 0; k < 2; ++k) \
;         acc[ai][bj][m][n] = __builtin_amdgcn_mfma_f32_16x16x32_bf16(Bt[n][k], At[m][k], acc[ai][bj][m][n], 0, 0, 0); __builtin_amdgcn_s_setprio(0); } while (0)
; #define PG8_WAIT_V(n) asm volatile("s_waitcnt vmcnt(" #n ")" ::: "memory")
; #define PG8_WAIT_L(n) asm volatile("s_waitcnt lgkmcnt(" #n ")" ::: "memory")
; #define PG8_BAR __builtin_amdgcn_s_barrier()
; template <class Epi, class Sched, bool ALIGN_EPI = false, bool SP2 = false>
; __device__ __forceinline__ void gemm_phase(LAS unsigned char* lds, const Gemm g, const Sched& S, const Epi& E) {
;     ...
;             const char* a1 = cA + (size_t)(t + 1) * kstep;
;             const char* a2 = last ? nA : cA + (size_t)(t + 2) * kstep; const char* b2 = last ? nB : cB + (size_t)(t + 2) * kstep;
;             const char* a3 = a2 + kstep; const char* b3 = b2 + kstep;
;             if (last && has_next) { S.a_ready(nxt); pre_nxt = E.pre(nxt, wr, fr); }
;             if constexpr (SP2) {
;             PG8_LDB(B0, 0, 0); PG8_LDB(B1, 0, 1); PG8_SCHED; PG8_LDA(At, 0, 0); PG8_STAGE(PG8_SA(1, 1), a1 + hstep, voffA);
;             PG8_WAIT_V(8); PG8_WAIT_L(0); PG8_BAR; PG8_MMA(0, 0, At, B0); PG8_MMA(0, 1, At, B1); PG8_BAR; PG8_SCHED;
;             PG8_LDA(At, 0, 1); PG8_STAGE(PG8_SB(0, 0), b2, voffB); PG8_STAGE(PG8_SB(0, 1), b2 + hstep, voffB); PG8_STAGE(PG8_SA(0, 0), a2, voffA);
;             PG8_WAIT_V(8); PG8_WAIT_L(0); PG8_BAR; PG8_MMA(1, 0, At, B0); PG8_MMA(1, 1, At, B1); PG8_BAR; PG8_SCHED;
.LBB0_146:
	v_add_u32_e32 v169, s70, v150
	ds_read_b128 v[170:173], v169
	ds_read_b128 v[178:181], v169 offset:1024
	ds_read_b128 v[182:185], v169 offset:2048
	ds_read_b128 v[190:193], v169 offset:3072
	v_add_u32_e32 v169, s71, v150
	ds_read_b128 v[194:197], v169
	ds_read_b128 v[198:201], v169 offset:1024
	ds_read_b128 v[202:205], v169 offset:2048
	ds_read_b128 v[206:209], v169 offset:3072
	s_add_u32 s48, s44, 0xfff80080
	s_addc_u32 s49, s45, -1
	s_and_b64 s[46:47], s[46:47], exec
	s_cselect_b32 s49, s29, s49
	s_cselect_b32 s48, s86, s48
	s_cselect_b32 s47, s11, s16
	s_cselect_b32 s46, s87, s88
	s_add_u32 s98, s46, 0x80
	s_addc_u32 s99, s47, 0
	s_add_u32 s100, s48, 0x80
	s_addc_u32 s101, s49, 0
	s_add_i32 m0, s43, 0xc000
	ds_read_b128 v[210:213], v152
	ds_read_b128 v[214:217], v152 offset:1024
	ds_read_b128 v[218:221], v152 offset:2048
	ds_read_b128 v[222:225], v152 offset:3072
	ds_read_b128 v[226:229], v152 offset:4096
	ds_read_b128 v[230:233], v152 offset:5120
	ds_read_b128 v[234:237], v152 offset:6144
	ds_read_b128 v[238:241], v152 offset:7168
	global_load_lds_dwordx4 v138, s[44:45]
	s_add_i32 m0, s43, 0xe000
	s_nop 0
	global_load_lds_dwordx4 v140, s[44:45]
	s_waitcnt vmcnt(8)
	s_waitcnt lgkmcnt(0)
	s_barrier
	s_setprio 1
	s_waitcnt lgkmcnt(0)
	v_mfma_f32_16x16x32_bf16 v[124:127], v[170:173], v[210:213], v[124:127]
	v_mfma_f32_16x16x32_bf16 v[120:123], v[182:185], v[210:213], v[120:123]
	v_mfma_f32_16x16x32_bf16 v[108:111], v[170:173], v[218:221], v[108:111]
	v_mfma_f32_16x16x32_bf16 v[104:107], v[182:185], v[218:221], v[104:107]
	v_mfma_f32_16x16x32_bf16 v[92:95], v[170:173], v[226:229], v[92:95]
	v_mfma_f32_16x16x32_bf16 v[88:91], v[182:185], v[226:229], v[88:91]
	v_mfma_f32_16x16x32_bf16 v[76:79], v[170:173], v[234:237], v[76:79]
	v_mfma_f32_16x16x32_bf16 v[72:75], v[182:185], v[234:237], v[72:75]
	v_mfma_f32_16x16x32_bf16 v[124:127], v[178:181], v[214:217], v[124:127]
	v_mfma_f32_16x16x32_bf16 v[120:123], v[190:193], v[214:217], v[120:123]
	v_mfma_f32_16x16x32_bf16 v[108:111], v[178:181], v[222:225], v[108:111]
	v_mfma_f32_16x16x32_bf16 v[104:107], v[190:193], v[222:225], v[104:107]
	v_mfma_f32_16x16x32_bf16 v[92:95], v[178:181], v[230:233], v[92:95]
	v_mfma_f32_16x16x32_bf16 v[88:91], v[190:193], v[230:233], v[88:91]
	v_mfma_f32_16x16x32_bf16 v[76:79], v[178:181], v[238:241], v[76:79]
	v_mfma_f32_16x16x32_bf16 v[72:75], v[190:193], v[238:241], v[72:75]
	s_setprio 0
	s_setprio 1
	v_mfma_f32_16x16x32_bf16 v[116:119], v[194:197], v[210:213], v[116:119]
	v_mfma_f32_16x16x32_bf16 v[112:115], v[202:205], v[210:213], v[112:115]
	v_mfma_f32_16x16x32_bf16 v[100:103], v[194:197], v[218:221], v[100:103]
	v_mfma_f32_16x16x32_bf16 v[96:99], v[202:205], v[218:221], v[96:99]
	v_mfma_f32_16x16x32_bf16 v[84:87], v[194:197], v[226:229], v[84:87]
	v_mfma_f32_16x16x32_bf16 v[80:83], v[202:205], v[226:229], v[80:83]
	v_mfma_f32_16x16x32_bf16 v[68:71], v[194:197], v[234:237], v[68:71]
	v_mfma_f32_16x16x32_bf16 v[64:67], v[202:205], v[234:237], v[64:67]
	v_mfma_f32_16x16x32_bf16 v[116:119], v[198:201], v[214:217], v[116:119]
	v_mfma_f32_16x16x32_bf16 v[112:115], v[206:209], v[214:217], v[112:115]
	v_mfma_f32_16x16x32_bf16 v[100:103], v[198:201], v[222:225], v[100:103]
	v_mfma_f32_16x16x32_bf16 v[96:99], v[206:209], v[222:225], v[96:99]
	v_mfma_f32_16x16x32_bf16 v[84:87], v[198:201], v[230:233], v[84:87]
	v_mfma_f32_16x16x32_bf16 v[80:83], v[206:209], v[230:233], v[80:83]
	v_mfma_f32_16x16x32_bf16 v[68:71], v[198:201], v[238:241], v[68:71]
	v_mfma_f32_16x16x32_bf16 v[64:67], v[206:209], v[238:241], v[64:67]
	s_setprio 0
	s_barrier
	s_add_i32 s74, s70, s15
	s_mov_b32 m0, s74
	ds_read_b128 v[210:213], v152 offset:16384
	ds_read_b128 v[214:217], v152 offset:17408
	ds_read_b128 v[218:221], v152 offset:18432
	ds_read_b128 v[222:225], v152 offset:19456
	ds_read_b128 v[226:229], v152 offset:20480
	ds_read_b128 v[230:233], v152 offset:21504
	ds_read_b128 v[234:237], v152 offset:22528
	ds_read_b128 v[238:241], v152 offset:23552
	global_load_lds_dwordx4 v132, s[46:47]
	s_add_i32 m0, s74, 0x2000
	s_add_u32 s90, s46, 0x80000
	s_addc_u32 s91, s47, 0
	s_add_i32 s74, s71, s15
	global_load_lds_dwordx4 v128, s[46:47]
	s_mov_b32 m0, s74
	s_nop 0
	global_load_lds_dwordx4 v132, s[90:91]
	s_add_i32 m0, s74, 0x2000
	s_nop 0
	global_load_lds_dwordx4 v128, s[90:91]
	s_mov_b32 m0, s43
	s_nop 0
	global_load_lds_dwordx4 v134, s[48:49]
	s_mov_b32 m0, s50
	s_nop 0
	global_load_lds_dwordx4 v130, s[48:49]
	s_waitcnt vmcnt(8)
	s_waitcnt lgkmcnt(0)
	s_barrier
	s_setprio 1
	s_waitcnt lgkmcnt(0)
	v_mfma_f32_16x16x32_bf16 v[60:63], v[170:173], v[210:213], v[60:63]
	v_mfma_f32_16x16x32_bf16 v[56:59], v[182:185], v[210:213], v[56:59]
	v_mfma_f32_16x16x32_bf16 v[44:47], v[170:173], v[218:221], v[44:47]
	v_mfma_f32_16x16x32_bf16 v[40:43], v[182:185], v[218:221], v[40:43]
	v_mfma_f32_16x16x32_bf16 v[28:31], v[170:173], v[226:229], v[28:31]
	v_mfma_f32_16x16x32_bf16 v[24:27], v[182:185], v[226:229], v[24:27]
	v_mfma_f32_16x16x32_bf16 v[12:15], v[170:173], v[234:237], v[12:15]
	v_mfma_f32_16x16x32_bf16 v[8:11], v[182:185], v[234:237], v[8:11]
	v_mfma_f32_16x16x32_bf16 v[60:63], v[178:181], v[214:217], v[60:63]
	v_mfma_f32_16x16x32_bf16 v[56:59], v[190:193], v[214:217], v[56:59]
	v_mfma_f32_16x16x32_bf16 v[44:47], v[178:181], v[222:225], v[44:47]
	v_mfma_f32_16x16x32_bf16 v[40:43], v[190:193], v[222:225], v[40:43]
	v_mfma_f32_16x16x32_bf16 v[28:31], v[178:181], v[230:233], v[28:31]
	v_mfma_f32_16x16x32_bf16 v[24:27], v[190:193], v[230:233], v[24:27]
	v_mfma_f32_16x16x32_bf16 v[12:15], v[178:181], v[238:241], v[12:15]
	v_mfma_f32_16x16x32_bf16 v[8:11], v[190:193], v[238:241], v[8:11]
	s_setprio 0
	s_setprio 1
	v_mfma_f32_16x16x32_bf16 v[52:55], v[194:197], v[210:213], v[52:55]
	v_mfma_f32_16x16x32_bf16 v[48:51], v[202:205], v[210:213], v[48:51]
	v_mfma_f32_16x16x32_bf16 v[36:39], v[194:197], v[218:221], v[36:39]
	v_mfma_f32_16x16x32_bf16 v[32:35], v[202:205], v[218:221], v[32:35]
	v_mfma_f32_16x16x32_bf16 v[20:23], v[194:197], v[226:229], v[20:23]
	v_mfma_f32_16x16x32_bf16 v[16:19], v[202:205], v[226:229], v[16:19]
	v_mfma_f32_16x16x32_bf16 v[4:7], v[194:197], v[234:237], v[4:7]
	v_mfma_f32_16x16x32_bf16 v[0:3], v[202:205], v[234:237], v[0:3]
	v_mfma_f32_16x16x32_bf16 v[52:55], v[198:201], v[214:217], v[52:55]
	v_mfma_f32_16x16x32_bf16 v[48:51], v[206:209], v[214:217], v[48:51]
	v_mfma_f32_16x16x32_bf16 v[36:39], v[198:201], v[222:225], v[36:39]
	v_mfma_f32_16x16x32_bf16 v[32:35], v[206:209], v[222:225], v[32:35]
	v_mfma_f32_16x16x32_bf16 v[20:23], v[198:201], v[230:233], v[20:23]
	v_mfma_f32_16x16x32_bf16 v[16:19], v[206:209], v[230:233], v[16:19]
	v_mfma_f32_16x16x32_bf16 v[4:7], v[198:201], v[238:241], v[4:7]
	v_mfma_f32_16x16x32_bf16 v[0:3], v[206:209], v[238:241], v[0:3]
	s_setprio 0
	s_barrier
; #define PG8_STAGE(bufoff, gbase, voff) do { _Pragma("unroll") for (int _i = 0; _i < 2; ++_i) \
;         __builtin_amdgcn_global_load_lds((const unsigned*)((const char*)(gbase) + (voff)[_i]), (LAS unsigned*)(lds + (bufoff) + ldsw + _i * 8192), 16, 0, 0); } while (0)
; #define PG8_LDA(dst, b, h) do { _Pragma("unroll") for (int m = 0; m < 4; ++m) _Pragma("unroll") for (int k = 0; k < 2; ++k) dst[m][k] = *(const LAS bf16x8*)(lds + PG8_SA(b, h) + aoff + m * 2048 + k * 1024); } while (0)
; #define PG8_LDB(dst, b, h) do { _Pragma("unroll") for (int n = 0; n < 2; ++n) _Pragma("unroll") for (int k = 0; k < 2; ++k) dst[n][k] = *(const LAS bf16x8*)(lds + PG8_SB(b, h) + boff + n * 2048 + k * 1024); } while (0)
; #define PG8_MMA(ai, bj, At, Bt) do { __builtin_amdgcn_s_setprio(1); _Pragma("unroll") for (int m = 0; m < 4; ++m) _Pragma("unroll") for (int n = 0; n < 2; ++n) _Pragma("unroll") for (int k = 0; k < 2; ++k) \
;         acc[ai][bj][m][n] = __builtin_amdgcn_mfma_f32_16x16x32_bf16(Bt[n][k], At[m][k], acc[ai][bj][m][n], 0, 0, 0); __builtin_amdgcn_s_setprio(0); } while (0)
; #define PG8_WAIT_V(n) asm volatile("s_waitcnt vmcnt(" #n ")" ::: "memory")
; #define PG8_WAIT_L(n) asm volatile("s_waitcnt lgkmcnt(" #n ")" ::: "memory")
; #define PG8_BAR __builtin_amdgcn_s_barrier()
; #define PG8_SCHED __builtin_amdgcn_sched_barrier(0)
; template <class Epi, class Sched, bool ALIGN_EPI = false, bool SP2 = false>
; __device__ __forceinline__ void gemm_phase(LAS unsigned char* lds, const Gemm g, const Sched& S, const Epi& E) {
;     ...
;             PG8_LDB(B0, 1, 0); PG8_LDB(B1, 1, 1); PG8_SCHED; PG8_LDA(At, 1, 0); PG8_STAGE(PG8_SA(0, 1), a2 + hstep, voffA);
;             PG8_WAIT_V(8); PG8_WAIT_L(0); PG8_BAR; PG8_MMA(0, 0, At, B0); PG8_MMA(0, 1, At, B1); PG8_BAR; PG8_SCHED;
;             PG8_LDA(At, 1, 1); PG8_STAGE(PG8_SB(1, 0), b3, voffB); PG8_STAGE(PG8_SB(1, 1), b3 + hstep, voffB); PG8_STAGE(PG8_SA(1, 0), a3, voffA);
;             PG8_WAIT_V(8); PG8_WAIT_L(0); PG8_BAR; PG8_MMA(1, 0, At, B0); PG8_MMA(1, 1, At, B1); PG8_BAR; PG8_SCHED;
	s_add_i32 s74, 0, 0x18000
	v_add_u32_e32 v169, s74, v150
	s_add_i32 s89, 0, 0x1c000
	ds_read_b128 v[170:173], v169
	ds_read_b128 v[178:181], v169 offset:1024
	ds_read_b128 v[182:185], v169 offset:2048
	ds_read_b128 v[190:193], v169 offset:3072
	v_add_u32_e32 v169, s89, v150
	ds_read_b128 v[194:197], v169
	ds_read_b128 v[198:201], v169 offset:1024
	ds_read_b128 v[202:205], v169 offset:2048
	ds_read_b128 v[206:209], v169 offset:3072
	s_add_u32 s48, s48, 0x80000
	s_addc_u32 s49, s49, 0
	s_mov_b32 m0, s51
	ds_read_b128 v[210:213], v152 offset:32768
	ds_read_b128 v[214:217], v152 offset:33792
	ds_read_b128 v[218:221], v152 offset:34816
	ds_read_b128 v[222:225], v152 offset:35840
	ds_read_b128 v[226:229], v152 offset:36864
	ds_read_b128 v[230:233], v152 offset:37888
	ds_read_b128 v[234:237], v152 offset:38912
	ds_read_b128 v[238:241], v152 offset:39936
	global_load_lds_dwordx4 v134, s[48:49]
	s_mov_b32 m0, s66
	s_nop 0
	global_load_lds_dwordx4 v130, s[48:49]
	s_waitcnt vmcnt(8)
	s_waitcnt lgkmcnt(0)
	s_barrier
	s_setprio 1
	s_waitcnt lgkmcnt(0)
	v_mfma_f32_16x16x32_bf16 v[124:127], v[170:173], v[210:213], v[124:127]
	v_mfma_f32_16x16x32_bf16 v[120:123], v[182:185], v[210:213], v[120:123]
	v_mfma_f32_16x16x32_bf16 v[108:111], v[170:173], v[218:221], v[108:111]
	v_mfma_f32_16x16x32_bf16 v[104:107], v[182:185], v[218:221], v[104:107]
	v_mfma_f32_16x16x32_bf16 v[92:95], v[170:173], v[226:229], v[92:95]
	v_mfma_f32_16x16x32_bf16 v[88:91], v[182:185], v[226:229], v[88:91]
	v_mfma_f32_16x16x32_bf16 v[76:79], v[170:173], v[234:237], v[76:79]
	v_mfma_f32_16x16x32_bf16 v[72:75], v[182:185], v[234:237], v[72:75]
	v_mfma_f32_16x16x32_bf16 v[124:127], v[178:181], v[214:217], v[124:127]
	v_mfma_f32_16x16x32_bf16 v[120:123], v[190:193], v[214:217], v[120:123]
	v_mfma_f32_16x16x32_bf16 v[108:111], v[178:181], v[222:225], v[108:111]
	v_mfma_f32_16x16x32_bf16 v[104:107], v[190:193], v[222:225], v[104:107]
	v_mfma_f32_16x16x32_bf16 v[92:95], v[178:181], v[230:233], v[92:95]
	v_mfma_f32_16x16x32_bf16 v[88:91], v[190:193], v[230:233], v[88:91]
	v_mfma_f32_16x16x32_bf16 v[76:79], v[178:181], v[238:241], v[76:79]
	v_mfma_f32_16x16x32_bf16 v[72:75], v[190:193], v[238:241], v[72:75]
	s_setprio 0
	s_setprio 1
	v_mfma_f32_16x16x32_bf16 v[116:119], v[194:197], v[210:213], v[116:119]
	v_mfma_f32_16x16x32_bf16 v[112:115], v[202:205], v[210:213], v[112:115]
	v_mfma_f32_16x16x32_bf16 v[100:103], v[194:197], v[218:221], v[100:103]
	v_mfma_f32_16x16x32_bf16 v[96:99], v[202:205], v[218:221], v[96:99]
	v_mfma_f32_16x16x32_bf16 v[84:87], v[194:197], v[226:229], v[84:87]
	v_mfma_f32_16x16x32_bf16 v[80:83], v[202:205], v[226:229], v[80:83]
	v_mfma_f32_16x16x32_bf16 v[68:71], v[194:197], v[234:237], v[68:71]
	v_mfma_f32_16x16x32_bf16 v[64:67], v[202:205], v[234:237], v[64:67]
	v_mfma_f32_16x16x32_bf16 v[116:119], v[198:201], v[214:217], v[116:119]
	v_mfma_f32_16x16x32_bf16 v[112:115], v[206:209], v[214:217], v[112:115]
	v_mfma_f32_16x16x32_bf16 v[100:103], v[198:201], v[222:225], v[100:103]
	v_mfma_f32_16x16x32_bf16 v[96:99], v[206:209], v[222:225], v[96:99]
	v_mfma_f32_16x16x32_bf16 v[84:87], v[198:201], v[230:233], v[84:87]
	v_mfma_f32_16x16x32_bf16 v[80:83], v[206:209], v[230:233], v[80:83]
	v_mfma_f32_16x16x32_bf16 v[68:71], v[198:201], v[238:241], v[68:71]
	v_mfma_f32_16x16x32_bf16 v[64:67], v[206:209], v[238:241], v[64:67]
	s_setprio 0
	s_barrier
	s_add_i32 s48, s74, s15
	s_mov_b32 m0, s48
	ds_read_b128 v[210:213], v152 offset:49152
	ds_read_b128 v[214:217], v152 offset:50176
	ds_read_b128 v[218:221], v152 offset:51200
	ds_read_b128 v[222:225], v152 offset:52224
	ds_read_b128 v[226:229], v152 offset:53248
	ds_read_b128 v[230:233], v152 offset:54272
	ds_read_b128 v[234:237], v152 offset:55296
	ds_read_b128 v[238:241], v152 offset:56320
	global_load_lds_dwordx4 v132, s[98:99]
	s_add_i32 m0, s48, 0x2000
	s_add_u32 s46, s46, 0x80080
	s_addc_u32 s47, s47, 0
	s_add_i32 s48, s89, s15
	global_load_lds_dwordx4 v128, s[98:99]
	s_mov_b32 m0, s48
	s_nop 0
	global_load_lds_dwordx4 v132, s[46:47]
	s_add_i32 m0, s48, 0x2000
	s_nop 0
	global_load_lds_dwordx4 v128, s[46:47]
	s_mov_b32 m0, s68
	s_nop 0
	global_load_lds_dwordx4 v134, s[100:101]
	s_mov_b32 m0, s69
	s_nop 0
	global_load_lds_dwordx4 v130, s[100:101]
	s_waitcnt vmcnt(8)
	s_waitcnt lgkmcnt(0)
	s_barrier
	s_setprio 1
	s_waitcnt lgkmcnt(0)
	v_mfma_f32_16x16x32_bf16 v[60:63], v[170:173], v[210:213], v[60:63]
	v_mfma_f32_16x16x32_bf16 v[56:59], v[182:185], v[210:213], v[56:59]
	v_mfma_f32_16x16x32_bf16 v[44:47], v[170:173], v[218:221], v[44:47]
	v_mfma_f32_16x16x32_bf16 v[40:43], v[182:185], v[218:221], v[40:43]
	v_mfma_f32_16x16x32_bf16 v[28:31], v[170:173], v[226:229], v[28:31]
	v_mfma_f32_16x16x32_bf16 v[24:27], v[182:185], v[226:229], v[24:27]
	v_mfma_f32_16x16x32_bf16 v[12:15], v[170:173], v[234:237], v[12:15]
	v_mfma_f32_16x16x32_bf16 v[8:11], v[182:185], v[234:237], v[8:11]
	v_mfma_f32_16x16x32_bf16 v[60:63], v[178:181], v[214:217], v[60:63]
	v_mfma_f32_16x16x32_bf16 v[56:59], v[190:193], v[214:217], v[56:59]
	v_mfma_f32_16x16x32_bf16 v[44:47], v[178:181], v[222:225], v[44:47]
	v_mfma_f32_16x16x32_bf16 v[40:43], v[190:193], v[222:225], v[40:43]
	v_mfma_f32_16x16x32_bf16 v[28:31], v[178:181], v[230:233], v[28:31]
	v_mfma_f32_16x16x32_bf16 v[24:27], v[190:193], v[230:233], v[24:27]
	v_mfma_f32_16x16x32_bf16 v[12:15], v[178:181], v[238:241], v[12:15]
	v_mfma_f32_16x16x32_bf16 v[8:11], v[190:193], v[238:241], v[8:11]
	s_setprio 0
	s_setprio 1
	v_mfma_f32_16x16x32_bf16 v[52:55], v[194:197], v[210:213], v[52:55]
	v_mfma_f32_16x16x32_bf16 v[48:51], v[202:205], v[210:213], v[48:51]
	v_mfma_f32_16x16x32_bf16 v[36:39], v[194:197], v[218:221], v[36:39]
	v_mfma_f32_16x16x32_bf16 v[32:35], v[202:205], v[218:221], v[32:35]
	v_mfma_f32_16x16x32_bf16 v[20:23], v[194:197], v[226:229], v[20:23]
	v_mfma_f32_16x16x32_bf16 v[16:19], v[202:205], v[226:229], v[16:19]
	v_mfma_f32_16x16x32_bf16 v[4:7], v[194:197], v[234:237], v[4:7]
	v_mfma_f32_16x16x32_bf16 v[0:3], v[202:205], v[234:237], v[0:3]
	v_mfma_f32_16x16x32_bf16 v[52:55], v[198:201], v[214:217], v[52:55]
	v_mfma_f32_16x16x32_bf16 v[48:51], v[206:209], v[214:217], v[48:51]
	v_mfma_f32_16x16x32_bf16 v[36:39], v[198:201], v[222:225], v[36:39]
	v_mfma_f32_16x16x32_bf16 v[32:35], v[206:209], v[222:225], v[32:35]
	v_mfma_f32_16x16x32_bf16 v[20:23], v[198:201], v[230:233], v[20:23]
	v_mfma_f32_16x16x32_bf16 v[16:19], v[206:209], v[230:233], v[16:19]
	v_mfma_f32_16x16x32_bf16 v[4:7], v[198:201], v[238:241], v[4:7]
	v_mfma_f32_16x16x32_bf16 v[0:3], v[206:209], v[238:241], v[0:3]
	s_setprio 0
	s_barrier
	s_add_i32 s17, s17, 2
	s_add_u32 s44, s44, 0x100
	s_addc_u32 s45, s45, 0
	s_add_u32 s88, s88, 0x100
	s_addc_u32 s16, s16, 0
	s_cmp_gt_u32 s17, 29
	s_cbranch_scc1 .LBB0_149
;     __device__ __forceinline__ Pre pre(const Unit& u, int wr, int fr) const { return load_rows8(ss, u, wr, fr); }
;     __device__ __forceinline__ Pre pre(const Unit& u, int wr, int fr) const { return load_rows8(ss, u, wr, fr); }
; template <class Epi, class Sched, bool ALIGN_EPI = false, bool SP2 = false>
; __device__ __forceinline__ void gemm_phase(LAS unsigned char* lds, const Gemm g, const Sched& S, const Epi& E) {
;     ...
;             const bool last = (t == nt - 2);
;             const char* a1 = cA + (size_t)(t + 1) * kstep;
;             const char* a2 = last ? nA : cA + (size_t)(t + 2) * kstep; const char* b2 = last ? nB : cB + (size_t)(t + 2) * kstep;
;             const char* a3 = a2 + kstep; const char* b3 = b2 + kstep;
;             if (last && has_next) { S.a_ready(nxt); pre_nxt = E.pre(nxt, wr, fr); }
; __device__ __forceinline__ PreRows load_rows8(const float* ss, const Unit& u, int wr, int fr) {
;     PreRows p; const float* b = ss + u.pm * BM + wr * 64 + fr;
; #pragma unroll
;     for (int ai = 0; ai < 2; ++ai)
; #pragma unroll
;         for (int m = 0; m < 4; ++m) p.v[ai * 4 + m] = b[ai * HALF + m * 16];
;     return p;
.LBB0_147:
	s_cmp_eq_u32 s17, 28
	s_cselect_b64 s[46:47], -1, 0
	s_and_b64 s[48:49], s[4:5], s[46:47]
	s_andn2_b64 vcc, exec, s[48:49]
	s_cbranch_vccnz .LBB0_146
	global_load_dword v155, v[146:147], off
	global_load_dword v156, v[146:147], off offset:64
	global_load_dword v157, v[146:147], off offset:128
	global_load_dword v158, v[146:147], off offset:192
	global_load_dword v159, v[146:147], off offset:512
	global_load_dword v160, v[146:147], off offset:576
	global_load_dword v162, v[146:147], off offset:640
	global_load_dword v163, v[146:147], off offset:704
	s_branch .LBB0_146
	s_nop 0
	s_nop 0
	s_nop 0
	s_nop 0
	s_nop 0
	s_nop 0
	s_nop 0
	s_nop 0
	s_nop 0
	s_nop 0
	s_nop 0
	s_nop 0
	s_nop 0
	s_nop 0
	s_nop 0
	s_nop 0
	s_nop 0
	s_nop 0
	s_nop 0
	s_nop 0
	s_nop 0
	s_nop 0
	s_nop 0
	s_nop 0
	s_nop 0

; #define PG8_STAGE(bufoff, gbase, voff) do { _Pragma("unroll") for (int _i = 0; _i < 2; ++_i) \
;         __builtin_amdgcn_global_load_lds((const unsigned*)((const char*)(gbase) + (voff)[_i]), (LAS unsigned*)(lds + (bufoff) + ldsw + _i * 8192), 16, 0, 0); } while (0)
; #define PG8_LDA(dst, b, h) do { _Pragma("unroll") for (int m = 0; m < 4; ++m) _Pragma("unroll") for (int k = 0; k < 2; ++k) dst[m][k] = *(const LAS bf16x8*)(lds + PG8_SA(b, h) + aoff + m * 2048 + k * 1024); } while (0)
; #define PG8_LDB(dst, b, h) do { _Pragma("unroll") for (int n = 0; n < 2; ++n) _Pragma("unroll") for (int k = 0; k < 2; ++k) dst[n][k] = *(const LAS bf16x8*)(lds + PG8_SB(b, h) + boff + n * 2048 + k * 1024); } while (0)
; #define PG8_MMA(ai, bj, At, Bt) do { __builtin_amdgcn_s_setprio(1); _Pragma("unroll") for (int m = 0; m < 4; ++m) _Pragma("unroll") for (int n = 0; n < 2; ++n) _Pragma("unroll") for (int k = 0; k < 2; ++k) \
;         acc[ai][bj][m][n] = __builtin_amdgcn_mfma_f32_16x16x32_bf16(Bt[n][k], At[m][k], acc[ai][bj][m][n], 0, 0, 0); __builtin_amdgcn_s_setprio(0); } while (0)
; #define PG8_WAIT_V(n) asm volatile("s_waitcnt vmcnt(" #n ")" ::: "memory")
; #define PG8_WAIT_L(n) asm volatile("s_waitcnt lgkmcnt(" #n ")" ::: "memory")
; #define PG8_BAR __builtin_amdgcn_s_barrier()
; template <class Epi, class Sched, bool ALIGN_EPI = false, bool SP2 = false>
; __device__ __forceinline__ void gemm_phase(LAS unsigned char* lds, const Gemm g, const Sched& S, const Epi& E) {
;     ...
;             const char* a1 = cA + (size_t)(t + 1) * kstep;
;             const char* a2 = last ? nA : cA + (size_t)(t + 2) * kstep; const char* b2 = last ? nB : cB + (size_t)(t + 2) * kstep;
;             const char* a3 = a2 + kstep; const char* b3 = b2 + kstep;
;             if (last && has_next) { S.a_ready(nxt); pre_nxt = E.pre(nxt, wr, fr); }
;             if constexpr (SP2) {
;             PG8_LDB(B0, 0, 0); PG8_LDB(B1, 0, 1); PG8_SCHED; PG8_LDA(At, 0, 0); PG8_STAGE(PG8_SA(1, 1), a1 + hstep, voffA);
;             PG8_WAIT_V(8); PG8_WAIT_L(0); PG8_BAR; PG8_MMA(0, 0, At, B0); PG8_MMA(0, 1, At, B1); PG8_BAR; PG8_SCHED;
;             PG8_LDA(At, 0, 1); PG8_STAGE(PG8_SB(0, 0), b2, voffB); PG8_STAGE(PG8_SB(0, 1), b2 + hstep, voffB); PG8_STAGE(PG8_SA(0, 0), a2, voffA);
;             PG8_WAIT_V(8); PG8_WAIT_L(0); PG8_BAR; PG8_MMA(1, 0, At, B0); PG8_MMA(1, 1, At, B1); PG8_BAR; PG8_SCHED;
.LBB0_231:
	ds_read_b128 v[128:131], v192
	ds_read_b128 v[132:135], v192 offset:1024
	ds_read_b128 v[136:139], v192 offset:2048
	ds_read_b128 v[140:143], v192 offset:3072
	ds_read_b128 v[144:147], v193
	ds_read_b128 v[148:151], v193 offset:1024
	ds_read_b128 v[168:171], v193 offset:2048
	ds_read_b128 v[172:175], v193 offset:3072
	s_add_u32 s44, s42, 0x100
	s_addc_u32 s45, s43, 0
	s_cmpk_eq_i32 s86, 0x54
	s_cselect_b32 s49, s1, s45
	s_cselect_b32 s48, s0, s44
	s_cselect_b32 s47, s41, s17
	s_cselect_b32 s46, s40, s16
	s_add_i32 m0, s35, 0xc000
	ds_read_b128 v[178:181], v194
	ds_read_b128 v[182:185], v194 offset:1024
	ds_read_b128 v[196:199], v194 offset:2048
	ds_read_b128 v[200:203], v194 offset:3072
	ds_read_b128 v[204:207], v194 offset:4096
	ds_read_b128 v[208:211], v194 offset:5120
	ds_read_b128 v[212:215], v194 offset:6144
	ds_read_b128 v[216:219], v194 offset:7168
	global_load_lds_dwordx4 v160, s[42:43]
	s_add_i32 m0, s35, 0xe000
	s_nop 0
	global_load_lds_dwordx4 v162, s[42:43]
	s_waitcnt vmcnt(8)
	s_waitcnt lgkmcnt(0)
	s_barrier
	s_setprio 1
	s_waitcnt lgkmcnt(0)
	v_mfma_f32_16x16x32_bf16 v[124:127], v[128:131], v[178:181], v[124:127]
	v_mfma_f32_16x16x32_bf16 v[120:123], v[136:139], v[178:181], v[120:123]
	v_mfma_f32_16x16x32_bf16 v[108:111], v[128:131], v[196:199], v[108:111]
	v_mfma_f32_16x16x32_bf16 v[104:107], v[136:139], v[196:199], v[104:107]
	v_mfma_f32_16x16x32_bf16 v[92:95], v[128:131], v[204:207], v[92:95]
	v_mfma_f32_16x16x32_bf16 v[88:91], v[136:139], v[204:207], v[88:91]
	v_mfma_f32_16x16x32_bf16 v[76:79], v[128:131], v[212:215], v[76:79]
	v_mfma_f32_16x16x32_bf16 v[72:75], v[136:139], v[212:215], v[72:75]
	v_mfma_f32_16x16x32_bf16 v[124:127], v[132:135], v[182:185], v[124:127]
	v_mfma_f32_16x16x32_bf16 v[120:123], v[140:143], v[182:185], v[120:123]
	v_mfma_f32_16x16x32_bf16 v[108:111], v[132:135], v[200:203], v[108:111]
	v_mfma_f32_16x16x32_bf16 v[104:107], v[140:143], v[200:203], v[104:107]
	v_mfma_f32_16x16x32_bf16 v[92:95], v[132:135], v[208:211], v[92:95]
	v_mfma_f32_16x16x32_bf16 v[88:91], v[140:143], v[208:211], v[88:91]
	v_mfma_f32_16x16x32_bf16 v[76:79], v[132:135], v[216:219], v[76:79]
	v_mfma_f32_16x16x32_bf16 v[72:75], v[140:143], v[216:219], v[72:75]
	s_setprio 0
	s_setprio 1
	v_mfma_f32_16x16x32_bf16 v[116:119], v[144:147], v[178:181], v[116:119]
	v_mfma_f32_16x16x32_bf16 v[112:115], v[168:171], v[178:181], v[112:115]
	v_mfma_f32_16x16x32_bf16 v[100:103], v[144:147], v[196:199], v[100:103]
	v_mfma_f32_16x16x32_bf16 v[96:99], v[168:171], v[196:199], v[96:99]
	v_mfma_f32_16x16x32_bf16 v[84:87], v[144:147], v[204:207], v[84:87]
	v_mfma_f32_16x16x32_bf16 v[80:83], v[168:171], v[204:207], v[80:83]
	v_mfma_f32_16x16x32_bf16 v[68:71], v[144:147], v[212:215], v[68:71]
	v_mfma_f32_16x16x32_bf16 v[64:67], v[168:171], v[212:215], v[64:67]
	v_mfma_f32_16x16x32_bf16 v[116:119], v[148:151], v[182:185], v[116:119]
	v_mfma_f32_16x16x32_bf16 v[112:115], v[172:175], v[182:185], v[112:115]
	v_mfma_f32_16x16x32_bf16 v[100:103], v[148:151], v[200:203], v[100:103]
	v_mfma_f32_16x16x32_bf16 v[96:99], v[172:175], v[200:203], v[96:99]
	v_mfma_f32_16x16x32_bf16 v[84:87], v[148:151], v[208:211], v[84:87]
	v_mfma_f32_16x16x32_bf16 v[80:83], v[172:175], v[208:211], v[80:83]
	v_mfma_f32_16x16x32_bf16 v[68:71], v[148:151], v[216:219], v[68:71]
	v_mfma_f32_16x16x32_bf16 v[64:67], v[172:175], v[216:219], v[64:67]
	s_setprio 0
	s_barrier
	s_add_u32 s100, s48, 0x80
	s_addc_u32 s101, s49, 0
	s_add_u32 s98, s46, 0x80
	s_addc_u32 s99, s47, 0
	s_add_i32 s42, s68, s15
	s_mov_b32 m0, s42
	ds_read_b128 v[178:181], v194 offset:16384
	ds_read_b128 v[182:185], v194 offset:17408
	ds_read_b128 v[196:199], v194 offset:18432
	ds_read_b128 v[200:203], v194 offset:19456
	ds_read_b128 v[204:207], v194 offset:20480
	ds_read_b128 v[208:211], v194 offset:21504
	ds_read_b128 v[212:215], v194 offset:22528
	ds_read_b128 v[216:219], v194 offset:23552
	global_load_lds_dwordx4 v154, s[46:47]
	s_add_i32 m0, s42, 0x2000
	s_add_u32 s42, s46, 0x160000
	s_addc_u32 s43, s47, 0
	s_add_i32 s74, s69, s15
	global_load_lds_dwordx4 v158, s[46:47]
	s_mov_b32 m0, s74
	s_nop 0
	global_load_lds_dwordx4 v154, s[42:43]
	s_add_i32 m0, s74, 0x2000
	s_nop 0
	global_load_lds_dwordx4 v158, s[42:43]
	s_mov_b32 m0, s35
	s_nop 0
	global_load_lds_dwordx4 v152, s[48:49]
	s_mov_b32 m0, s50
	s_nop 0
	global_load_lds_dwordx4 v156, s[48:49]
	s_waitcnt vmcnt(8)
	s_waitcnt lgkmcnt(0)
	s_barrier
	s_setprio 1
	s_waitcnt lgkmcnt(0)
	v_mfma_f32_16x16x32_bf16 v[60:63], v[128:131], v[178:181], v[60:63]
	v_mfma_f32_16x16x32_bf16 v[56:59], v[136:139], v[178:181], v[56:59]
	v_mfma_f32_16x16x32_bf16 v[44:47], v[128:131], v[196:199], v[44:47]
	v_mfma_f32_16x16x32_bf16 v[40:43], v[136:139], v[196:199], v[40:43]
	v_mfma_f32_16x16x32_bf16 v[28:31], v[128:131], v[204:207], v[28:31]
	v_mfma_f32_16x16x32_bf16 v[24:27], v[136:139], v[204:207], v[24:27]
	v_mfma_f32_16x16x32_bf16 v[12:15], v[128:131], v[212:215], v[12:15]
	v_mfma_f32_16x16x32_bf16 v[8:11], v[136:139], v[212:215], v[8:11]
	v_mfma_f32_16x16x32_bf16 v[60:63], v[132:135], v[182:185], v[60:63]
	v_mfma_f32_16x16x32_bf16 v[56:59], v[140:143], v[182:185], v[56:59]
	v_mfma_f32_16x16x32_bf16 v[44:47], v[132:135], v[200:203], v[44:47]
	v_mfma_f32_16x16x32_bf16 v[40:43], v[140:143], v[200:203], v[40:43]
	v_mfma_f32_16x16x32_bf16 v[28:31], v[132:135], v[208:211], v[28:31]
	v_mfma_f32_16x16x32_bf16 v[24:27], v[140:143], v[208:211], v[24:27]
	v_mfma_f32_16x16x32_bf16 v[12:15], v[132:135], v[216:219], v[12:15]
	v_mfma_f32_16x16x32_bf16 v[8:11], v[140:143], v[216:219], v[8:11]
	s_setprio 0
	s_setprio 1
	v_mfma_f32_16x16x32_bf16 v[52:55], v[144:147], v[178:181], v[52:55]
	v_mfma_f32_16x16x32_bf16 v[48:51], v[168:171], v[178:181], v[48:51]
	v_mfma_f32_16x16x32_bf16 v[36:39], v[144:147], v[196:199], v[36:39]
	v_mfma_f32_16x16x32_bf16 v[32:35], v[168:171], v[196:199], v[32:35]
	v_mfma_f32_16x16x32_bf16 v[20:23], v[144:147], v[204:207], v[20:23]
	v_mfma_f32_16x16x32_bf16 v[16:19], v[168:171], v[204:207], v[16:19]
	v_mfma_f32_16x16x32_bf16 v[4:7], v[144:147], v[212:215], v[4:7]
	v_mfma_f32_16x16x32_bf16 v[0:3], v[168:171], v[212:215], v[0:3]
	v_mfma_f32_16x16x32_bf16 v[52:55], v[148:151], v[182:185], v[52:55]
	v_mfma_f32_16x16x32_bf16 v[48:51], v[172:175], v[182:185], v[48:51]
	v_mfma_f32_16x16x32_bf16 v[36:39], v[148:151], v[200:203], v[36:39]
	v_mfma_f32_16x16x32_bf16 v[32:35], v[172:175], v[200:203], v[32:35]
	v_mfma_f32_16x16x32_bf16 v[20:23], v[148:151], v[208:211], v[20:23]
	v_mfma_f32_16x16x32_bf16 v[16:19], v[172:175], v[208:211], v[16:19]
	v_mfma_f32_16x16x32_bf16 v[4:7], v[148:151], v[216:219], v[4:7]
	v_mfma_f32_16x16x32_bf16 v[0:3], v[172:175], v[216:219], v[0:3]
	s_setprio 0
	s_barrier
; #define PG8_STAGE(bufoff, gbase, voff) do { _Pragma("unroll") for (int _i = 0; _i < 2; ++_i) \
;         __builtin_amdgcn_global_load_lds((const unsigned*)((const char*)(gbase) + (voff)[_i]), (LAS unsigned*)(lds + (bufoff) + ldsw + _i * 8192), 16, 0, 0); } while (0)
; #define PG8_LDA(dst, b, h) do { _Pragma("unroll") for (int m = 0; m < 4; ++m) _Pragma("unroll") for (int k = 0; k < 2; ++k) dst[m][k] = *(const LAS bf16x8*)(lds + PG8_SA(b, h) + aoff + m * 2048 + k * 1024); } while (0)
; #define PG8_LDB(dst, b, h) do { _Pragma("unroll") for (int n = 0; n < 2; ++n) _Pragma("unroll") for (int k = 0; k < 2; ++k) dst[n][k] = *(const LAS bf16x8*)(lds + PG8_SB(b, h) + boff + n * 2048 + k * 1024); } while (0)
; #define PG8_MMA(ai, bj, At, Bt) do { __builtin_amdgcn_s_setprio(1); _Pragma("unroll") for (int m = 0; m < 4; ++m) _Pragma("unroll") for (int n = 0; n < 2; ++n) _Pragma("unroll") for (int k = 0; k < 2; ++k) \
;         acc[ai][bj][m][n] = __builtin_amdgcn_mfma_f32_16x16x32_bf16(Bt[n][k], At[m][k], acc[ai][bj][m][n], 0, 0, 0); __builtin_amdgcn_s_setprio(0); } while (0)
; #define PG8_WAIT_V(n) asm volatile("s_waitcnt vmcnt(" #n ")" ::: "memory")
; #define PG8_WAIT_L(n) asm volatile("s_waitcnt lgkmcnt(" #n ")" ::: "memory")
; #define PG8_BAR __builtin_amdgcn_s_barrier()
; #define PG8_SCHED __builtin_amdgcn_sched_barrier(0)
; template <class Epi, class Sched, bool ALIGN_EPI = false, bool SP2 = false>
; __device__ __forceinline__ void gemm_phase(LAS unsigned char* lds, const Gemm g, const Sched& S, const Epi& E) {
;     ...
;             PG8_LDB(B0, 1, 0); PG8_LDB(B1, 1, 1); PG8_SCHED; PG8_LDA(At, 1, 0); PG8_STAGE(PG8_SA(0, 1), a2 + hstep, voffA);
;             PG8_WAIT_V(8); PG8_WAIT_L(0); PG8_BAR; PG8_MMA(0, 0, At, B0); PG8_MMA(0, 1, At, B1); PG8_BAR; PG8_SCHED;
;             PG8_LDA(At, 1, 1); PG8_STAGE(PG8_SB(1, 0), b3, voffB); PG8_STAGE(PG8_SB(1, 1), b3 + hstep, voffB); PG8_STAGE(PG8_SA(1, 0), a3, voffA);
;             PG8_WAIT_V(8); PG8_WAIT_L(0); PG8_BAR; PG8_MMA(1, 0, At, B0); PG8_MMA(1, 1, At, B1); PG8_BAR; PG8_SCHED;
	s_add_i32 s74, 0, 0x18000
	s_add_i32 s87, 0, 0x1c000
	v_add_u32_e32 v140, s74, v190
	v_add_u32_e32 v172, s87, v190
	ds_read_b128 v[128:131], v140
	ds_read_b128 v[132:135], v140 offset:1024
	ds_read_b128 v[136:139], v140 offset:2048
	ds_read_b128 v[140:143], v140 offset:3072
	ds_read_b128 v[144:147], v172
	ds_read_b128 v[148:151], v172 offset:1024
	ds_read_b128 v[168:171], v172 offset:2048
	ds_read_b128 v[172:175], v172 offset:3072
	s_add_u32 s42, s48, 0x160000
	s_addc_u32 s43, s49, 0
	s_mov_b32 m0, s51
	ds_read_b128 v[178:181], v194 offset:32768
	ds_read_b128 v[182:185], v194 offset:33792
	ds_read_b128 v[196:199], v194 offset:34816
	ds_read_b128 v[200:203], v194 offset:35840
	ds_read_b128 v[204:207], v194 offset:36864
	ds_read_b128 v[208:211], v194 offset:37888
	ds_read_b128 v[212:215], v194 offset:38912
	ds_read_b128 v[216:219], v194 offset:39936
	global_load_lds_dwordx4 v152, s[42:43]
	s_mov_b32 m0, s64
	s_nop 0
	global_load_lds_dwordx4 v156, s[42:43]
	s_waitcnt vmcnt(8)
	s_waitcnt lgkmcnt(0)
	s_barrier
	s_setprio 1
	s_waitcnt lgkmcnt(0)
	v_mfma_f32_16x16x32_bf16 v[124:127], v[128:131], v[178:181], v[124:127]
	v_mfma_f32_16x16x32_bf16 v[120:123], v[136:139], v[178:181], v[120:123]
	v_mfma_f32_16x16x32_bf16 v[108:111], v[128:131], v[196:199], v[108:111]
	v_mfma_f32_16x16x32_bf16 v[104:107], v[136:139], v[196:199], v[104:107]
	v_mfma_f32_16x16x32_bf16 v[92:95], v[128:131], v[204:207], v[92:95]
	v_mfma_f32_16x16x32_bf16 v[88:91], v[136:139], v[204:207], v[88:91]
	v_mfma_f32_16x16x32_bf16 v[76:79], v[128:131], v[212:215], v[76:79]
	v_mfma_f32_16x16x32_bf16 v[72:75], v[136:139], v[212:215], v[72:75]
	v_mfma_f32_16x16x32_bf16 v[124:127], v[132:135], v[182:185], v[124:127]
	v_mfma_f32_16x16x32_bf16 v[120:123], v[140:143], v[182:185], v[120:123]
	v_mfma_f32_16x16x32_bf16 v[108:111], v[132:135], v[200:203], v[108:111]
	v_mfma_f32_16x16x32_bf16 v[104:107], v[140:143], v[200:203], v[104:107]
	v_mfma_f32_16x16x32_bf16 v[92:95], v[132:135], v[208:211], v[92:95]
	v_mfma_f32_16x16x32_bf16 v[88:91], v[140:143], v[208:211], v[88:91]
	v_mfma_f32_16x16x32_bf16 v[76:79], v[132:135], v[216:219], v[76:79]
	v_mfma_f32_16x16x32_bf16 v[72:75], v[140:143], v[216:219], v[72:75]
	s_setprio 0
	s_setprio 1
	v_mfma_f32_16x16x32_bf16 v[116:119], v[144:147], v[178:181], v[116:119]
	v_mfma_f32_16x16x32_bf16 v[112:115], v[168:171], v[178:181], v[112:115]
	v_mfma_f32_16x16x32_bf16 v[100:103], v[144:147], v[196:199], v[100:103]
	v_mfma_f32_16x16x32_bf16 v[96:99], v[168:171], v[196:199], v[96:99]
	v_mfma_f32_16x16x32_bf16 v[84:87], v[144:147], v[204:207], v[84:87]
	v_mfma_f32_16x16x32_bf16 v[80:83], v[168:171], v[204:207], v[80:83]
	v_mfma_f32_16x16x32_bf16 v[68:71], v[144:147], v[212:215], v[68:71]
	v_mfma_f32_16x16x32_bf16 v[64:67], v[168:171], v[212:215], v[64:67]
	v_mfma_f32_16x16x32_bf16 v[116:119], v[148:151], v[182:185], v[116:119]
	v_mfma_f32_16x16x32_bf16 v[112:115], v[172:175], v[182:185], v[112:115]
	v_mfma_f32_16x16x32_bf16 v[100:103], v[148:151], v[200:203], v[100:103]
	v_mfma_f32_16x16x32_bf16 v[96:99], v[172:175], v[200:203], v[96:99]
	v_mfma_f32_16x16x32_bf16 v[84:87], v[148:151], v[208:211], v[84:87]
	v_mfma_f32_16x16x32_bf16 v[80:83], v[172:175], v[208:211], v[80:83]
	v_mfma_f32_16x16x32_bf16 v[68:71], v[148:151], v[216:219], v[68:71]
	v_mfma_f32_16x16x32_bf16 v[64:67], v[172:175], v[216:219], v[64:67]
	s_setprio 0
	s_barrier
	s_add_i32 s42, s74, s15
	s_mov_b32 m0, s42
	ds_read_b128 v[178:181], v194 offset:49152
	ds_read_b128 v[182:185], v194 offset:50176
	ds_read_b128 v[196:199], v194 offset:51200
	ds_read_b128 v[200:203], v194 offset:52224
	ds_read_b128 v[204:207], v194 offset:53248
	ds_read_b128 v[208:211], v194 offset:54272
	ds_read_b128 v[212:215], v194 offset:55296
	ds_read_b128 v[216:219], v194 offset:56320
	global_load_lds_dwordx4 v154, s[98:99]
	s_add_i32 m0, s42, 0x2000
	s_add_u32 s42, s46, 0x160080
	s_addc_u32 s43, s47, 0
	s_add_i32 s46, s87, s15
	global_load_lds_dwordx4 v158, s[98:99]
	s_mov_b32 m0, s46
	s_nop 0
	global_load_lds_dwordx4 v154, s[42:43]
	s_add_i32 m0, s46, 0x2000
	s_nop 0
	global_load_lds_dwordx4 v158, s[42:43]
	s_mov_b32 m0, s66
	s_nop 0
	global_load_lds_dwordx4 v152, s[100:101]
	s_mov_b32 m0, s67
	s_nop 0
	global_load_lds_dwordx4 v156, s[100:101]
	s_waitcnt vmcnt(8)
	s_waitcnt lgkmcnt(0)
	s_barrier
	s_setprio 1
	s_waitcnt lgkmcnt(0)
	v_mfma_f32_16x16x32_bf16 v[60:63], v[128:131], v[178:181], v[60:63]
	v_mfma_f32_16x16x32_bf16 v[56:59], v[136:139], v[178:181], v[56:59]
	v_mfma_f32_16x16x32_bf16 v[44:47], v[128:131], v[196:199], v[44:47]
	v_mfma_f32_16x16x32_bf16 v[40:43], v[136:139], v[196:199], v[40:43]
	v_mfma_f32_16x16x32_bf16 v[28:31], v[128:131], v[204:207], v[28:31]
	v_mfma_f32_16x16x32_bf16 v[24:27], v[136:139], v[204:207], v[24:27]
	v_mfma_f32_16x16x32_bf16 v[12:15], v[128:131], v[212:215], v[12:15]
	v_mfma_f32_16x16x32_bf16 v[8:11], v[136:139], v[212:215], v[8:11]
	v_mfma_f32_16x16x32_bf16 v[60:63], v[132:135], v[182:185], v[60:63]
	v_mfma_f32_16x16x32_bf16 v[56:59], v[140:143], v[182:185], v[56:59]
	v_mfma_f32_16x16x32_bf16 v[44:47], v[132:135], v[200:203], v[44:47]
	v_mfma_f32_16x16x32_bf16 v[40:43], v[140:143], v[200:203], v[40:43]
	v_mfma_f32_16x16x32_bf16 v[28:31], v[132:135], v[208:211], v[28:31]
	v_mfma_f32_16x16x32_bf16 v[24:27], v[140:143], v[208:211], v[24:27]
	v_mfma_f32_16x16x32_bf16 v[12:15], v[132:135], v[216:219], v[12:15]
	v_mfma_f32_16x16x32_bf16 v[8:11], v[140:143], v[216:219], v[8:11]
	s_setprio 0
	s_setprio 1
	v_mfma_f32_16x16x32_bf16 v[52:55], v[144:147], v[178:181], v[52:55]
	v_mfma_f32_16x16x32_bf16 v[48:51], v[168:171], v[178:181], v[48:51]
	v_mfma_f32_16x16x32_bf16 v[36:39], v[144:147], v[196:199], v[36:39]
	v_mfma_f32_16x16x32_bf16 v[32:35], v[168:171], v[196:199], v[32:35]
	v_mfma_f32_16x16x32_bf16 v[20:23], v[144:147], v[204:207], v[20:23]
	v_mfma_f32_16x16x32_bf16 v[16:19], v[168:171], v[204:207], v[16:19]
	v_mfma_f32_16x16x32_bf16 v[4:7], v[144:147], v[212:215], v[4:7]
	v_mfma_f32_16x16x32_bf16 v[0:3], v[168:171], v[212:215], v[0:3]
	v_mfma_f32_16x16x32_bf16 v[52:55], v[148:151], v[182:185], v[52:55]
	v_mfma_f32_16x16x32_bf16 v[48:51], v[172:175], v[182:185], v[48:51]
	v_mfma_f32_16x16x32_bf16 v[36:39], v[148:151], v[200:203], v[36:39]
	v_mfma_f32_16x16x32_bf16 v[32:35], v[172:175], v[200:203], v[32:35]
	v_mfma_f32_16x16x32_bf16 v[20:23], v[148:151], v[208:211], v[20:23]
	v_mfma_f32_16x16x32_bf16 v[16:19], v[172:175], v[208:211], v[16:19]
	v_mfma_f32_16x16x32_bf16 v[4:7], v[148:151], v[216:219], v[4:7]
	v_mfma_f32_16x16x32_bf16 v[0:3], v[172:175], v[216:219], v[0:3]
	s_setprio 0
	s_barrier
	s_add_i32 s86, s86, 2
	s_add_u32 s16, s16, 0x100
	s_addc_u32 s17, s17, 0
	s_cmpk_gt_u32 s86, 0x55
	s_mov_b64 s[42:43], s[44:45]
	s_cbranch_scc0 .LBB0_231
	s_branch .Lsapad0
	s_nop 0
	s_nop 0
	s_nop 0
	s_nop 0
	s_nop 0
	s_nop 0
	s_nop 0
	s_nop 0
	s_nop 0
	s_nop 0
	s_nop 0
	s_nop 0
	s_nop 0
	s_nop 0
	s_nop 0
	s_nop 0
	s_nop 0
	s_nop 0
	s_nop 0
	s_nop 0
	s_nop 0
	s_nop 0
	s_nop 0
	s_nop 0
;     __device__ __forceinline__ void load(Row& r, size_t off) const {
; #pragma unroll
;         for (int bj = 0; bj < 2; ++bj) {
;             if (BASE_BF16) r.h[bj] = *(const u32x4*)(baseb + off + bj * HALF);
;             else { r.f[bj][0] = *(const f32x4*)(basef + off + bj * HALF); r.f[bj][1] = *(const f32x4*)(basef + off + bj * HALF + 4); } }
;     }
;     __device__ __forceinline__ void row(const Row& r, const f32x4 (&a)[2][2][4][2], int ai, int m, int row_, int col0, int fq) const {
;         const size_t off = (size_t)row_ * D + col0; float sq = 0.f;
; #pragma unroll
;         for (int bj = 0; bj < 2; ++bj) {
;             f32x4 b0, b1;
;             if (BASE_BF16) { const u32x4 h = r.h[bj];
;                 b0 = (f32x4){__builtin_bit_cast(float, h[0] << 16), __builtin_bit_cast(float, h[0] & 0xffff0000u), __builtin_bit_cast(float, h[1] << 16), __builtin_bit_cast(float, h[1] & 0xffff0000u)};
;                 b1 = (f32x4){__builtin_bit_cast(float, h[2] << 16), __builtin_bit_cast(float, h[2] & 0xffff0000u), __builtin_bit_cast(float, h[3] << 16), __builtin_bit_cast(float, h[3] & 0xffff0000u)}; }
;             else { b0 = r.f[bj][0]; b1 = r.f[bj][1]; }
;             const f32x4 v0 = b0 + a[ai][bj][m][0] * alpha, v1 = b1 + a[ai][bj][m][1] * alpha;
;             u32x4 w; w.x = cvt_pk_bf16(v0[0], v0[1]); w.y = cvt_pk_bf16(v0[2], v0[3]); w.z = cvt_pk_bf16(v1[0], v1[1]); w.w = cvt_pk_bf16(v1[2], v1[3]);
;             *(u32x4*)(xb + off + bj * HALF) = w;
;             sq += (v0[0] * v0[0] + v0[1] * v0[1]) + (v0[2] * v0[2] + v0[3] * v0[3]) + (v1[0] * v1[0] + v1[1] * v1[1]) + (v1[2] * v1[2] + v1[3] * v1[3]);
;         }
;         sq += __shfl_xor(sq, 16); sq += __shfl_xor(sq, 32);
;         if (fq == 0) unsafeAtomicAdd(ss + row_, sq);
;     }
;     __device__ __forceinline__ void operator()(const f32x4 (&acc)[2][2][4][2], const Unit& u, int wr, int wc, int fr, int fq, const Pre&) const {
;         const int row0 = u.pm * BM + wr * 64 + fr, col0 = u.pn * BM + wc * 32 + 8 * fq;
;         Row pre[4];
; #pragma unroll
;         for (int m = 0; m < 4; ++m) load(pre[m], (size_t)(row0 + m * 16) * D + col0);
;         asm volatile("" ::: "memory");
; #pragma unroll
;         for (int m = 0; m < 4; ++m) {
;             row(pre[m], acc, 0, m, row0 + m * 16, col0, fq);
;             load(pre[m], (size_t)(row0 + HALF + m * 16) * D + col0);
.Lsapad0:
	s_and_b64 vcc, exec, s[36:37]
	s_cbranch_vccz .LBB0_234
	s_barrier
.LBB0_234:
	v_lshl_or_b32 v168, s73, 8, v191
	v_lshl_add_u32 v170, s72, 8, v189
	v_ashrrev_i32_e32 v169, 31, v168
	v_lshlrev_b64 v[172:173], 1, v[168:169]
	v_ashrrev_i32_e32 v171, 31, v170
	v_lshl_add_u64 v[128:129], s[20:21], 0, v[172:173]
	v_lshlrev_b64 v[196:197], 12, v[170:171]
	v_lshl_add_u64 v[130:131], v[128:129], 0, v[196:197]
	global_load_dwordx4 v[198:201], v[130:131], off
	global_load_dwordx4 v[202:205], v[130:131], off offset:256
	v_or_b32_e32 v184, 16, v170
	v_or_b32_e32 v180, 32, v170
	v_or_b32_e32 v174, 48, v170
	v_ashrrev_i32_e32 v185, 31, v184
	v_ashrrev_i32_e32 v181, 31, v180
	v_ashrrev_i32_e32 v175, 31, v174
	v_lshlrev_b64 v[186:187], 12, v[184:185]
	v_lshlrev_b64 v[182:183], 12, v[180:181]
	v_lshlrev_b64 v[178:179], 12, v[174:175]
	v_lshl_add_u64 v[130:131], v[128:129], 0, v[186:187]
	v_lshl_add_u64 v[132:133], v[128:129], 0, v[182:183]
	v_lshl_add_u64 v[128:129], v[128:129], 0, v[178:179]
	global_load_dwordx4 v[148:151], v[130:131], off
	global_load_dwordx4 v[144:147], v[130:131], off offset:256
	global_load_dwordx4 v[140:143], v[132:133], off
	global_load_dwordx4 v[136:139], v[132:133], off offset:256
	s_nop 0
	global_load_dwordx4 v[132:135], v[128:129], off
	s_nop 0
	global_load_dwordx4 v[128:131], v[128:129], off offset:256
	v_and_b32_e32 v207, 64, v195
	v_xor_b32_e32 v206, 16, v195
	v_add_u32_e32 v207, 64, v207
	v_xor_b32_e32 v208, 32, v195
	v_cmp_lt_i32_e32 vcc, v206, v207
	s_waitcnt vmcnt(0)
	v_lshlrev_b32_e32 v210, 16, v200
	v_cndmask_b32_e32 v209, v195, v206, vcc
	v_cmp_lt_i32_e32 vcc, v208, v207
	v_lshl_add_u64 v[206:207], s[20:21], 0, v[196:197]
	v_lshlrev_b32_e32 v196, 2, v209
	v_cndmask_b32_e32 v216, v195, v208, vcc
	v_lshlrev_b32_e32 v208, 16, v198
	v_and_b32_e32 v209, 0xffff0000, v198
	v_lshlrev_b32_e32 v198, 16, v199
	v_and_b32_e32 v199, 0xffff0000, v199
	v_lshlrev_b32_e32 v212, 16, v202
	v_and_b32_e32 v213, 0xffff0000, v202
	v_lshlrev_b32_e32 v202, 16, v203
	v_and_b32_e32 v203, 0xffff0000, v203
	v_and_b32_e32 v211, 0xffff0000, v200
	v_lshlrev_b32_e32 v200, 16, v201
	v_and_b32_e32 v201, 0xffff0000, v201
	v_lshlrev_b32_e32 v214, 16, v204
	v_and_b32_e32 v215, 0xffff0000, v204
	v_lshlrev_b32_e32 v204, 16, v205
	v_and_b32_e32 v205, 0xffff0000, v205
	v_pk_fma_f32 v[126:127], v[126:127], 0.5, v[198:199] op_sel_hi:[1,0,1]
	v_pk_fma_f32 v[124:125], v[124:125], 0.5, v[208:209] op_sel_hi:[1,0,1]
	v_pk_fma_f32 v[118:119], v[118:119], 0.5, v[202:203] op_sel_hi:[1,0,1]
	v_pk_fma_f32 v[116:117], v[116:117], 0.5, v[212:213] op_sel_hi:[1,0,1]
	v_pk_fma_f32 v[122:123], v[122:123], 0.5, v[200:201] op_sel_hi:[1,0,1]
	v_pk_fma_f32 v[120:121], v[120:121], 0.5, v[210:211] op_sel_hi:[1,0,1]
	v_pk_fma_f32 v[198:199], v[114:115], 0.5, v[204:205] op_sel_hi:[1,0,1]
	v_pk_fma_f32 v[200:201], v[112:113], 0.5, v[214:215] op_sel_hi:[1,0,1]
	v_mul_f32_e32 v114, v125, v125
	v_mul_f32_e32 v115, v127, v127
	v_mul_f32_e32 v197, v117, v117
	v_mul_f32_e32 v202, v119, v119
	v_cvt_pk_bf16_f32 v112, v124, v125
	v_mul_f32_e32 v125, v121, v121
	v_mul_f32_e32 v203, v201, v201
	v_fmac_f32_e32 v114, v124, v124
	v_fmac_f32_e32 v115, v126, v126
	v_fmac_f32_e32 v197, v116, v116
	v_fmac_f32_e32 v202, v118, v118
	v_cvt_pk_bf16_f32 v113, v126, v127
	v_mul_f32_e32 v127, v123, v123
	v_mul_f32_e32 v204, v199, v199
	v_fmac_f32_e32 v125, v120, v120
	v_fmac_f32_e32 v203, v200, v200
	v_add_f32_e32 v114, v114, v115
	v_add_f32_e32 v115, v197, v202
	v_fmac_f32_e32 v127, v122, v122
	v_fmac_f32_e32 v204, v198, v198
	v_add_f32_e32 v114, v125, v114
	v_add_f32_e32 v115, v203, v115
	v_add_f32_e32 v114, v127, v114
	v_add_f32_e32 v115, v204, v115
	v_add_f32_e32 v124, v114, v115
	ds_bpermute_b32 v125, v196, v124
	v_lshl_add_u64 v[206:207], v[206:207], 0, v[172:173]
	v_cvt_pk_bf16_f32 v114, v120, v121
	v_cvt_pk_bf16_f32 v115, v122, v123
	global_store_dwordx4 v[206:207], v[112:115], off
	s_waitcnt lgkmcnt(0)
	s_nop 0
	v_add_f32_e32 v112, v124, v125
	v_lshlrev_b32_e32 v124, 2, v216
	ds_bpermute_b32 v113, v124, v112
	v_cvt_pk_bf16_f32 v114, v116, v117
	v_cvt_pk_bf16_f32 v115, v118, v119
	v_cvt_pk_bf16_f32 v116, v200, v201
	v_cvt_pk_bf16_f32 v117, v198, v199
	global_store_dwordx4 v[206:207], v[114:117], off offset:256
	s_and_saveexec_b64 s[42:43], s[6:7]
	s_cbranch_execz .LBB0_236
	v_lshl_add_u64 v[114:115], v[170:171], 2, s[60:61]
	s_waitcnt lgkmcnt(0)
	v_add_f32_e32 v112, v112, v113
	global_atomic_add_f32 v[114:115], v112, off

; #define PG8_STAGE(bufoff, gbase, voff) do { _Pragma("unroll") for (int _i = 0; _i < 2; ++_i) \
;         __builtin_amdgcn_global_load_lds((const unsigned*)((const char*)(gbase) + (voff)[_i]), (LAS unsigned*)(lds + (bufoff) + ldsw + _i * 8192), 16, 0, 0); } while (0)
; #define PG8_LDA(dst, b, h) do { _Pragma("unroll") for (int m = 0; m < 4; ++m) _Pragma("unroll") for (int k = 0; k < 2; ++k) dst[m][k] = *(const LAS bf16x8*)(lds + PG8_SA(b, h) + aoff + m * 2048 + k * 1024); } while (0)
; #define PG8_LDB(dst, b, h) do { _Pragma("unroll") for (int n = 0; n < 2; ++n) _Pragma("unroll") for (int k = 0; k < 2; ++k) dst[n][k] = *(const LAS bf16x8*)(lds + PG8_SB(b, h) + boff + n * 2048 + k * 1024); } while (0)
; #define PG8_MMA(ai, bj, At, Bt) do { __builtin_amdgcn_s_setprio(1); _Pragma("unroll") for (int m = 0; m < 4; ++m) _Pragma("unroll") for (int n = 0; n < 2; ++n) _Pragma("unroll") for (int k = 0; k < 2; ++k) \
;         acc[ai][bj][m][n] = __builtin_amdgcn_mfma_f32_16x16x32_bf16(Bt[n][k], At[m][k], acc[ai][bj][m][n], 0, 0, 0); __builtin_amdgcn_s_setprio(0); } while (0)
; #define PG8_WAIT_V(n) asm volatile("s_waitcnt vmcnt(" #n ")" ::: "memory")
; #define PG8_WAIT_L(n) asm volatile("s_waitcnt lgkmcnt(" #n ")" ::: "memory")
; #define PG8_BAR __builtin_amdgcn_s_barrier()
; template <class Epi, class Sched, bool ALIGN_EPI = false, bool SP2 = false>
; __device__ __forceinline__ void gemm_phase(LAS unsigned char* lds, const Gemm g, const Sched& S, const Epi& E) {
;     ...
;             const char* a1 = cA + (size_t)(t + 1) * kstep;
;             const char* a2 = last ? nA : cA + (size_t)(t + 2) * kstep; const char* b2 = last ? nB : cB + (size_t)(t + 2) * kstep;
;             const char* a3 = a2 + kstep; const char* b3 = b2 + kstep;
;             if (last && has_next) { S.a_ready(nxt); pre_nxt = E.pre(nxt, wr, fr); }
;             if constexpr (SP2) {
;             PG8_LDB(B0, 0, 0); PG8_LDB(B1, 0, 1); PG8_SCHED; PG8_LDA(At, 0, 0); PG8_STAGE(PG8_SA(1, 1), a1 + hstep, voffA);
;             PG8_WAIT_V(8); PG8_WAIT_L(0); PG8_BAR; PG8_MMA(0, 0, At, B0); PG8_MMA(0, 1, At, B1); PG8_BAR; PG8_SCHED;
;             PG8_LDA(At, 0, 1); PG8_STAGE(PG8_SB(0, 0), b2, voffB); PG8_STAGE(PG8_SB(0, 1), b2 + hstep, voffB); PG8_STAGE(PG8_SA(0, 0), a2, voffA);
;             PG8_WAIT_V(8); PG8_WAIT_L(0); PG8_BAR; PG8_MMA(1, 0, At, B0); PG8_MMA(1, 1, At, B1); PG8_BAR; PG8_SCHED;
.LBB0_317:
	v_add_u32_e32 v50, s91, v165
	ds_read_b128 v[154:157], v50
	ds_read_b128 v[158:161], v50 offset:1024
	ds_read_b128 v[190:193], v50 offset:2048
	ds_read_b128 v[194:197], v50 offset:3072
	v_add_u32_e32 v50, s92, v165
	ds_read_b128 v[198:201], v50
	ds_read_b128 v[202:205], v50 offset:1024
	ds_read_b128 v[206:209], v50 offset:2048
	ds_read_b128 v[210:213], v50 offset:3072
	s_add_u32 s72, s10, 0xfff80080
	s_addc_u32 s73, s11, -1
	s_and_b64 s[70:71], s[70:71], exec
	s_cselect_b32 s73, s51, s73
	s_cselect_b32 s72, s67, s72
	s_cselect_b32 s71, s49, s16
	s_cselect_b32 s70, s96, s97
	s_add_i32 m0, s35, 0xc000
	ds_read_b128 v[214:217], v167
	ds_read_b128 v[218:221], v167 offset:1024
	ds_read_b128 v[222:225], v167 offset:2048
	ds_read_b128 v[226:229], v167 offset:3072
	ds_read_b128 v[230:233], v167 offset:4096
	ds_read_b128 v[234:237], v167 offset:5120
	ds_read_b128 v[238:241], v167 offset:6144
	ds_read_b128 v[242:245], v167 offset:7168
	global_load_lds_dwordx4 v144, s[10:11]
	s_add_i32 m0, s35, 0xe000
	s_nop 0
	global_load_lds_dwordx4 v146, s[10:11]
	s_waitcnt vmcnt(8)
	s_waitcnt lgkmcnt(0)
	s_barrier
	s_setprio 1
	s_waitcnt lgkmcnt(0)
	v_mfma_f32_16x16x32_bf16 v[128:131], v[154:157], v[214:217], v[128:131]
	v_mfma_f32_16x16x32_bf16 v[124:127], v[190:193], v[214:217], v[124:127]
	v_mfma_f32_16x16x32_bf16 v[112:115], v[154:157], v[222:225], v[112:115]
	v_mfma_f32_16x16x32_bf16 v[108:111], v[190:193], v[222:225], v[108:111]
	v_mfma_f32_16x16x32_bf16 v[96:99], v[154:157], v[230:233], v[96:99]
	v_mfma_f32_16x16x32_bf16 v[92:95], v[190:193], v[230:233], v[92:95]
	v_mfma_f32_16x16x32_bf16 v[80:83], v[154:157], v[238:241], v[80:83]
	v_mfma_f32_16x16x32_bf16 v[76:79], v[190:193], v[238:241], v[76:79]
	v_mfma_f32_16x16x32_bf16 v[128:131], v[158:161], v[218:221], v[128:131]
	v_mfma_f32_16x16x32_bf16 v[124:127], v[194:197], v[218:221], v[124:127]
	v_mfma_f32_16x16x32_bf16 v[112:115], v[158:161], v[226:229], v[112:115]
	v_mfma_f32_16x16x32_bf16 v[108:111], v[194:197], v[226:229], v[108:111]
	v_mfma_f32_16x16x32_bf16 v[96:99], v[158:161], v[234:237], v[96:99]
	v_mfma_f32_16x16x32_bf16 v[92:95], v[194:197], v[234:237], v[92:95]
	v_mfma_f32_16x16x32_bf16 v[80:83], v[158:161], v[242:245], v[80:83]
	v_mfma_f32_16x16x32_bf16 v[76:79], v[194:197], v[242:245], v[76:79]
	s_setprio 0
	s_setprio 1
	v_mfma_f32_16x16x32_bf16 v[120:123], v[198:201], v[214:217], v[120:123]
	v_mfma_f32_16x16x32_bf16 v[116:119], v[206:209], v[214:217], v[116:119]
	v_mfma_f32_16x16x32_bf16 v[104:107], v[198:201], v[222:225], v[104:107]
	v_mfma_f32_16x16x32_bf16 v[100:103], v[206:209], v[222:225], v[100:103]
	v_mfma_f32_16x16x32_bf16 v[88:91], v[198:201], v[230:233], v[88:91]
	v_mfma_f32_16x16x32_bf16 v[84:87], v[206:209], v[230:233], v[84:87]
	v_mfma_f32_16x16x32_bf16 v[72:75], v[198:201], v[238:241], v[72:75]
	v_mfma_f32_16x16x32_bf16 v[68:71], v[206:209], v[238:241], v[68:71]
	v_mfma_f32_16x16x32_bf16 v[120:123], v[202:205], v[218:221], v[120:123]
	v_mfma_f32_16x16x32_bf16 v[116:119], v[210:213], v[218:221], v[116:119]
	v_mfma_f32_16x16x32_bf16 v[104:107], v[202:205], v[226:229], v[104:107]
	v_mfma_f32_16x16x32_bf16 v[100:103], v[210:213], v[226:229], v[100:103]
	v_mfma_f32_16x16x32_bf16 v[88:91], v[202:205], v[234:237], v[88:91]
	v_mfma_f32_16x16x32_bf16 v[84:87], v[210:213], v[234:237], v[84:87]
	v_mfma_f32_16x16x32_bf16 v[72:75], v[202:205], v[242:245], v[72:75]
	v_mfma_f32_16x16x32_bf16 v[68:71], v[210:213], v[242:245], v[68:71]
	s_setprio 0
	s_barrier
	s_add_u32 s100, s72, 0x80
	s_addc_u32 s101, s73, 0
	s_add_u32 s98, s70, 0x80
	s_addc_u32 s99, s71, 0
	s_add_i32 s74, s91, s15
	s_mov_b32 m0, s74
	ds_read_b128 v[214:217], v167 offset:16384
	ds_read_b128 v[218:221], v167 offset:17408
	ds_read_b128 v[222:225], v167 offset:18432
	ds_read_b128 v[226:229], v167 offset:19456
	ds_read_b128 v[230:233], v167 offset:20480
	ds_read_b128 v[234:237], v167 offset:21504
	ds_read_b128 v[238:241], v167 offset:22528
	ds_read_b128 v[242:245], v167 offset:23552
	global_load_lds_dwordx4 v132, s[70:71]
	s_add_i32 m0, s74, 0x2000
	s_add_u32 vcc_lo, s70, 0x80000
	s_addc_u32 vcc_hi, s71, 0
	s_add_i32 s74, s92, s15
	global_load_lds_dwordx4 v134, s[70:71]
	s_mov_b32 m0, s74
	s_nop 0
	global_load_lds_dwordx4 v132, vcc
	s_add_i32 m0, s74, 0x2000
	s_nop 0
	global_load_lds_dwordx4 v134, vcc
	s_mov_b32 m0, s35
	s_nop 0
	global_load_lds_dwordx4 v132, s[72:73]
	s_mov_b32 m0, s69
	s_nop 0
	global_load_lds_dwordx4 v134, s[72:73]
	s_waitcnt vmcnt(8)
	s_waitcnt lgkmcnt(0)
	s_barrier
	s_setprio 1
	s_waitcnt lgkmcnt(0)
	v_mfma_f32_16x16x32_bf16 v[64:67], v[154:157], v[214:217], v[64:67]
	v_mfma_f32_16x16x32_bf16 v[60:63], v[190:193], v[214:217], v[60:63]
	v_mfma_f32_16x16x32_bf16 v[44:47], v[154:157], v[222:225], v[44:47]
	v_mfma_f32_16x16x32_bf16 v[40:43], v[190:193], v[222:225], v[40:43]
	v_mfma_f32_16x16x32_bf16 v[28:31], v[154:157], v[230:233], v[28:31]
	v_mfma_f32_16x16x32_bf16 v[24:27], v[190:193], v[230:233], v[24:27]
	v_mfma_f32_16x16x32_bf16 v[12:15], v[154:157], v[238:241], v[12:15]
	v_mfma_f32_16x16x32_bf16 v[8:11], v[190:193], v[238:241], v[8:11]
	v_mfma_f32_16x16x32_bf16 v[64:67], v[158:161], v[218:221], v[64:67]
	v_mfma_f32_16x16x32_bf16 v[60:63], v[194:197], v[218:221], v[60:63]
	v_mfma_f32_16x16x32_bf16 v[44:47], v[158:161], v[226:229], v[44:47]
	v_mfma_f32_16x16x32_bf16 v[40:43], v[194:197], v[226:229], v[40:43]
	v_mfma_f32_16x16x32_bf16 v[28:31], v[158:161], v[234:237], v[28:31]
	v_mfma_f32_16x16x32_bf16 v[24:27], v[194:197], v[234:237], v[24:27]
	v_mfma_f32_16x16x32_bf16 v[12:15], v[158:161], v[242:245], v[12:15]
	v_mfma_f32_16x16x32_bf16 v[8:11], v[194:197], v[242:245], v[8:11]
	s_setprio 0
	s_setprio 1
	v_mfma_f32_16x16x32_bf16 v[56:59], v[198:201], v[214:217], v[56:59]
	v_mfma_f32_16x16x32_bf16 v[50:53], v[206:209], v[214:217], v[52:55]
	v_mfma_f32_16x16x32_bf16 v[36:39], v[198:201], v[222:225], v[36:39]
	v_mfma_f32_16x16x32_bf16 v[32:35], v[206:209], v[222:225], v[32:35]
	v_mfma_f32_16x16x32_bf16 v[20:23], v[198:201], v[230:233], v[20:23]
	v_mfma_f32_16x16x32_bf16 v[16:19], v[206:209], v[230:233], v[16:19]
	v_mfma_f32_16x16x32_bf16 v[4:7], v[198:201], v[238:241], v[4:7]
	v_mfma_f32_16x16x32_bf16 v[0:3], v[206:209], v[238:241], v[0:3]
	v_mfma_f32_16x16x32_bf16 v[56:59], v[202:205], v[218:221], v[56:59]
	v_mfma_f32_16x16x32_bf16 v[50:53], v[210:213], v[218:221], v[50:53]
	v_mfma_f32_16x16x32_bf16 v[36:39], v[202:205], v[226:229], v[36:39]
	v_mfma_f32_16x16x32_bf16 v[32:35], v[210:213], v[226:229], v[32:35]
	v_mfma_f32_16x16x32_bf16 v[20:23], v[202:205], v[234:237], v[20:23]
	v_mfma_f32_16x16x32_bf16 v[16:19], v[210:213], v[234:237], v[16:19]
	v_mfma_f32_16x16x32_bf16 v[4:7], v[202:205], v[242:245], v[4:7]
	v_mfma_f32_16x16x32_bf16 v[0:3], v[210:213], v[242:245], v[0:3]
	s_setprio 0
	s_barrier
; #define PG8_STAGE(bufoff, gbase, voff) do { _Pragma("unroll") for (int _i = 0; _i < 2; ++_i) \
;         __builtin_amdgcn_global_load_lds((const unsigned*)((const char*)(gbase) + (voff)[_i]), (LAS unsigned*)(lds + (bufoff) + ldsw + _i * 8192), 16, 0, 0); } while (0)
; #define PG8_LDA(dst, b, h) do { _Pragma("unroll") for (int m = 0; m < 4; ++m) _Pragma("unroll") for (int k = 0; k < 2; ++k) dst[m][k] = *(const LAS bf16x8*)(lds + PG8_SA(b, h) + aoff + m * 2048 + k * 1024); } while (0)
; #define PG8_LDB(dst, b, h) do { _Pragma("unroll") for (int n = 0; n < 2; ++n) _Pragma("unroll") for (int k = 0; k < 2; ++k) dst[n][k] = *(const LAS bf16x8*)(lds + PG8_SB(b, h) + boff + n * 2048 + k * 1024); } while (0)
; #define PG8_MMA(ai, bj, At, Bt) do { __builtin_amdgcn_s_setprio(1); _Pragma("unroll") for (int m = 0; m < 4; ++m) _Pragma("unroll") for (int n = 0; n < 2; ++n) _Pragma("unroll") for (int k = 0; k < 2; ++k) \
;         acc[ai][bj][m][n] = __builtin_amdgcn_mfma_f32_16x16x32_bf16(Bt[n][k], At[m][k], acc[ai][bj][m][n], 0, 0, 0); __builtin_amdgcn_s_setprio(0); } while (0)
; #define PG8_WAIT_V(n) asm volatile("s_waitcnt vmcnt(" #n ")" ::: "memory")
; #define PG8_WAIT_L(n) asm volatile("s_waitcnt lgkmcnt(" #n ")" ::: "memory")
; #define PG8_BAR __builtin_amdgcn_s_barrier()
; #define PG8_SCHED __builtin_amdgcn_sched_barrier(0)
; template <class Epi, class Sched, bool ALIGN_EPI = false, bool SP2 = false>
; __device__ __forceinline__ void gemm_phase(LAS unsigned char* lds, const Gemm g, const Sched& S, const Epi& E) {
;     ...
;             PG8_LDB(B0, 1, 0); PG8_LDB(B1, 1, 1); PG8_SCHED; PG8_LDA(At, 1, 0); PG8_STAGE(PG8_SA(0, 1), a2 + hstep, voffA);
;             PG8_WAIT_V(8); PG8_WAIT_L(0); PG8_BAR; PG8_MMA(0, 0, At, B0); PG8_MMA(0, 1, At, B1); PG8_BAR; PG8_SCHED;
;             PG8_LDA(At, 1, 1); PG8_STAGE(PG8_SB(1, 0), b3, voffB); PG8_STAGE(PG8_SB(1, 1), b3 + hstep, voffB); PG8_STAGE(PG8_SA(1, 0), a3, voffA);
;             PG8_WAIT_V(8); PG8_WAIT_L(0); PG8_BAR; PG8_MMA(1, 0, At, B0); PG8_MMA(1, 1, At, B1); PG8_BAR; PG8_SCHED;
	s_add_i32 s74, 0, 0x18000
	v_add_u32_e32 v54, s74, v165
	s_add_i32 vcc_lo, 0, 0x1c000
	ds_read_b128 v[154:157], v54
	ds_read_b128 v[158:161], v54 offset:1024
	ds_read_b128 v[190:193], v54 offset:2048
	ds_read_b128 v[194:197], v54 offset:3072
	v_add_u32_e32 v54, vcc_lo, v165
	ds_read_b128 v[198:201], v54
	ds_read_b128 v[202:205], v54 offset:1024
	ds_read_b128 v[206:209], v54 offset:2048
	ds_read_b128 v[210:213], v54 offset:3072
	s_add_u32 s72, s72, 0x80000
	s_addc_u32 s73, s73, 0
	s_mov_b32 m0, s86
	ds_read_b128 v[214:217], v167 offset:32768
	ds_read_b128 v[218:221], v167 offset:33792
	ds_read_b128 v[222:225], v167 offset:34816
	ds_read_b128 v[226:229], v167 offset:35840
	ds_read_b128 v[230:233], v167 offset:36864
	ds_read_b128 v[234:237], v167 offset:37888
	ds_read_b128 v[238:241], v167 offset:38912
	ds_read_b128 v[242:245], v167 offset:39936
	global_load_lds_dwordx4 v132, s[72:73]
	s_mov_b32 m0, s87
	s_nop 0
	global_load_lds_dwordx4 v134, s[72:73]
	s_waitcnt vmcnt(8)
	s_waitcnt lgkmcnt(0)
	s_barrier
	s_setprio 1
	s_waitcnt lgkmcnt(0)
	v_mfma_f32_16x16x32_bf16 v[128:131], v[154:157], v[214:217], v[128:131]
	v_mfma_f32_16x16x32_bf16 v[124:127], v[190:193], v[214:217], v[124:127]
	v_mfma_f32_16x16x32_bf16 v[112:115], v[154:157], v[222:225], v[112:115]
	v_mfma_f32_16x16x32_bf16 v[108:111], v[190:193], v[222:225], v[108:111]
	v_mfma_f32_16x16x32_bf16 v[96:99], v[154:157], v[230:233], v[96:99]
	v_mfma_f32_16x16x32_bf16 v[92:95], v[190:193], v[230:233], v[92:95]
	v_mfma_f32_16x16x32_bf16 v[80:83], v[154:157], v[238:241], v[80:83]
	v_mfma_f32_16x16x32_bf16 v[76:79], v[190:193], v[238:241], v[76:79]
	v_mfma_f32_16x16x32_bf16 v[128:131], v[158:161], v[218:221], v[128:131]
	v_mfma_f32_16x16x32_bf16 v[124:127], v[194:197], v[218:221], v[124:127]
	v_mfma_f32_16x16x32_bf16 v[112:115], v[158:161], v[226:229], v[112:115]
	v_mfma_f32_16x16x32_bf16 v[108:111], v[194:197], v[226:229], v[108:111]
	v_mfma_f32_16x16x32_bf16 v[96:99], v[158:161], v[234:237], v[96:99]
	v_mfma_f32_16x16x32_bf16 v[92:95], v[194:197], v[234:237], v[92:95]
	v_mfma_f32_16x16x32_bf16 v[80:83], v[158:161], v[242:245], v[80:83]
	v_mfma_f32_16x16x32_bf16 v[76:79], v[194:197], v[242:245], v[76:79]
	s_setprio 0
	s_setprio 1
	v_mfma_f32_16x16x32_bf16 v[120:123], v[198:201], v[214:217], v[120:123]
	v_mfma_f32_16x16x32_bf16 v[116:119], v[206:209], v[214:217], v[116:119]
	v_mfma_f32_16x16x32_bf16 v[104:107], v[198:201], v[222:225], v[104:107]
	v_mfma_f32_16x16x32_bf16 v[100:103], v[206:209], v[222:225], v[100:103]
	v_mfma_f32_16x16x32_bf16 v[88:91], v[198:201], v[230:233], v[88:91]
	v_mfma_f32_16x16x32_bf16 v[84:87], v[206:209], v[230:233], v[84:87]
	v_mfma_f32_16x16x32_bf16 v[72:75], v[198:201], v[238:241], v[72:75]
	v_mfma_f32_16x16x32_bf16 v[68:71], v[206:209], v[238:241], v[68:71]
	v_mfma_f32_16x16x32_bf16 v[120:123], v[202:205], v[218:221], v[120:123]
	v_mfma_f32_16x16x32_bf16 v[116:119], v[210:213], v[218:221], v[116:119]
	v_mfma_f32_16x16x32_bf16 v[104:107], v[202:205], v[226:229], v[104:107]
	v_mfma_f32_16x16x32_bf16 v[100:103], v[210:213], v[226:229], v[100:103]
	v_mfma_f32_16x16x32_bf16 v[88:91], v[202:205], v[234:237], v[88:91]
	v_mfma_f32_16x16x32_bf16 v[84:87], v[210:213], v[234:237], v[84:87]
	v_mfma_f32_16x16x32_bf16 v[72:75], v[202:205], v[242:245], v[72:75]
	v_mfma_f32_16x16x32_bf16 v[68:71], v[210:213], v[242:245], v[68:71]
	s_setprio 0
	s_barrier
	s_add_i32 s72, s74, s15
	s_mov_b32 m0, s72
	ds_read_b128 v[214:217], v167 offset:49152
	ds_read_b128 v[218:221], v167 offset:50176
	ds_read_b128 v[222:225], v167 offset:51200
	ds_read_b128 v[226:229], v167 offset:52224
	ds_read_b128 v[230:233], v167 offset:53248
	ds_read_b128 v[234:237], v167 offset:54272
	ds_read_b128 v[238:241], v167 offset:55296
	ds_read_b128 v[242:245], v167 offset:56320
	global_load_lds_dwordx4 v132, s[98:99]
	s_add_i32 m0, s72, 0x2000
	s_add_u32 s70, s70, 0x80080
	s_addc_u32 s71, s71, 0
	s_add_i32 s72, vcc_lo, s15
	global_load_lds_dwordx4 v134, s[98:99]
	s_mov_b32 m0, s72
	s_nop 0
	global_load_lds_dwordx4 v132, s[70:71]
	s_add_i32 m0, s72, 0x2000
	s_nop 0
	global_load_lds_dwordx4 v134, s[70:71]
	s_mov_b32 m0, s89
	s_nop 0
	global_load_lds_dwordx4 v132, s[100:101]
	s_mov_b32 m0, s90
	s_nop 0
	global_load_lds_dwordx4 v134, s[100:101]
	s_waitcnt vmcnt(8)
	s_waitcnt lgkmcnt(0)
	s_barrier
	s_setprio 1
	s_waitcnt lgkmcnt(0)
	v_mfma_f32_16x16x32_bf16 v[64:67], v[154:157], v[214:217], v[64:67]
	v_mfma_f32_16x16x32_bf16 v[60:63], v[190:193], v[214:217], v[60:63]
	v_mfma_f32_16x16x32_bf16 v[44:47], v[154:157], v[222:225], v[44:47]
	v_mfma_f32_16x16x32_bf16 v[40:43], v[190:193], v[222:225], v[40:43]
	v_mfma_f32_16x16x32_bf16 v[28:31], v[154:157], v[230:233], v[28:31]
	v_mfma_f32_16x16x32_bf16 v[24:27], v[190:193], v[230:233], v[24:27]
	v_mfma_f32_16x16x32_bf16 v[12:15], v[154:157], v[238:241], v[12:15]
	v_mfma_f32_16x16x32_bf16 v[8:11], v[190:193], v[238:241], v[8:11]
	v_mfma_f32_16x16x32_bf16 v[64:67], v[158:161], v[218:221], v[64:67]
	v_mfma_f32_16x16x32_bf16 v[60:63], v[194:197], v[218:221], v[60:63]
	v_mfma_f32_16x16x32_bf16 v[44:47], v[158:161], v[226:229], v[44:47]
	v_mfma_f32_16x16x32_bf16 v[40:43], v[194:197], v[226:229], v[40:43]
	v_mfma_f32_16x16x32_bf16 v[28:31], v[158:161], v[234:237], v[28:31]
	v_mfma_f32_16x16x32_bf16 v[24:27], v[194:197], v[234:237], v[24:27]
	v_mfma_f32_16x16x32_bf16 v[12:15], v[158:161], v[242:245], v[12:15]
	v_mfma_f32_16x16x32_bf16 v[8:11], v[194:197], v[242:245], v[8:11]
	s_setprio 0
	s_setprio 1
	v_mfma_f32_16x16x32_bf16 v[54:57], v[198:201], v[214:217], v[56:59]
	v_mfma_f32_16x16x32_bf16 v[50:53], v[206:209], v[214:217], v[50:53]
	v_mfma_f32_16x16x32_bf16 v[36:39], v[198:201], v[222:225], v[36:39]
	v_mfma_f32_16x16x32_bf16 v[32:35], v[206:209], v[222:225], v[32:35]
	v_mfma_f32_16x16x32_bf16 v[20:23], v[198:201], v[230:233], v[20:23]
	v_mfma_f32_16x16x32_bf16 v[16:19], v[206:209], v[230:233], v[16:19]
	v_mfma_f32_16x16x32_bf16 v[4:7], v[198:201], v[238:241], v[4:7]
	v_mfma_f32_16x16x32_bf16 v[0:3], v[206:209], v[238:241], v[0:3]
	v_mfma_f32_16x16x32_bf16 v[56:59], v[202:205], v[218:221], v[54:57]
	v_mfma_f32_16x16x32_bf16 v[52:55], v[210:213], v[218:221], v[50:53]
	v_mfma_f32_16x16x32_bf16 v[36:39], v[202:205], v[226:229], v[36:39]
	v_mfma_f32_16x16x32_bf16 v[32:35], v[210:213], v[226:229], v[32:35]
	v_mfma_f32_16x16x32_bf16 v[20:23], v[202:205], v[234:237], v[20:23]
	v_mfma_f32_16x16x32_bf16 v[16:19], v[210:213], v[234:237], v[16:19]
	v_mfma_f32_16x16x32_bf16 v[4:7], v[202:205], v[242:245], v[4:7]
	v_mfma_f32_16x16x32_bf16 v[0:3], v[210:213], v[242:245], v[0:3]
	s_setprio 0
	s_barrier
	s_add_i32 s17, s17, 2
	s_add_u32 s10, s10, 0x100
	s_addc_u32 s11, s11, 0
	s_add_u32 s97, s97, 0x100
	s_addc_u32 s16, s16, 0
	s_cmp_gt_u32 s17, 29
	s_cbranch_scc1 .LBB0_320
;     __device__ __forceinline__ Pre pre(const Unit& u, int wr, int fr) const { return load_rows8(ss, u, wr, fr); }
;     __device__ __forceinline__ Pre pre(const Unit& u, int wr, int fr) const { return load_rows8(ss, u, wr, fr); }
; template <class Epi, class Sched, bool ALIGN_EPI = false, bool SP2 = false>
; __device__ __forceinline__ void gemm_phase(LAS unsigned char* lds, const Gemm g, const Sched& S, const Epi& E) {
;     ...
;             const bool last = (t == nt - 2);
;             const char* a1 = cA + (size_t)(t + 1) * kstep;
;             const char* a2 = last ? nA : cA + (size_t)(t + 2) * kstep; const char* b2 = last ? nB : cB + (size_t)(t + 2) * kstep;
;             const char* a3 = a2 + kstep; const char* b3 = b2 + kstep;
;             if (last && has_next) { S.a_ready(nxt); pre_nxt = E.pre(nxt, wr, fr); }
; __device__ __forceinline__ PreRows load_rows8(const float* ss, const Unit& u, int wr, int fr) {
;     PreRows p; const float* b = ss + u.pm * BM + wr * 64 + fr;
; #pragma unroll
;     for (int ai = 0; ai < 2; ++ai)
; #pragma unroll
;         for (int m = 0; m < 4; ++m) p.v[ai * 4 + m] = b[ai * HALF + m * 16];
;     return p;
.LBB0_318:
	s_cmp_eq_u32 s17, 28
	s_cselect_b64 s[70:71], -1, 0
	s_and_b64 s[72:73], s[8:9], s[70:71]
	s_andn2_b64 vcc, exec, s[72:73]
	s_cbranch_vccnz .LBB0_317
	global_load_dword v171, v[48:49], off
	global_load_dword v172, v[48:49], off offset:64
	global_load_dword v173, v[48:49], off offset:128
	global_load_dword v174, v[48:49], off offset:192
	global_load_dword v175, v[48:49], off offset:512
	global_load_dword v178, v[48:49], off offset:576
	global_load_dword v179, v[48:49], off offset:640
	global_load_dword v180, v[48:49], off offset:704
	s_branch .LBB0_317
	s_nop 0
	s_nop 0
	s_nop 0
	s_nop 0
	s_nop 0
	s_nop 0
	s_nop 0
	s_nop 0
	s_nop 0
	s_nop 0
	s_nop 0
	s_nop 0
	s_nop 0
	s_nop 0
	s_nop 0
	s_nop 0
	s_nop 0
	s_nop 0
	s_nop 0
	s_nop 0
	s_nop 0
	s_nop 0
	s_nop 0
	s_nop 0

; #define PG8_STAGE(bufoff, gbase, voff) do { _Pragma("unroll") for (int _i = 0; _i < 2; ++_i) \
;         __builtin_amdgcn_global_load_lds((const unsigned*)((const char*)(gbase) + (voff)[_i]), (LAS unsigned*)(lds + (bufoff) + ldsw + _i * 8192), 16, 0, 0); } while (0)
; #define PG8_LDA(dst, b, h) do { _Pragma("unroll") for (int m = 0; m < 4; ++m) _Pragma("unroll") for (int k = 0; k < 2; ++k) dst[m][k] = *(const LAS bf16x8*)(lds + PG8_SA(b, h) + aoff + m * 2048 + k * 1024); } while (0)
; #define PG8_LDB(dst, b, h) do { _Pragma("unroll") for (int n = 0; n < 2; ++n) _Pragma("unroll") for (int k = 0; k < 2; ++k) dst[n][k] = *(const LAS bf16x8*)(lds + PG8_SB(b, h) + boff + n * 2048 + k * 1024); } while (0)
; #define PG8_MMA(ai, bj, At, Bt) do { __builtin_amdgcn_s_setprio(1); _Pragma("unroll") for (int m = 0; m < 4; ++m) _Pragma("unroll") for (int n = 0; n < 2; ++n) _Pragma("unroll") for (int k = 0; k < 2; ++k) \
;         acc[ai][bj][m][n] = __builtin_amdgcn_mfma_f32_16x16x32_bf16(Bt[n][k], At[m][k], acc[ai][bj][m][n], 0, 0, 0); __builtin_amdgcn_s_setprio(0); } while (0)
; #define PG8_WAIT_V(n) asm volatile("s_waitcnt vmcnt(" #n ")" ::: "memory")
; #define PG8_WAIT_L(n) asm volatile("s_waitcnt lgkmcnt(" #n ")" ::: "memory")
; #define PG8_BAR __builtin_amdgcn_s_barrier()
; template <class Epi, class Sched, bool ALIGN_EPI = false, bool SP2 = false>
; __device__ __forceinline__ void gemm_phase(LAS unsigned char* lds, const Gemm g, const Sched& S, const Epi& E) {
;     ...
;             const char* a1 = cA + (size_t)(t + 1) * kstep;
;             const char* a2 = last ? nA : cA + (size_t)(t + 2) * kstep; const char* b2 = last ? nB : cB + (size_t)(t + 2) * kstep;
;             const char* a3 = a2 + kstep; const char* b3 = b2 + kstep;
;             if (last && has_next) { S.a_ready(nxt); pre_nxt = E.pre(nxt, wr, fr); }
;             if constexpr (SP2) {
;             PG8_LDB(B0, 0, 0); PG8_LDB(B1, 0, 1); PG8_SCHED; PG8_LDA(At, 0, 0); PG8_STAGE(PG8_SA(1, 1), a1 + hstep, voffA);
;             PG8_WAIT_V(8); PG8_WAIT_L(0); PG8_BAR; PG8_MMA(0, 0, At, B0); PG8_MMA(0, 1, At, B1); PG8_BAR; PG8_SCHED;
;             PG8_LDA(At, 0, 1); PG8_STAGE(PG8_SB(0, 0), b2, voffB); PG8_STAGE(PG8_SB(0, 1), b2 + hstep, voffB); PG8_STAGE(PG8_SA(0, 0), a2, voffA);
;             PG8_WAIT_V(8); PG8_WAIT_L(0); PG8_BAR; PG8_MMA(1, 0, At, B0); PG8_MMA(1, 1, At, B1); PG8_BAR; PG8_SCHED;
.LBB0_369:
	ds_read_b128 v[144:147], v167
	ds_read_b128 v[148:151], v167 offset:1024
	ds_read_b128 v[152:155], v167 offset:2048
	ds_read_b128 v[156:159], v167 offset:3072
	ds_read_b128 v[160:163], v168
	ds_read_b128 v[172:175], v168 offset:1024
	ds_read_b128 v[178:181], v168 offset:2048
	ds_read_b128 v[182:185], v168 offset:3072
	s_add_u32 s66, s64, 0xfff80080
	s_addc_u32 s67, s65, -1
	s_cmp_eq_u32 s96, 28
	s_cselect_b32 s69, s16, s67
	s_cselect_b32 s68, s17, s66
	s_cselect_b32 s67, s45, s95
	s_cselect_b32 s66, s47, s94
	s_add_i32 m0, s63, 0xc000
	ds_read_b128 v[190:193], v169
	ds_read_b128 v[194:197], v169 offset:1024
	ds_read_b128 v[198:201], v169 offset:2048
	ds_read_b128 v[202:205], v169 offset:3072
	ds_read_b128 v[206:209], v169 offset:4096
	ds_read_b128 v[210:213], v169 offset:5120
	ds_read_b128 v[214:217], v169 offset:6144
	ds_read_b128 v[218:221], v169 offset:7168
	global_load_lds_dwordx4 v136, s[64:65]
	s_add_i32 m0, s63, 0xe000
	s_nop 0
	global_load_lds_dwordx4 v138, s[64:65]
	s_waitcnt vmcnt(8)
	s_waitcnt lgkmcnt(0)
	s_barrier
	s_setprio 1
	s_waitcnt lgkmcnt(0)
	v_mfma_f32_16x16x32_bf16 v[124:127], v[144:147], v[190:193], v[124:127]
	v_mfma_f32_16x16x32_bf16 v[120:123], v[152:155], v[190:193], v[120:123]
	v_mfma_f32_16x16x32_bf16 v[116:119], v[144:147], v[198:201], v[116:119]
	v_mfma_f32_16x16x32_bf16 v[112:115], v[152:155], v[198:201], v[112:115]
	v_mfma_f32_16x16x32_bf16 v[108:111], v[144:147], v[206:209], v[108:111]
	v_mfma_f32_16x16x32_bf16 v[100:103], v[152:155], v[206:209], v[100:103]
	v_mfma_f32_16x16x32_bf16 v[80:83], v[144:147], v[214:217], v[80:83]
	v_mfma_f32_16x16x32_bf16 v[72:75], v[152:155], v[214:217], v[72:75]
	v_mfma_f32_16x16x32_bf16 v[124:127], v[148:151], v[194:197], v[124:127]
	v_mfma_f32_16x16x32_bf16 v[120:123], v[156:159], v[194:197], v[120:123]
	v_mfma_f32_16x16x32_bf16 v[116:119], v[148:151], v[202:205], v[116:119]
	v_mfma_f32_16x16x32_bf16 v[112:115], v[156:159], v[202:205], v[112:115]
	v_mfma_f32_16x16x32_bf16 v[108:111], v[148:151], v[210:213], v[108:111]
	v_mfma_f32_16x16x32_bf16 v[100:103], v[156:159], v[210:213], v[100:103]
	v_mfma_f32_16x16x32_bf16 v[80:83], v[148:151], v[218:221], v[80:83]
	v_mfma_f32_16x16x32_bf16 v[72:75], v[156:159], v[218:221], v[72:75]
	s_setprio 0
	s_setprio 1
	v_mfma_f32_16x16x32_bf16 v[104:107], v[160:163], v[190:193], v[104:107]
	v_mfma_f32_16x16x32_bf16 v[96:99], v[178:181], v[190:193], v[96:99]
	v_mfma_f32_16x16x32_bf16 v[92:95], v[160:163], v[198:201], v[92:95]
	v_mfma_f32_16x16x32_bf16 v[88:91], v[178:181], v[198:201], v[88:91]
	v_mfma_f32_16x16x32_bf16 v[84:87], v[160:163], v[206:209], v[84:87]
	v_mfma_f32_16x16x32_bf16 v[76:79], v[178:181], v[206:209], v[76:79]
	v_mfma_f32_16x16x32_bf16 v[68:71], v[160:163], v[214:217], v[68:71]
	v_mfma_f32_16x16x32_bf16 v[64:67], v[178:181], v[214:217], v[64:67]
	v_mfma_f32_16x16x32_bf16 v[104:107], v[172:175], v[194:197], v[104:107]
	v_mfma_f32_16x16x32_bf16 v[96:99], v[182:185], v[194:197], v[96:99]
	v_mfma_f32_16x16x32_bf16 v[92:95], v[172:175], v[202:205], v[92:95]
	v_mfma_f32_16x16x32_bf16 v[88:91], v[182:185], v[202:205], v[88:91]
	v_mfma_f32_16x16x32_bf16 v[84:87], v[172:175], v[210:213], v[84:87]
	v_mfma_f32_16x16x32_bf16 v[76:79], v[182:185], v[210:213], v[76:79]
	v_mfma_f32_16x16x32_bf16 v[68:71], v[172:175], v[218:221], v[68:71]
	v_mfma_f32_16x16x32_bf16 v[64:67], v[182:185], v[218:221], v[64:67]
	s_setprio 0
	s_barrier
	s_add_u32 s100, s68, 0x80
	s_addc_u32 s101, s69, 0
	s_add_u32 s98, s66, 0x80
	s_addc_u32 s99, s67, 0
	s_add_i32 s74, s87, s70
	s_mov_b32 m0, s74
	ds_read_b128 v[190:193], v169 offset:16384
	ds_read_b128 v[194:197], v169 offset:17408
	ds_read_b128 v[198:201], v169 offset:18432
	ds_read_b128 v[202:205], v169 offset:19456
	ds_read_b128 v[206:209], v169 offset:20480
	ds_read_b128 v[210:213], v169 offset:21504
	ds_read_b128 v[214:217], v169 offset:22528
	ds_read_b128 v[218:221], v169 offset:23552
	global_load_lds_dwordx4 v130, s[66:67]
	s_add_i32 m0, s74, 0x2000
	s_add_u32 vcc_lo, s66, 0x80000
	s_addc_u32 vcc_hi, s67, 0
	s_add_i32 s74, s88, s70
	global_load_lds_dwordx4 v134, s[66:67]
	s_mov_b32 m0, s74
	s_nop 0
	global_load_lds_dwordx4 v130, vcc
	s_add_i32 m0, s74, 0x2000
	s_nop 0
	global_load_lds_dwordx4 v134, vcc
	s_mov_b32 m0, s63
	s_nop 0
	global_load_lds_dwordx4 v128, s[68:69]
	s_mov_b32 m0, s71
	s_nop 0
	global_load_lds_dwordx4 v132, s[68:69]
	s_waitcnt vmcnt(8)
	s_waitcnt lgkmcnt(0)
	s_barrier
	s_setprio 1
	s_waitcnt lgkmcnt(0)
	v_mfma_f32_16x16x32_bf16 v[60:63], v[144:147], v[190:193], v[60:63]
	v_mfma_f32_16x16x32_bf16 v[56:59], v[152:155], v[190:193], v[56:59]
	v_mfma_f32_16x16x32_bf16 v[48:51], v[144:147], v[198:201], v[48:51]
	v_mfma_f32_16x16x32_bf16 v[40:43], v[152:155], v[198:201], v[40:43]
	v_mfma_f32_16x16x32_bf16 v[32:35], v[144:147], v[206:209], v[32:35]
	v_mfma_f32_16x16x32_bf16 v[24:27], v[152:155], v[206:209], v[24:27]
	v_mfma_f32_16x16x32_bf16 v[16:19], v[144:147], v[214:217], v[16:19]
	v_mfma_f32_16x16x32_bf16 v[8:11], v[152:155], v[214:217], v[8:11]
	v_mfma_f32_16x16x32_bf16 v[60:63], v[148:151], v[194:197], v[60:63]
	v_mfma_f32_16x16x32_bf16 v[56:59], v[156:159], v[194:197], v[56:59]
	v_mfma_f32_16x16x32_bf16 v[48:51], v[148:151], v[202:205], v[48:51]
	v_mfma_f32_16x16x32_bf16 v[40:43], v[156:159], v[202:205], v[40:43]
	v_mfma_f32_16x16x32_bf16 v[32:35], v[148:151], v[210:213], v[32:35]
	v_mfma_f32_16x16x32_bf16 v[24:27], v[156:159], v[210:213], v[24:27]
	v_mfma_f32_16x16x32_bf16 v[16:19], v[148:151], v[218:221], v[16:19]
	v_mfma_f32_16x16x32_bf16 v[8:11], v[156:159], v[218:221], v[8:11]
	s_setprio 0
	s_setprio 1
	v_mfma_f32_16x16x32_bf16 v[52:55], v[160:163], v[190:193], v[52:55]
	v_mfma_f32_16x16x32_bf16 v[44:47], v[178:181], v[190:193], v[44:47]
	v_mfma_f32_16x16x32_bf16 v[36:39], v[160:163], v[198:201], v[36:39]
	v_mfma_f32_16x16x32_bf16 v[28:31], v[178:181], v[198:201], v[28:31]
	v_mfma_f32_16x16x32_bf16 v[20:23], v[160:163], v[206:209], v[20:23]
	v_mfma_f32_16x16x32_bf16 v[12:15], v[178:181], v[206:209], v[12:15]
	v_mfma_f32_16x16x32_bf16 v[4:7], v[160:163], v[214:217], v[4:7]
	v_mfma_f32_16x16x32_bf16 v[0:3], v[178:181], v[214:217], v[0:3]
	v_mfma_f32_16x16x32_bf16 v[52:55], v[172:175], v[194:197], v[52:55]
	v_mfma_f32_16x16x32_bf16 v[44:47], v[182:185], v[194:197], v[44:47]
	v_mfma_f32_16x16x32_bf16 v[36:39], v[172:175], v[202:205], v[36:39]
	v_mfma_f32_16x16x32_bf16 v[28:31], v[182:185], v[202:205], v[28:31]
	v_mfma_f32_16x16x32_bf16 v[20:23], v[172:175], v[210:213], v[20:23]
	v_mfma_f32_16x16x32_bf16 v[12:15], v[182:185], v[210:213], v[12:15]
	v_mfma_f32_16x16x32_bf16 v[4:7], v[172:175], v[218:221], v[4:7]
	v_mfma_f32_16x16x32_bf16 v[0:3], v[182:185], v[218:221], v[0:3]
	s_setprio 0
	s_barrier
; #define PG8_STAGE(bufoff, gbase, voff) do { _Pragma("unroll") for (int _i = 0; _i < 2; ++_i) \
;         __builtin_amdgcn_global_load_lds((const unsigned*)((const char*)(gbase) + (voff)[_i]), (LAS unsigned*)(lds + (bufoff) + ldsw + _i * 8192), 16, 0, 0); } while (0)
; #define PG8_LDA(dst, b, h) do { _Pragma("unroll") for (int m = 0; m < 4; ++m) _Pragma("unroll") for (int k = 0; k < 2; ++k) dst[m][k] = *(const LAS bf16x8*)(lds + PG8_SA(b, h) + aoff + m * 2048 + k * 1024); } while (0)
; #define PG8_LDB(dst, b, h) do { _Pragma("unroll") for (int n = 0; n < 2; ++n) _Pragma("unroll") for (int k = 0; k < 2; ++k) dst[n][k] = *(const LAS bf16x8*)(lds + PG8_SB(b, h) + boff + n * 2048 + k * 1024); } while (0)
; #define PG8_MMA(ai, bj, At, Bt) do { __builtin_amdgcn_s_setprio(1); _Pragma("unroll") for (int m = 0; m < 4; ++m) _Pragma("unroll") for (int n = 0; n < 2; ++n) _Pragma("unroll") for (int k = 0; k < 2; ++k) \
;         acc[ai][bj][m][n] = __builtin_amdgcn_mfma_f32_16x16x32_bf16(Bt[n][k], At[m][k], acc[ai][bj][m][n], 0, 0, 0); __builtin_amdgcn_s_setprio(0); } while (0)
; #define PG8_WAIT_V(n) asm volatile("s_waitcnt vmcnt(" #n ")" ::: "memory")
; #define PG8_WAIT_L(n) asm volatile("s_waitcnt lgkmcnt(" #n ")" ::: "memory")
; #define PG8_BAR __builtin_amdgcn_s_barrier()
; #define PG8_SCHED __builtin_amdgcn_sched_barrier(0)
; template <class Epi, class Sched, bool ALIGN_EPI = false, bool SP2 = false>
; __device__ __forceinline__ void gemm_phase(LAS unsigned char* lds, const Gemm g, const Sched& S, const Epi& E) {
;     ...
;             PG8_LDB(B0, 1, 0); PG8_LDB(B1, 1, 1); PG8_SCHED; PG8_LDA(At, 1, 0); PG8_STAGE(PG8_SA(0, 1), a2 + hstep, voffA);
;             PG8_WAIT_V(8); PG8_WAIT_L(0); PG8_BAR; PG8_MMA(0, 0, At, B0); PG8_MMA(0, 1, At, B1); PG8_BAR; PG8_SCHED;
;             PG8_LDA(At, 1, 1); PG8_STAGE(PG8_SB(1, 0), b3, voffB); PG8_STAGE(PG8_SB(1, 1), b3 + hstep, voffB); PG8_STAGE(PG8_SA(1, 0), a3, voffA);
;             PG8_WAIT_V(8); PG8_WAIT_L(0); PG8_BAR; PG8_MMA(1, 0, At, B0); PG8_MMA(1, 1, At, B1); PG8_BAR; PG8_SCHED;
;     ...
;         if constexpr (ALIGN_EPI) { if (wr == 0) PG8_BAR; }
	s_add_i32 s74, 0, 0x18000
	s_add_i32 s97, 0, 0x1c000
	v_add_u32_e32 v156, s74, v165
	v_add_u32_e32 v171, s97, v165
	ds_read_b128 v[144:147], v156
	ds_read_b128 v[148:151], v156 offset:1024
	ds_read_b128 v[152:155], v156 offset:2048
	ds_read_b128 v[156:159], v156 offset:3072
	ds_read_b128 v[160:163], v171
	ds_read_b128 v[172:175], v171 offset:1024
	ds_read_b128 v[178:181], v171 offset:2048
	ds_read_b128 v[182:185], v171 offset:3072
	s_add_u32 s68, s68, 0x80000
	s_addc_u32 s69, s69, 0
	s_mov_b32 m0, s72
	ds_read_b128 v[190:193], v169 offset:32768
	ds_read_b128 v[194:197], v169 offset:33792
	ds_read_b128 v[198:201], v169 offset:34816
	ds_read_b128 v[202:205], v169 offset:35840
	ds_read_b128 v[206:209], v169 offset:36864
	ds_read_b128 v[210:213], v169 offset:37888
	ds_read_b128 v[214:217], v169 offset:38912
	ds_read_b128 v[218:221], v169 offset:39936
	global_load_lds_dwordx4 v128, s[68:69]
	s_mov_b32 m0, s73
	s_nop 0
	global_load_lds_dwordx4 v132, s[68:69]
	s_waitcnt vmcnt(8)
	s_waitcnt lgkmcnt(0)
	s_barrier
	s_setprio 1
	s_waitcnt lgkmcnt(0)
	v_mfma_f32_16x16x32_bf16 v[124:127], v[144:147], v[190:193], v[124:127]
	v_mfma_f32_16x16x32_bf16 v[120:123], v[152:155], v[190:193], v[120:123]
	v_mfma_f32_16x16x32_bf16 v[116:119], v[144:147], v[198:201], v[116:119]
	v_mfma_f32_16x16x32_bf16 v[112:115], v[152:155], v[198:201], v[112:115]
	v_mfma_f32_16x16x32_bf16 v[108:111], v[144:147], v[206:209], v[108:111]
	v_mfma_f32_16x16x32_bf16 v[100:103], v[152:155], v[206:209], v[100:103]
	v_mfma_f32_16x16x32_bf16 v[80:83], v[144:147], v[214:217], v[80:83]
	v_mfma_f32_16x16x32_bf16 v[72:75], v[152:155], v[214:217], v[72:75]
	v_mfma_f32_16x16x32_bf16 v[124:127], v[148:151], v[194:197], v[124:127]
	v_mfma_f32_16x16x32_bf16 v[120:123], v[156:159], v[194:197], v[120:123]
	v_mfma_f32_16x16x32_bf16 v[116:119], v[148:151], v[202:205], v[116:119]
	v_mfma_f32_16x16x32_bf16 v[112:115], v[156:159], v[202:205], v[112:115]
	v_mfma_f32_16x16x32_bf16 v[108:111], v[148:151], v[210:213], v[108:111]
	v_mfma_f32_16x16x32_bf16 v[100:103], v[156:159], v[210:213], v[100:103]
	v_mfma_f32_16x16x32_bf16 v[80:83], v[148:151], v[218:221], v[80:83]
	v_mfma_f32_16x16x32_bf16 v[72:75], v[156:159], v[218:221], v[72:75]
	s_setprio 0
	s_setprio 1
	v_mfma_f32_16x16x32_bf16 v[104:107], v[160:163], v[190:193], v[104:107]
	v_mfma_f32_16x16x32_bf16 v[96:99], v[178:181], v[190:193], v[96:99]
	v_mfma_f32_16x16x32_bf16 v[92:95], v[160:163], v[198:201], v[92:95]
	v_mfma_f32_16x16x32_bf16 v[88:91], v[178:181], v[198:201], v[88:91]
	v_mfma_f32_16x16x32_bf16 v[84:87], v[160:163], v[206:209], v[84:87]
	v_mfma_f32_16x16x32_bf16 v[76:79], v[178:181], v[206:209], v[76:79]
	v_mfma_f32_16x16x32_bf16 v[68:71], v[160:163], v[214:217], v[68:71]
	v_mfma_f32_16x16x32_bf16 v[64:67], v[178:181], v[214:217], v[64:67]
	v_mfma_f32_16x16x32_bf16 v[104:107], v[172:175], v[194:197], v[104:107]
	v_mfma_f32_16x16x32_bf16 v[96:99], v[182:185], v[194:197], v[96:99]
	v_mfma_f32_16x16x32_bf16 v[92:95], v[172:175], v[202:205], v[92:95]
	v_mfma_f32_16x16x32_bf16 v[88:91], v[182:185], v[202:205], v[88:91]
	v_mfma_f32_16x16x32_bf16 v[84:87], v[172:175], v[210:213], v[84:87]
	v_mfma_f32_16x16x32_bf16 v[76:79], v[182:185], v[210:213], v[76:79]
	v_mfma_f32_16x16x32_bf16 v[68:71], v[172:175], v[218:221], v[68:71]
	v_mfma_f32_16x16x32_bf16 v[64:67], v[182:185], v[218:221], v[64:67]
	s_setprio 0
	s_barrier
	s_add_i32 s68, s74, s70
	s_mov_b32 m0, s68
	ds_read_b128 v[190:193], v169 offset:49152
	ds_read_b128 v[194:197], v169 offset:50176
	ds_read_b128 v[198:201], v169 offset:51200
	ds_read_b128 v[202:205], v169 offset:52224
	ds_read_b128 v[206:209], v169 offset:53248
	ds_read_b128 v[210:213], v169 offset:54272
	ds_read_b128 v[214:217], v169 offset:55296
	ds_read_b128 v[218:221], v169 offset:56320
	global_load_lds_dwordx4 v130, s[98:99]
	s_add_i32 m0, s68, 0x2000
	s_add_u32 s66, s66, 0x80080
	s_addc_u32 s67, s67, 0
	s_add_i32 s68, s97, s70
	global_load_lds_dwordx4 v134, s[98:99]
	s_mov_b32 m0, s68
	s_nop 0
	global_load_lds_dwordx4 v130, s[66:67]
	s_add_i32 m0, s68, 0x2000
	s_nop 0
	global_load_lds_dwordx4 v134, s[66:67]
	s_mov_b32 m0, s85
	s_nop 0
	global_load_lds_dwordx4 v128, s[100:101]
	s_mov_b32 m0, s86
	s_nop 0
	global_load_lds_dwordx4 v132, s[100:101]
	s_waitcnt vmcnt(8)
	s_waitcnt lgkmcnt(0)
	s_barrier
	s_setprio 1
	s_waitcnt lgkmcnt(0)
	v_mfma_f32_16x16x32_bf16 v[60:63], v[144:147], v[190:193], v[60:63]
	v_mfma_f32_16x16x32_bf16 v[56:59], v[152:155], v[190:193], v[56:59]
	v_mfma_f32_16x16x32_bf16 v[48:51], v[144:147], v[198:201], v[48:51]
	v_mfma_f32_16x16x32_bf16 v[40:43], v[152:155], v[198:201], v[40:43]
	v_mfma_f32_16x16x32_bf16 v[32:35], v[144:147], v[206:209], v[32:35]
	v_mfma_f32_16x16x32_bf16 v[24:27], v[152:155], v[206:209], v[24:27]
	v_mfma_f32_16x16x32_bf16 v[16:19], v[144:147], v[214:217], v[16:19]
	v_mfma_f32_16x16x32_bf16 v[8:11], v[152:155], v[214:217], v[8:11]
	v_mfma_f32_16x16x32_bf16 v[60:63], v[148:151], v[194:197], v[60:63]
	v_mfma_f32_16x16x32_bf16 v[56:59], v[156:159], v[194:197], v[56:59]
	v_mfma_f32_16x16x32_bf16 v[48:51], v[148:151], v[202:205], v[48:51]
	v_mfma_f32_16x16x32_bf16 v[40:43], v[156:159], v[202:205], v[40:43]
	v_mfma_f32_16x16x32_bf16 v[32:35], v[148:151], v[210:213], v[32:35]
	v_mfma_f32_16x16x32_bf16 v[24:27], v[156:159], v[210:213], v[24:27]
	v_mfma_f32_16x16x32_bf16 v[16:19], v[148:151], v[218:221], v[16:19]
	v_mfma_f32_16x16x32_bf16 v[8:11], v[156:159], v[218:221], v[8:11]
	s_setprio 0
	s_setprio 1
	v_mfma_f32_16x16x32_bf16 v[52:55], v[160:163], v[190:193], v[52:55]
	v_mfma_f32_16x16x32_bf16 v[44:47], v[178:181], v[190:193], v[44:47]
	v_mfma_f32_16x16x32_bf16 v[36:39], v[160:163], v[198:201], v[36:39]
	v_mfma_f32_16x16x32_bf16 v[28:31], v[178:181], v[198:201], v[28:31]
	v_mfma_f32_16x16x32_bf16 v[20:23], v[160:163], v[206:209], v[20:23]
	v_mfma_f32_16x16x32_bf16 v[12:15], v[178:181], v[206:209], v[12:15]
	v_mfma_f32_16x16x32_bf16 v[4:7], v[160:163], v[214:217], v[4:7]
	v_mfma_f32_16x16x32_bf16 v[0:3], v[178:181], v[214:217], v[0:3]
	v_mfma_f32_16x16x32_bf16 v[52:55], v[172:175], v[194:197], v[52:55]
	v_mfma_f32_16x16x32_bf16 v[44:47], v[182:185], v[194:197], v[44:47]
	v_mfma_f32_16x16x32_bf16 v[36:39], v[172:175], v[202:205], v[36:39]
	v_mfma_f32_16x16x32_bf16 v[28:31], v[182:185], v[202:205], v[28:31]
	v_mfma_f32_16x16x32_bf16 v[20:23], v[172:175], v[210:213], v[20:23]
	v_mfma_f32_16x16x32_bf16 v[12:15], v[182:185], v[210:213], v[12:15]
	v_mfma_f32_16x16x32_bf16 v[4:7], v[172:175], v[218:221], v[4:7]
	v_mfma_f32_16x16x32_bf16 v[0:3], v[182:185], v[218:221], v[0:3]
	s_setprio 0
	s_barrier
	s_add_i32 s96, s96, 2
	s_add_u32 s64, s64, 0x100
	s_addc_u32 s65, s65, 0
	s_add_u32 s94, s94, 0x100
	s_addc_u32 s95, s95, 0
	s_cmp_gt_u32 s96, 29
	s_cbranch_scc0 .LBB0_369
	s_branch .Lsapad1
	s_nop 0
	s_nop 0
	s_nop 0
	s_nop 0
	s_nop 0
	s_nop 0
	s_nop 0
	s_nop 0
	s_nop 0
	s_nop 0
	s_nop 0
	s_nop 0
	s_nop 0
	s_nop 0
	s_nop 0
	s_nop 0
	s_nop 0
	s_nop 0
	s_nop 0
	s_nop 0
	s_nop 0
	s_nop 0
	s_nop 0
	s_nop 0
.Lsapad1:
	s_and_b64 vcc, exec, s[10:11]
	s_cbranch_vccz .LBB0_372
	s_barrier

; #define PG8_STAGE(bufoff, gbase, voff) do { _Pragma("unroll") for (int _i = 0; _i < 2; ++_i) \
;         __builtin_amdgcn_global_load_lds((const unsigned*)((const char*)(gbase) + (voff)[_i]), (LAS unsigned*)(lds + (bufoff) + ldsw + _i * 8192), 16, 0, 0); } while (0)
; #define PG8_LDA(dst, b, h) do { _Pragma("unroll") for (int m = 0; m < 4; ++m) _Pragma("unroll") for (int k = 0; k < 2; ++k) dst[m][k] = *(const LAS bf16x8*)(lds + PG8_SA(b, h) + aoff + m * 2048 + k * 1024); } while (0)
; #define PG8_LDB(dst, b, h) do { _Pragma("unroll") for (int n = 0; n < 2; ++n) _Pragma("unroll") for (int k = 0; k < 2; ++k) dst[n][k] = *(const LAS bf16x8*)(lds + PG8_SB(b, h) + boff + n * 2048 + k * 1024); } while (0)
; #define PG8_MMA(ai, bj, At, Bt) do { __builtin_amdgcn_s_setprio(1); _Pragma("unroll") for (int m = 0; m < 4; ++m) _Pragma("unroll") for (int n = 0; n < 2; ++n) _Pragma("unroll") for (int k = 0; k < 2; ++k) \
;         acc[ai][bj][m][n] = __builtin_amdgcn_mfma_f32_16x16x32_bf16(Bt[n][k], At[m][k], acc[ai][bj][m][n], 0, 0, 0); __builtin_amdgcn_s_setprio(0); } while (0)
; #define PG8_WAIT_V(n) asm volatile("s_waitcnt vmcnt(" #n ")" ::: "memory")
; #define PG8_WAIT_L(n) asm volatile("s_waitcnt lgkmcnt(" #n ")" ::: "memory")
; #define PG8_BAR __builtin_amdgcn_s_barrier()
; template <class Epi, class Sched, bool ALIGN_EPI = false, bool SP2 = false>
; __device__ __forceinline__ void gemm_phase(LAS unsigned char* lds, const Gemm g, const Sched& S, const Epi& E) {
;     ...
;             const char* a1 = cA + (size_t)(t + 1) * kstep;
;             const char* a2 = last ? nA : cA + (size_t)(t + 2) * kstep; const char* b2 = last ? nB : cB + (size_t)(t + 2) * kstep;
;             const char* a3 = a2 + kstep; const char* b3 = b2 + kstep;
;             if (last && has_next) { S.a_ready(nxt); pre_nxt = E.pre(nxt, wr, fr); }
;             if constexpr (SP2) {
;             PG8_LDB(B0, 0, 0); PG8_LDB(B1, 0, 1); PG8_SCHED; PG8_LDA(At, 0, 0); PG8_STAGE(PG8_SA(1, 1), a1 + hstep, voffA);
;             PG8_WAIT_V(8); PG8_WAIT_L(0); PG8_BAR; PG8_MMA(0, 0, At, B0); PG8_MMA(0, 1, At, B1); PG8_BAR; PG8_SCHED;
;             PG8_LDA(At, 0, 1); PG8_STAGE(PG8_SB(0, 0), b2, voffB); PG8_STAGE(PG8_SB(0, 1), b2 + hstep, voffB); PG8_STAGE(PG8_SA(0, 0), a2, voffA);
;             PG8_WAIT_V(8); PG8_WAIT_L(0); PG8_BAR; PG8_MMA(1, 0, At, B0); PG8_MMA(1, 1, At, B1); PG8_BAR; PG8_SCHED;
.LBB0_626:
	ds_read_b128 v[128:131], v192
	ds_read_b128 v[132:135], v192 offset:1024
	ds_read_b128 v[136:139], v192 offset:2048
	ds_read_b128 v[140:143], v192 offset:3072
	ds_read_b128 v[144:147], v193
	ds_read_b128 v[148:151], v193 offset:1024
	ds_read_b128 v[168:171], v193 offset:2048
	ds_read_b128 v[172:175], v193 offset:3072
	s_add_u32 s58, s50, 0xfff80080
	s_addc_u32 s59, s51, -1
	s_cmp_eq_u32 s70, 28
	s_cselect_b32 s61, s16, s59
	s_cselect_b32 s60, s17, s58
	s_cselect_b32 s59, s39, s69
	s_cselect_b32 s58, s41, s47
	s_add_i32 m0, s35, 0xc000
	ds_read_b128 v[178:181], v194
	ds_read_b128 v[182:185], v194 offset:1024
	ds_read_b128 v[196:199], v194 offset:2048
	ds_read_b128 v[200:203], v194 offset:3072
	ds_read_b128 v[204:207], v194 offset:4096
	ds_read_b128 v[208:211], v194 offset:5120
	ds_read_b128 v[212:215], v194 offset:6144
	ds_read_b128 v[216:219], v194 offset:7168
	global_load_lds_dwordx4 v160, s[50:51]
	s_add_i32 m0, s35, 0xe000
	s_nop 0
	global_load_lds_dwordx4 v162, s[50:51]
	s_waitcnt vmcnt(8)
	s_waitcnt lgkmcnt(0)
	s_barrier
	s_setprio 1
	s_waitcnt lgkmcnt(0)
	v_mfma_f32_16x16x32_bf16 v[124:127], v[128:131], v[178:181], v[124:127]
	v_mfma_f32_16x16x32_bf16 v[120:123], v[136:139], v[178:181], v[120:123]
	v_mfma_f32_16x16x32_bf16 v[108:111], v[128:131], v[196:199], v[108:111]
	v_mfma_f32_16x16x32_bf16 v[104:107], v[136:139], v[196:199], v[104:107]
	v_mfma_f32_16x16x32_bf16 v[92:95], v[128:131], v[204:207], v[92:95]
	v_mfma_f32_16x16x32_bf16 v[88:91], v[136:139], v[204:207], v[88:91]
	v_mfma_f32_16x16x32_bf16 v[76:79], v[128:131], v[212:215], v[76:79]
	v_mfma_f32_16x16x32_bf16 v[72:75], v[136:139], v[212:215], v[72:75]
	v_mfma_f32_16x16x32_bf16 v[124:127], v[132:135], v[182:185], v[124:127]
	v_mfma_f32_16x16x32_bf16 v[120:123], v[140:143], v[182:185], v[120:123]
	v_mfma_f32_16x16x32_bf16 v[108:111], v[132:135], v[200:203], v[108:111]
	v_mfma_f32_16x16x32_bf16 v[104:107], v[140:143], v[200:203], v[104:107]
	v_mfma_f32_16x16x32_bf16 v[92:95], v[132:135], v[208:211], v[92:95]
	v_mfma_f32_16x16x32_bf16 v[88:91], v[140:143], v[208:211], v[88:91]
	v_mfma_f32_16x16x32_bf16 v[76:79], v[132:135], v[216:219], v[76:79]
	v_mfma_f32_16x16x32_bf16 v[72:75], v[140:143], v[216:219], v[72:75]
	s_setprio 0
	s_setprio 1
	v_mfma_f32_16x16x32_bf16 v[116:119], v[144:147], v[178:181], v[116:119]
	v_mfma_f32_16x16x32_bf16 v[112:115], v[168:171], v[178:181], v[112:115]
	v_mfma_f32_16x16x32_bf16 v[100:103], v[144:147], v[196:199], v[100:103]
	v_mfma_f32_16x16x32_bf16 v[96:99], v[168:171], v[196:199], v[96:99]
	v_mfma_f32_16x16x32_bf16 v[84:87], v[144:147], v[204:207], v[84:87]
	v_mfma_f32_16x16x32_bf16 v[80:83], v[168:171], v[204:207], v[80:83]
	v_mfma_f32_16x16x32_bf16 v[68:71], v[144:147], v[212:215], v[68:71]
	v_mfma_f32_16x16x32_bf16 v[64:67], v[168:171], v[212:215], v[64:67]
	v_mfma_f32_16x16x32_bf16 v[116:119], v[148:151], v[182:185], v[116:119]
	v_mfma_f32_16x16x32_bf16 v[112:115], v[172:175], v[182:185], v[112:115]
	v_mfma_f32_16x16x32_bf16 v[100:103], v[148:151], v[200:203], v[100:103]
	v_mfma_f32_16x16x32_bf16 v[96:99], v[172:175], v[200:203], v[96:99]
	v_mfma_f32_16x16x32_bf16 v[84:87], v[148:151], v[208:211], v[84:87]
	v_mfma_f32_16x16x32_bf16 v[80:83], v[172:175], v[208:211], v[80:83]
	v_mfma_f32_16x16x32_bf16 v[68:71], v[148:151], v[216:219], v[68:71]
	v_mfma_f32_16x16x32_bf16 v[64:67], v[172:175], v[216:219], v[64:67]
	s_setprio 0
	s_barrier
	s_add_u32 s100, s60, 0x80
	s_addc_u32 s101, s61, 0
	s_add_u32 s98, s58, 0x80
	s_addc_u32 s99, s59, 0
	s_add_i32 s71, s67, s15
	s_mov_b32 m0, s71
	ds_read_b128 v[178:181], v194 offset:16384
	ds_read_b128 v[182:185], v194 offset:17408
	ds_read_b128 v[196:199], v194 offset:18432
	ds_read_b128 v[200:203], v194 offset:19456
	ds_read_b128 v[204:207], v194 offset:20480
	ds_read_b128 v[208:211], v194 offset:21504
	ds_read_b128 v[212:215], v194 offset:22528
	ds_read_b128 v[216:219], v194 offset:23552
	global_load_lds_dwordx4 v154, s[58:59]
	s_add_i32 m0, s71, 0x2000
	s_add_u32 s72, s58, 0x80000
	s_addc_u32 s73, s59, 0
	s_add_i32 s71, s68, s15
	global_load_lds_dwordx4 v158, s[58:59]
	s_mov_b32 m0, s71
	s_nop 0
	global_load_lds_dwordx4 v154, s[72:73]
	s_add_i32 m0, s71, 0x2000
	s_nop 0
	global_load_lds_dwordx4 v158, s[72:73]
	s_mov_b32 m0, s35
	s_nop 0
	global_load_lds_dwordx4 v152, s[60:61]
	s_mov_b32 m0, s49
	s_nop 0
	global_load_lds_dwordx4 v156, s[60:61]
	s_waitcnt vmcnt(8)
	s_waitcnt lgkmcnt(0)
	s_barrier
	s_setprio 1
	s_waitcnt lgkmcnt(0)
	v_mfma_f32_16x16x32_bf16 v[60:63], v[128:131], v[178:181], v[60:63]
	v_mfma_f32_16x16x32_bf16 v[56:59], v[136:139], v[178:181], v[56:59]
	v_mfma_f32_16x16x32_bf16 v[44:47], v[128:131], v[196:199], v[44:47]
	v_mfma_f32_16x16x32_bf16 v[40:43], v[136:139], v[196:199], v[40:43]
	v_mfma_f32_16x16x32_bf16 v[28:31], v[128:131], v[204:207], v[28:31]
	v_mfma_f32_16x16x32_bf16 v[24:27], v[136:139], v[204:207], v[24:27]
	v_mfma_f32_16x16x32_bf16 v[12:15], v[128:131], v[212:215], v[12:15]
	v_mfma_f32_16x16x32_bf16 v[8:11], v[136:139], v[212:215], v[8:11]
	v_mfma_f32_16x16x32_bf16 v[60:63], v[132:135], v[182:185], v[60:63]
	v_mfma_f32_16x16x32_bf16 v[56:59], v[140:143], v[182:185], v[56:59]
	v_mfma_f32_16x16x32_bf16 v[44:47], v[132:135], v[200:203], v[44:47]
	v_mfma_f32_16x16x32_bf16 v[40:43], v[140:143], v[200:203], v[40:43]
	v_mfma_f32_16x16x32_bf16 v[28:31], v[132:135], v[208:211], v[28:31]
	v_mfma_f32_16x16x32_bf16 v[24:27], v[140:143], v[208:211], v[24:27]
	v_mfma_f32_16x16x32_bf16 v[12:15], v[132:135], v[216:219], v[12:15]
	v_mfma_f32_16x16x32_bf16 v[8:11], v[140:143], v[216:219], v[8:11]
	s_setprio 0
	s_setprio 1
	v_mfma_f32_16x16x32_bf16 v[52:55], v[144:147], v[178:181], v[52:55]
	v_mfma_f32_16x16x32_bf16 v[48:51], v[168:171], v[178:181], v[48:51]
	v_mfma_f32_16x16x32_bf16 v[36:39], v[144:147], v[196:199], v[36:39]
	v_mfma_f32_16x16x32_bf16 v[32:35], v[168:171], v[196:199], v[32:35]
	v_mfma_f32_16x16x32_bf16 v[20:23], v[144:147], v[204:207], v[20:23]
	v_mfma_f32_16x16x32_bf16 v[16:19], v[168:171], v[204:207], v[16:19]
	v_mfma_f32_16x16x32_bf16 v[4:7], v[144:147], v[212:215], v[4:7]
	v_mfma_f32_16x16x32_bf16 v[0:3], v[168:171], v[212:215], v[0:3]
	v_mfma_f32_16x16x32_bf16 v[52:55], v[148:151], v[182:185], v[52:55]
	v_mfma_f32_16x16x32_bf16 v[48:51], v[172:175], v[182:185], v[48:51]
	v_mfma_f32_16x16x32_bf16 v[36:39], v[148:151], v[200:203], v[36:39]
	v_mfma_f32_16x16x32_bf16 v[32:35], v[172:175], v[200:203], v[32:35]
	v_mfma_f32_16x16x32_bf16 v[20:23], v[148:151], v[208:211], v[20:23]
	v_mfma_f32_16x16x32_bf16 v[16:19], v[172:175], v[208:211], v[16:19]
	v_mfma_f32_16x16x32_bf16 v[4:7], v[148:151], v[216:219], v[4:7]
	v_mfma_f32_16x16x32_bf16 v[0:3], v[172:175], v[216:219], v[0:3]
	s_setprio 0
	s_barrier
; #define PG8_STAGE(bufoff, gbase, voff) do { _Pragma("unroll") for (int _i = 0; _i < 2; ++_i) \
;         __builtin_amdgcn_global_load_lds((const unsigned*)((const char*)(gbase) + (voff)[_i]), (LAS unsigned*)(lds + (bufoff) + ldsw + _i * 8192), 16, 0, 0); } while (0)
; #define PG8_LDA(dst, b, h) do { _Pragma("unroll") for (int m = 0; m < 4; ++m) _Pragma("unroll") for (int k = 0; k < 2; ++k) dst[m][k] = *(const LAS bf16x8*)(lds + PG8_SA(b, h) + aoff + m * 2048 + k * 1024); } while (0)
; #define PG8_LDB(dst, b, h) do { _Pragma("unroll") for (int n = 0; n < 2; ++n) _Pragma("unroll") for (int k = 0; k < 2; ++k) dst[n][k] = *(const LAS bf16x8*)(lds + PG8_SB(b, h) + boff + n * 2048 + k * 1024); } while (0)
; #define PG8_MMA(ai, bj, At, Bt) do { __builtin_amdgcn_s_setprio(1); _Pragma("unroll") for (int m = 0; m < 4; ++m) _Pragma("unroll") for (int n = 0; n < 2; ++n) _Pragma("unroll") for (int k = 0; k < 2; ++k) \
;         acc[ai][bj][m][n] = __builtin_amdgcn_mfma_f32_16x16x32_bf16(Bt[n][k], At[m][k], acc[ai][bj][m][n], 0, 0, 0); __builtin_amdgcn_s_setprio(0); } while (0)
; #define PG8_WAIT_V(n) asm volatile("s_waitcnt vmcnt(" #n ")" ::: "memory")
; #define PG8_WAIT_L(n) asm volatile("s_waitcnt lgkmcnt(" #n ")" ::: "memory")
; #define PG8_BAR __builtin_amdgcn_s_barrier()
; #define PG8_SCHED __builtin_amdgcn_sched_barrier(0)
; template <class Epi, class Sched, bool ALIGN_EPI = false, bool SP2 = false>
; __device__ __forceinline__ void gemm_phase(LAS unsigned char* lds, const Gemm g, const Sched& S, const Epi& E) {
;     ...
;             PG8_LDB(B0, 1, 0); PG8_LDB(B1, 1, 1); PG8_SCHED; PG8_LDA(At, 1, 0); PG8_STAGE(PG8_SA(0, 1), a2 + hstep, voffA);
;             PG8_WAIT_V(8); PG8_WAIT_L(0); PG8_BAR; PG8_MMA(0, 0, At, B0); PG8_MMA(0, 1, At, B1); PG8_BAR; PG8_SCHED;
;             PG8_LDA(At, 1, 1); PG8_STAGE(PG8_SB(1, 0), b3, voffB); PG8_STAGE(PG8_SB(1, 1), b3 + hstep, voffB); PG8_STAGE(PG8_SA(1, 0), a3, voffA);
;             PG8_WAIT_V(8); PG8_WAIT_L(0); PG8_BAR; PG8_MMA(1, 0, At, B0); PG8_MMA(1, 1, At, B1); PG8_BAR; PG8_SCHED;
	s_add_i32 s71, 0, 0x18000
	s_add_i32 s72, 0, 0x1c000
	v_add_u32_e32 v140, s71, v190
	v_add_u32_e32 v172, s72, v190
	ds_read_b128 v[128:131], v140
	ds_read_b128 v[132:135], v140 offset:1024
	ds_read_b128 v[136:139], v140 offset:2048
	ds_read_b128 v[140:143], v140 offset:3072
	ds_read_b128 v[144:147], v172
	ds_read_b128 v[148:151], v172 offset:1024
	ds_read_b128 v[168:171], v172 offset:2048
	ds_read_b128 v[172:175], v172 offset:3072
	s_add_u32 s60, s60, 0x80000
	s_addc_u32 s61, s61, 0
	s_mov_b32 m0, s62
	ds_read_b128 v[178:181], v194 offset:32768
	ds_read_b128 v[182:185], v194 offset:33792
	ds_read_b128 v[196:199], v194 offset:34816
	ds_read_b128 v[200:203], v194 offset:35840
	ds_read_b128 v[204:207], v194 offset:36864
	ds_read_b128 v[208:211], v194 offset:37888
	ds_read_b128 v[212:215], v194 offset:38912
	ds_read_b128 v[216:219], v194 offset:39936
	global_load_lds_dwordx4 v152, s[60:61]
	s_mov_b32 m0, s63
	s_nop 0
	global_load_lds_dwordx4 v156, s[60:61]
	s_waitcnt vmcnt(8)
	s_waitcnt lgkmcnt(0)
	s_barrier
	s_setprio 1
	s_waitcnt lgkmcnt(0)
	v_mfma_f32_16x16x32_bf16 v[124:127], v[128:131], v[178:181], v[124:127]
	v_mfma_f32_16x16x32_bf16 v[120:123], v[136:139], v[178:181], v[120:123]
	v_mfma_f32_16x16x32_bf16 v[108:111], v[128:131], v[196:199], v[108:111]
	v_mfma_f32_16x16x32_bf16 v[104:107], v[136:139], v[196:199], v[104:107]
	v_mfma_f32_16x16x32_bf16 v[92:95], v[128:131], v[204:207], v[92:95]
	v_mfma_f32_16x16x32_bf16 v[88:91], v[136:139], v[204:207], v[88:91]
	v_mfma_f32_16x16x32_bf16 v[76:79], v[128:131], v[212:215], v[76:79]
	v_mfma_f32_16x16x32_bf16 v[72:75], v[136:139], v[212:215], v[72:75]
	v_mfma_f32_16x16x32_bf16 v[124:127], v[132:135], v[182:185], v[124:127]
	v_mfma_f32_16x16x32_bf16 v[120:123], v[140:143], v[182:185], v[120:123]
	v_mfma_f32_16x16x32_bf16 v[108:111], v[132:135], v[200:203], v[108:111]
	v_mfma_f32_16x16x32_bf16 v[104:107], v[140:143], v[200:203], v[104:107]
	v_mfma_f32_16x16x32_bf16 v[92:95], v[132:135], v[208:211], v[92:95]
	v_mfma_f32_16x16x32_bf16 v[88:91], v[140:143], v[208:211], v[88:91]
	v_mfma_f32_16x16x32_bf16 v[76:79], v[132:135], v[216:219], v[76:79]
	v_mfma_f32_16x16x32_bf16 v[72:75], v[140:143], v[216:219], v[72:75]
	s_setprio 0
	s_setprio 1
	v_mfma_f32_16x16x32_bf16 v[116:119], v[144:147], v[178:181], v[116:119]
	v_mfma_f32_16x16x32_bf16 v[112:115], v[168:171], v[178:181], v[112:115]
	v_mfma_f32_16x16x32_bf16 v[100:103], v[144:147], v[196:199], v[100:103]
	v_mfma_f32_16x16x32_bf16 v[96:99], v[168:171], v[196:199], v[96:99]
	v_mfma_f32_16x16x32_bf16 v[84:87], v[144:147], v[204:207], v[84:87]
	v_mfma_f32_16x16x32_bf16 v[80:83], v[168:171], v[204:207], v[80:83]
	v_mfma_f32_16x16x32_bf16 v[68:71], v[144:147], v[212:215], v[68:71]
	v_mfma_f32_16x16x32_bf16 v[64:67], v[168:171], v[212:215], v[64:67]
	v_mfma_f32_16x16x32_bf16 v[116:119], v[148:151], v[182:185], v[116:119]
	v_mfma_f32_16x16x32_bf16 v[112:115], v[172:175], v[182:185], v[112:115]
	v_mfma_f32_16x16x32_bf16 v[100:103], v[148:151], v[200:203], v[100:103]
	v_mfma_f32_16x16x32_bf16 v[96:99], v[172:175], v[200:203], v[96:99]
	v_mfma_f32_16x16x32_bf16 v[84:87], v[148:151], v[208:211], v[84:87]
	v_mfma_f32_16x16x32_bf16 v[80:83], v[172:175], v[208:211], v[80:83]
	v_mfma_f32_16x16x32_bf16 v[68:71], v[148:151], v[216:219], v[68:71]
	v_mfma_f32_16x16x32_bf16 v[64:67], v[172:175], v[216:219], v[64:67]
	s_setprio 0
	s_barrier
	s_add_i32 s60, s71, s15
	s_mov_b32 m0, s60
	ds_read_b128 v[178:181], v194 offset:49152
	ds_read_b128 v[182:185], v194 offset:50176
	ds_read_b128 v[196:199], v194 offset:51200
	ds_read_b128 v[200:203], v194 offset:52224
	ds_read_b128 v[204:207], v194 offset:53248
	ds_read_b128 v[208:211], v194 offset:54272
	ds_read_b128 v[212:215], v194 offset:55296
	ds_read_b128 v[216:219], v194 offset:56320
	global_load_lds_dwordx4 v154, s[98:99]
	s_add_i32 m0, s60, 0x2000
	s_add_u32 s58, s58, 0x80080
	s_addc_u32 s59, s59, 0
	s_add_i32 s60, s72, s15
	global_load_lds_dwordx4 v158, s[98:99]
	s_mov_b32 m0, s60
	s_nop 0
	global_load_lds_dwordx4 v154, s[58:59]
	s_add_i32 m0, s60, 0x2000
	s_nop 0
	global_load_lds_dwordx4 v158, s[58:59]
	s_mov_b32 m0, s65
	s_nop 0
	global_load_lds_dwordx4 v152, s[100:101]
	s_mov_b32 m0, s66
	s_nop 0
	global_load_lds_dwordx4 v156, s[100:101]
	s_waitcnt vmcnt(8)
	s_waitcnt lgkmcnt(0)
	s_barrier
	s_setprio 1
	s_waitcnt lgkmcnt(0)
	v_mfma_f32_16x16x32_bf16 v[60:63], v[128:131], v[178:181], v[60:63]
	v_mfma_f32_16x16x32_bf16 v[56:59], v[136:139], v[178:181], v[56:59]
	v_mfma_f32_16x16x32_bf16 v[44:47], v[128:131], v[196:199], v[44:47]
	v_mfma_f32_16x16x32_bf16 v[40:43], v[136:139], v[196:199], v[40:43]
	v_mfma_f32_16x16x32_bf16 v[28:31], v[128:131], v[204:207], v[28:31]
	v_mfma_f32_16x16x32_bf16 v[24:27], v[136:139], v[204:207], v[24:27]
	v_mfma_f32_16x16x32_bf16 v[12:15], v[128:131], v[212:215], v[12:15]
	v_mfma_f32_16x16x32_bf16 v[8:11], v[136:139], v[212:215], v[8:11]
	v_mfma_f32_16x16x32_bf16 v[60:63], v[132:135], v[182:185], v[60:63]
	v_mfma_f32_16x16x32_bf16 v[56:59], v[140:143], v[182:185], v[56:59]
	v_mfma_f32_16x16x32_bf16 v[44:47], v[132:135], v[200:203], v[44:47]
	v_mfma_f32_16x16x32_bf16 v[40:43], v[140:143], v[200:203], v[40:43]
	v_mfma_f32_16x16x32_bf16 v[28:31], v[132:135], v[208:211], v[28:31]
	v_mfma_f32_16x16x32_bf16 v[24:27], v[140:143], v[208:211], v[24:27]
	v_mfma_f32_16x16x32_bf16 v[12:15], v[132:135], v[216:219], v[12:15]
	v_mfma_f32_16x16x32_bf16 v[8:11], v[140:143], v[216:219], v[8:11]
	s_setprio 0
	s_setprio 1
	v_mfma_f32_16x16x32_bf16 v[52:55], v[144:147], v[178:181], v[52:55]
	v_mfma_f32_16x16x32_bf16 v[48:51], v[168:171], v[178:181], v[48:51]
	v_mfma_f32_16x16x32_bf16 v[36:39], v[144:147], v[196:199], v[36:39]
	v_mfma_f32_16x16x32_bf16 v[32:35], v[168:171], v[196:199], v[32:35]
	v_mfma_f32_16x16x32_bf16 v[20:23], v[144:147], v[204:207], v[20:23]
	v_mfma_f32_16x16x32_bf16 v[16:19], v[168:171], v[204:207], v[16:19]
	v_mfma_f32_16x16x32_bf16 v[4:7], v[144:147], v[212:215], v[4:7]
	v_mfma_f32_16x16x32_bf16 v[0:3], v[168:171], v[212:215], v[0:3]
	v_mfma_f32_16x16x32_bf16 v[52:55], v[148:151], v[182:185], v[52:55]
	v_mfma_f32_16x16x32_bf16 v[48:51], v[172:175], v[182:185], v[48:51]
	v_mfma_f32_16x16x32_bf16 v[36:39], v[148:151], v[200:203], v[36:39]
	v_mfma_f32_16x16x32_bf16 v[32:35], v[172:175], v[200:203], v[32:35]
	v_mfma_f32_16x16x32_bf16 v[20:23], v[148:151], v[208:211], v[20:23]
	v_mfma_f32_16x16x32_bf16 v[16:19], v[172:175], v[208:211], v[16:19]
	v_mfma_f32_16x16x32_bf16 v[4:7], v[148:151], v[216:219], v[4:7]
	v_mfma_f32_16x16x32_bf16 v[0:3], v[172:175], v[216:219], v[0:3]
	s_setprio 0
	s_barrier
	s_add_i32 s70, s70, 2
	s_add_u32 s50, s50, 0x100
	s_addc_u32 s51, s51, 0
	s_add_u32 s47, s47, 0x100
	s_addc_u32 s69, s69, 0
	s_cmp_gt_u32 s70, 29
	s_cbranch_scc0 .LBB0_626
	s_branch .Lsapad2
	s_nop 0
	s_nop 0
	s_nop 0
	s_nop 0
	s_nop 0
	s_nop 0
	s_nop 0
	s_nop 0
	s_nop 0
	s_nop 0
	s_nop 0
	s_nop 0
	s_nop 0
	s_nop 0
	s_nop 0
	s_nop 0
	s_nop 0
	s_nop 0
	s_nop 0
	s_nop 0
	s_nop 0
	s_nop 0
	s_nop 0
	s_nop 0
;     __device__ __forceinline__ void load(Row& r, size_t off) const {
; #pragma unroll
;         for (int bj = 0; bj < 2; ++bj) {
;             if (BASE_BF16) r.h[bj] = *(const u32x4*)(baseb + off + bj * HALF);
;             else { r.f[bj][0] = *(const f32x4*)(basef + off + bj * HALF); r.f[bj][1] = *(const f32x4*)(basef + off + bj * HALF + 4); } }
;     }
;     __device__ __forceinline__ void row(const Row& r, const f32x4 (&a)[2][2][4][2], int ai, int m, int row_, int col0, int fq) const {
;         const size_t off = (size_t)row_ * D + col0; float sq = 0.f;
; #pragma unroll
;         for (int bj = 0; bj < 2; ++bj) {
;             f32x4 b0, b1;
;             if (BASE_BF16) { const u32x4 h = r.h[bj];
;                 b0 = (f32x4){__builtin_bit_cast(float, h[0] << 16), __builtin_bit_cast(float, h[0] & 0xffff0000u), __builtin_bit_cast(float, h[1] << 16), __builtin_bit_cast(float, h[1] & 0xffff0000u)};
;                 b1 = (f32x4){__builtin_bit_cast(float, h[2] << 16), __builtin_bit_cast(float, h[2] & 0xffff0000u), __builtin_bit_cast(float, h[3] << 16), __builtin_bit_cast(float, h[3] & 0xffff0000u)}; }
;             else { b0 = r.f[bj][0]; b1 = r.f[bj][1]; }
;             const f32x4 v0 = b0 + a[ai][bj][m][0] * alpha, v1 = b1 + a[ai][bj][m][1] * alpha;
;             u32x4 w; w.x = cvt_pk_bf16(v0[0], v0[1]); w.y = cvt_pk_bf16(v0[2], v0[3]); w.z = cvt_pk_bf16(v1[0], v1[1]); w.w = cvt_pk_bf16(v1[2], v1[3]);
;             *(u32x4*)(xb + off + bj * HALF) = w;
;             sq += (v0[0] * v0[0] + v0[1] * v0[1]) + (v0[2] * v0[2] + v0[3] * v0[3]) + (v1[0] * v1[0] + v1[1] * v1[1]) + (v1[2] * v1[2] + v1[3] * v1[3]);
;         }
;         sq += __shfl_xor(sq, 16); sq += __shfl_xor(sq, 32);
;         if (fq == 0) unsafeAtomicAdd(ss + row_, sq);
;     }
;     __device__ __forceinline__ void operator()(const f32x4 (&acc)[2][2][4][2], const Unit& u, int wr, int wc, int fr, int fq, const Pre&) const {
;         const int row0 = u.pm * BM + wr * 64 + fr, col0 = u.pn * BM + wc * 32 + 8 * fq;
;         Row pre[4];
; #pragma unroll
;         for (int m = 0; m < 4; ++m) load(pre[m], (size_t)(row0 + m * 16) * D + col0);
;         asm volatile("" ::: "memory");
; #pragma unroll
;         for (int m = 0; m < 4; ++m) {
;             row(pre[m], acc, 0, m, row0 + m * 16, col0, fq);
;             load(pre[m], (size_t)(row0 + HALF + m * 16) * D + col0);
.Lsapad2:
	s_and_b64 vcc, exec, s[36:37]
	s_cbranch_vccz .LBB0_629
	s_barrier
.LBB0_629:
	v_lshl_or_b32 v168, s48, 8, v191
	v_lshl_add_u32 v170, s46, 8, v189
	v_ashrrev_i32_e32 v169, 31, v168
	v_lshlrev_b64 v[172:173], 1, v[168:169]
	v_ashrrev_i32_e32 v171, 31, v170
	v_lshl_add_u64 v[128:129], s[20:21], 0, v[172:173]
	v_lshlrev_b64 v[196:197], 12, v[170:171]
	v_lshl_add_u64 v[130:131], v[128:129], 0, v[196:197]
	global_load_dwordx4 v[198:201], v[130:131], off
	global_load_dwordx4 v[202:205], v[130:131], off offset:256
	v_or_b32_e32 v184, 16, v170
	v_or_b32_e32 v180, 32, v170
	v_or_b32_e32 v174, 48, v170
	v_ashrrev_i32_e32 v185, 31, v184
	v_ashrrev_i32_e32 v181, 31, v180
	v_ashrrev_i32_e32 v175, 31, v174
	v_lshlrev_b64 v[186:187], 12, v[184:185]
	v_lshlrev_b64 v[182:183], 12, v[180:181]
	v_lshlrev_b64 v[178:179], 12, v[174:175]
	v_lshl_add_u64 v[130:131], v[128:129], 0, v[186:187]
	v_lshl_add_u64 v[132:133], v[128:129], 0, v[182:183]
	v_lshl_add_u64 v[128:129], v[128:129], 0, v[178:179]
	global_load_dwordx4 v[148:151], v[130:131], off
	global_load_dwordx4 v[144:147], v[130:131], off offset:256
	global_load_dwordx4 v[140:143], v[132:133], off
	global_load_dwordx4 v[136:139], v[132:133], off offset:256
	s_nop 0
	global_load_dwordx4 v[132:135], v[128:129], off
	s_nop 0
	global_load_dwordx4 v[128:131], v[128:129], off offset:256
	v_and_b32_e32 v207, 64, v195
	v_xor_b32_e32 v206, 16, v195
	v_add_u32_e32 v207, 64, v207
	v_xor_b32_e32 v208, 32, v195
	v_cmp_lt_i32_e32 vcc, v206, v207
	s_waitcnt vmcnt(0)
	v_lshlrev_b32_e32 v210, 16, v200
	v_cndmask_b32_e32 v209, v195, v206, vcc
	v_cmp_lt_i32_e32 vcc, v208, v207
	v_lshl_add_u64 v[206:207], s[20:21], 0, v[196:197]
	v_lshlrev_b32_e32 v196, 2, v209
	v_cndmask_b32_e32 v216, v195, v208, vcc
	v_lshlrev_b32_e32 v208, 16, v198
	v_and_b32_e32 v209, 0xffff0000, v198
	v_lshlrev_b32_e32 v198, 16, v199
	v_and_b32_e32 v199, 0xffff0000, v199
	v_lshlrev_b32_e32 v212, 16, v202
	v_and_b32_e32 v213, 0xffff0000, v202
	v_lshlrev_b32_e32 v202, 16, v203
	v_and_b32_e32 v203, 0xffff0000, v203
	v_and_b32_e32 v211, 0xffff0000, v200
	v_lshlrev_b32_e32 v200, 16, v201
	v_and_b32_e32 v201, 0xffff0000, v201
	v_lshlrev_b32_e32 v214, 16, v204
	v_and_b32_e32 v215, 0xffff0000, v204
	v_lshlrev_b32_e32 v204, 16, v205
	v_and_b32_e32 v205, 0xffff0000, v205
	v_pk_add_f32 v[126:127], v[126:127], v[198:199]
	v_pk_add_f32 v[124:125], v[124:125], v[208:209]
	v_pk_add_f32 v[118:119], v[118:119], v[202:203]
	v_pk_add_f32 v[116:117], v[116:117], v[212:213]
	v_pk_add_f32 v[122:123], v[122:123], v[200:201]
	v_pk_add_f32 v[120:121], v[120:121], v[210:211]
	v_pk_add_f32 v[198:199], v[114:115], v[204:205]
	v_pk_add_f32 v[200:201], v[112:113], v[214:215]
	v_mul_f32_e32 v114, v125, v125
	v_mul_f32_e32 v115, v127, v127
	v_mul_f32_e32 v197, v117, v117
	v_mul_f32_e32 v202, v119, v119
	v_cvt_pk_bf16_f32 v112, v124, v125
	v_mul_f32_e32 v125, v121, v121
	v_mul_f32_e32 v203, v201, v201
	v_fmac_f32_e32 v114, v124, v124
	v_fmac_f32_e32 v115, v126, v126
	v_fmac_f32_e32 v197, v116, v116
	v_fmac_f32_e32 v202, v118, v118
	v_cvt_pk_bf16_f32 v113, v126, v127
	v_mul_f32_e32 v127, v123, v123
	v_mul_f32_e32 v204, v199, v199
	v_fmac_f32_e32 v125, v120, v120
	v_fmac_f32_e32 v203, v200, v200
	v_add_f32_e32 v114, v114, v115
	v_add_f32_e32 v115, v197, v202
	v_fmac_f32_e32 v127, v122, v122
	v_fmac_f32_e32 v204, v198, v198
	v_add_f32_e32 v114, v125, v114
	v_add_f32_e32 v115, v203, v115
	v_add_f32_e32 v114, v127, v114
	v_add_f32_e32 v115, v204, v115
	v_add_f32_e32 v124, v114, v115
	ds_bpermute_b32 v125, v196, v124
	v_lshl_add_u64 v[206:207], v[206:207], 0, v[172:173]
	v_cvt_pk_bf16_f32 v114, v120, v121
	v_cvt_pk_bf16_f32 v115, v122, v123
	global_store_dwordx4 v[206:207], v[112:115], off
	s_waitcnt lgkmcnt(0)
	s_nop 0
	v_add_f32_e32 v112, v124, v125
	v_lshlrev_b32_e32 v124, 2, v216
	ds_bpermute_b32 v113, v124, v112
	v_cvt_pk_bf16_f32 v114, v116, v117
	v_cvt_pk_bf16_f32 v115, v118, v119
	v_cvt_pk_bf16_f32 v116, v200, v201
	v_cvt_pk_bf16_f32 v117, v198, v199
	global_store_dwordx4 v[206:207], v[114:117], off offset:256
	s_and_saveexec_b64 s[46:47], s[6:7]
	s_cbranch_execz .LBB0_631
	v_lshl_add_u64 v[114:115], v[170:171], 2, s[0:1]
	s_waitcnt lgkmcnt(0)
	v_add_f32_e32 v112, v112, v113
	global_atomic_add_f32 v[114:115], v112, off

; #define PG8_STAGE(bufoff, gbase, voff) do { _Pragma("unroll") for (int _i = 0; _i < 2; ++_i) \
;         __builtin_amdgcn_global_load_lds((const unsigned*)((const char*)(gbase) + (voff)[_i]), (LAS unsigned*)(lds + (bufoff) + ldsw + _i * 8192), 16, 0, 0); } while (0)
; #define PG8_LDA(dst, b, h) do { _Pragma("unroll") for (int m = 0; m < 4; ++m) _Pragma("unroll") for (int k = 0; k < 2; ++k) dst[m][k] = *(const LAS bf16x8*)(lds + PG8_SA(b, h) + aoff + m * 2048 + k * 1024); } while (0)
; #define PG8_LDB(dst, b, h) do { _Pragma("unroll") for (int n = 0; n < 2; ++n) _Pragma("unroll") for (int k = 0; k < 2; ++k) dst[n][k] = *(const LAS bf16x8*)(lds + PG8_SB(b, h) + boff + n * 2048 + k * 1024); } while (0)
; #define PG8_MMA(ai, bj, At, Bt) do { __builtin_amdgcn_s_setprio(1); _Pragma("unroll") for (int m = 0; m < 4; ++m) _Pragma("unroll") for (int n = 0; n < 2; ++n) _Pragma("unroll") for (int k = 0; k < 2; ++k) \
;         acc[ai][bj][m][n] = __builtin_amdgcn_mfma_f32_16x16x32_bf16(Bt[n][k], At[m][k], acc[ai][bj][m][n], 0, 0, 0); __builtin_amdgcn_s_setprio(0); } while (0)
; #define PG8_WAIT_V(n) asm volatile("s_waitcnt vmcnt(" #n ")" ::: "memory")
; #define PG8_WAIT_L(n) asm volatile("s_waitcnt lgkmcnt(" #n ")" ::: "memory")
; #define PG8_BAR __builtin_amdgcn_s_barrier()
; template <class Epi, class Sched, bool ALIGN_EPI = false, bool SP2 = false>
; __device__ __forceinline__ void gemm_phase(LAS unsigned char* lds, const Gemm g, const Sched& S, const Epi& E) {
;     ...
;             const char* a1 = cA + (size_t)(t + 1) * kstep;
;             const char* a2 = last ? nA : cA + (size_t)(t + 2) * kstep; const char* b2 = last ? nB : cB + (size_t)(t + 2) * kstep;
;             const char* a3 = a2 + kstep; const char* b3 = b2 + kstep;
;             if (last && has_next) { S.a_ready(nxt); pre_nxt = E.pre(nxt, wr, fr); }
;             if constexpr (SP2) {
;             PG8_LDB(B0, 0, 0); PG8_LDB(B1, 0, 1); PG8_SCHED; PG8_LDA(At, 0, 0); PG8_STAGE(PG8_SA(1, 1), a1 + hstep, voffA);
;             PG8_WAIT_V(8); PG8_WAIT_L(0); PG8_BAR; PG8_MMA(0, 0, At, B0); PG8_MMA(0, 1, At, B1); PG8_BAR; PG8_SCHED;
;             PG8_LDA(At, 0, 1); PG8_STAGE(PG8_SB(0, 0), b2, voffB); PG8_STAGE(PG8_SB(0, 1), b2 + hstep, voffB); PG8_STAGE(PG8_SA(0, 0), a2, voffA);
;             PG8_WAIT_V(8); PG8_WAIT_L(0); PG8_BAR; PG8_MMA(1, 0, At, B0); PG8_MMA(1, 1, At, B1); PG8_BAR; PG8_SCHED;
.LBB0_710:
	v_add_u32_e32 v169, s58, v150
	ds_read_b128 v[170:173], v169
	ds_read_b128 v[178:181], v169 offset:1024
	ds_read_b128 v[182:185], v169 offset:2048
	ds_read_b128 v[190:193], v169 offset:3072
	v_add_u32_e32 v169, s59, v150
	ds_read_b128 v[194:197], v169
	ds_read_b128 v[198:201], v169 offset:1024
	ds_read_b128 v[202:205], v169 offset:2048
	ds_read_b128 v[206:209], v169 offset:3072
	s_add_u32 s44, s40, 0xfff80080
	s_addc_u32 s45, s41, -1
	s_and_b64 s[42:43], s[42:43], exec
	s_cselect_b32 s45, s27, s45
	s_cselect_b32 s44, s62, s44
	s_cselect_b32 s43, s19, s16
	s_cselect_b32 s42, s63, s64
	s_add_i32 m0, s39, 0xc000
	ds_read_b128 v[210:213], v152
	ds_read_b128 v[214:217], v152 offset:1024
	ds_read_b128 v[218:221], v152 offset:2048
	ds_read_b128 v[222:225], v152 offset:3072
	ds_read_b128 v[226:229], v152 offset:4096
	ds_read_b128 v[230:233], v152 offset:5120
	ds_read_b128 v[234:237], v152 offset:6144
	ds_read_b128 v[238:241], v152 offset:7168
	global_load_lds_dwordx4 v138, s[40:41]
	s_add_i32 m0, s39, 0xe000
	s_nop 0
	global_load_lds_dwordx4 v140, s[40:41]
	s_waitcnt vmcnt(8)
	s_waitcnt lgkmcnt(0)
	s_barrier
	s_setprio 1
	s_waitcnt lgkmcnt(0)
	v_mfma_f32_16x16x32_bf16 v[124:127], v[170:173], v[210:213], v[124:127]
	v_mfma_f32_16x16x32_bf16 v[120:123], v[182:185], v[210:213], v[120:123]
	v_mfma_f32_16x16x32_bf16 v[108:111], v[170:173], v[218:221], v[108:111]
	v_mfma_f32_16x16x32_bf16 v[104:107], v[182:185], v[218:221], v[104:107]
	v_mfma_f32_16x16x32_bf16 v[92:95], v[170:173], v[226:229], v[92:95]
	v_mfma_f32_16x16x32_bf16 v[88:91], v[182:185], v[226:229], v[88:91]
	v_mfma_f32_16x16x32_bf16 v[76:79], v[170:173], v[234:237], v[76:79]
	v_mfma_f32_16x16x32_bf16 v[72:75], v[182:185], v[234:237], v[72:75]
	v_mfma_f32_16x16x32_bf16 v[124:127], v[178:181], v[214:217], v[124:127]
	v_mfma_f32_16x16x32_bf16 v[120:123], v[190:193], v[214:217], v[120:123]
	v_mfma_f32_16x16x32_bf16 v[108:111], v[178:181], v[222:225], v[108:111]
	v_mfma_f32_16x16x32_bf16 v[104:107], v[190:193], v[222:225], v[104:107]
	v_mfma_f32_16x16x32_bf16 v[92:95], v[178:181], v[230:233], v[92:95]
	v_mfma_f32_16x16x32_bf16 v[88:91], v[190:193], v[230:233], v[88:91]
	v_mfma_f32_16x16x32_bf16 v[76:79], v[178:181], v[238:241], v[76:79]
	v_mfma_f32_16x16x32_bf16 v[72:75], v[190:193], v[238:241], v[72:75]
	s_setprio 0
	s_setprio 1
	v_mfma_f32_16x16x32_bf16 v[116:119], v[194:197], v[210:213], v[116:119]
	v_mfma_f32_16x16x32_bf16 v[112:115], v[202:205], v[210:213], v[112:115]
	v_mfma_f32_16x16x32_bf16 v[100:103], v[194:197], v[218:221], v[100:103]
	v_mfma_f32_16x16x32_bf16 v[96:99], v[202:205], v[218:221], v[96:99]
	v_mfma_f32_16x16x32_bf16 v[84:87], v[194:197], v[226:229], v[84:87]
	v_mfma_f32_16x16x32_bf16 v[80:83], v[202:205], v[226:229], v[80:83]
	v_mfma_f32_16x16x32_bf16 v[68:71], v[194:197], v[234:237], v[68:71]
	v_mfma_f32_16x16x32_bf16 v[64:67], v[202:205], v[234:237], v[64:67]
	v_mfma_f32_16x16x32_bf16 v[116:119], v[198:201], v[214:217], v[116:119]
	v_mfma_f32_16x16x32_bf16 v[112:115], v[206:209], v[214:217], v[112:115]
	v_mfma_f32_16x16x32_bf16 v[100:103], v[198:201], v[222:225], v[100:103]
	v_mfma_f32_16x16x32_bf16 v[96:99], v[206:209], v[222:225], v[96:99]
	v_mfma_f32_16x16x32_bf16 v[84:87], v[198:201], v[230:233], v[84:87]
	v_mfma_f32_16x16x32_bf16 v[80:83], v[206:209], v[230:233], v[80:83]
	v_mfma_f32_16x16x32_bf16 v[68:71], v[198:201], v[238:241], v[68:71]
	v_mfma_f32_16x16x32_bf16 v[64:67], v[206:209], v[238:241], v[64:67]
	s_setprio 0
	s_barrier
	s_add_u32 s100, s44, 0x80
	s_addc_u32 s101, s45, 0
	s_add_u32 s98, s42, 0x80
	s_addc_u32 s99, s43, 0
	s_add_i32 s65, s58, s15
	s_mov_b32 m0, s65
	ds_read_b128 v[210:213], v152 offset:16384
	ds_read_b128 v[214:217], v152 offset:17408
	ds_read_b128 v[218:221], v152 offset:18432
	ds_read_b128 v[222:225], v152 offset:19456
	ds_read_b128 v[226:229], v152 offset:20480
	ds_read_b128 v[230:233], v152 offset:21504
	ds_read_b128 v[234:237], v152 offset:22528
	ds_read_b128 v[238:241], v152 offset:23552
	global_load_lds_dwordx4 v132, s[42:43]
	s_add_i32 m0, s65, 0x2000
	s_add_u32 s66, s42, 0x80000
	s_addc_u32 s67, s43, 0
	s_add_i32 s65, s59, s15
	global_load_lds_dwordx4 v128, s[42:43]
	s_mov_b32 m0, s65
	s_nop 0
	global_load_lds_dwordx4 v132, s[66:67]
	s_add_i32 m0, s65, 0x2000
	s_nop 0
	global_load_lds_dwordx4 v128, s[66:67]
	s_mov_b32 m0, s39
	s_nop 0
	global_load_lds_dwordx4 v134, s[44:45]
	s_mov_b32 m0, s46
	s_nop 0
	global_load_lds_dwordx4 v130, s[44:45]
	s_waitcnt vmcnt(8)
	s_waitcnt lgkmcnt(0)
	s_barrier
	s_setprio 1
	s_waitcnt lgkmcnt(0)
	v_mfma_f32_16x16x32_bf16 v[60:63], v[170:173], v[210:213], v[60:63]
	v_mfma_f32_16x16x32_bf16 v[56:59], v[182:185], v[210:213], v[56:59]
	v_mfma_f32_16x16x32_bf16 v[44:47], v[170:173], v[218:221], v[44:47]
	v_mfma_f32_16x16x32_bf16 v[40:43], v[182:185], v[218:221], v[40:43]
	v_mfma_f32_16x16x32_bf16 v[28:31], v[170:173], v[226:229], v[28:31]
	v_mfma_f32_16x16x32_bf16 v[24:27], v[182:185], v[226:229], v[24:27]
	v_mfma_f32_16x16x32_bf16 v[12:15], v[170:173], v[234:237], v[12:15]
	v_mfma_f32_16x16x32_bf16 v[8:11], v[182:185], v[234:237], v[8:11]
	v_mfma_f32_16x16x32_bf16 v[60:63], v[178:181], v[214:217], v[60:63]
	v_mfma_f32_16x16x32_bf16 v[56:59], v[190:193], v[214:217], v[56:59]
	v_mfma_f32_16x16x32_bf16 v[44:47], v[178:181], v[222:225], v[44:47]
	v_mfma_f32_16x16x32_bf16 v[40:43], v[190:193], v[222:225], v[40:43]
	v_mfma_f32_16x16x32_bf16 v[28:31], v[178:181], v[230:233], v[28:31]
	v_mfma_f32_16x16x32_bf16 v[24:27], v[190:193], v[230:233], v[24:27]
	v_mfma_f32_16x16x32_bf16 v[12:15], v[178:181], v[238:241], v[12:15]
	v_mfma_f32_16x16x32_bf16 v[8:11], v[190:193], v[238:241], v[8:11]
	s_setprio 0
	s_setprio 1
	v_mfma_f32_16x16x32_bf16 v[52:55], v[194:197], v[210:213], v[52:55]
	v_mfma_f32_16x16x32_bf16 v[48:51], v[202:205], v[210:213], v[48:51]
	v_mfma_f32_16x16x32_bf16 v[36:39], v[194:197], v[218:221], v[36:39]
	v_mfma_f32_16x16x32_bf16 v[32:35], v[202:205], v[218:221], v[32:35]
	v_mfma_f32_16x16x32_bf16 v[20:23], v[194:197], v[226:229], v[20:23]
	v_mfma_f32_16x16x32_bf16 v[16:19], v[202:205], v[226:229], v[16:19]
	v_mfma_f32_16x16x32_bf16 v[4:7], v[194:197], v[234:237], v[4:7]
	v_mfma_f32_16x16x32_bf16 v[0:3], v[202:205], v[234:237], v[0:3]
	v_mfma_f32_16x16x32_bf16 v[52:55], v[198:201], v[214:217], v[52:55]
	v_mfma_f32_16x16x32_bf16 v[48:51], v[206:209], v[214:217], v[48:51]
	v_mfma_f32_16x16x32_bf16 v[36:39], v[198:201], v[222:225], v[36:39]
	v_mfma_f32_16x16x32_bf16 v[32:35], v[206:209], v[222:225], v[32:35]
	v_mfma_f32_16x16x32_bf16 v[20:23], v[198:201], v[230:233], v[20:23]
	v_mfma_f32_16x16x32_bf16 v[16:19], v[206:209], v[230:233], v[16:19]
	v_mfma_f32_16x16x32_bf16 v[4:7], v[198:201], v[238:241], v[4:7]
	v_mfma_f32_16x16x32_bf16 v[0:3], v[206:209], v[238:241], v[0:3]
	s_setprio 0
	s_barrier
; #define PG8_STAGE(bufoff, gbase, voff) do { _Pragma("unroll") for (int _i = 0; _i < 2; ++_i) \
;         __builtin_amdgcn_global_load_lds((const unsigned*)((const char*)(gbase) + (voff)[_i]), (LAS unsigned*)(lds + (bufoff) + ldsw + _i * 8192), 16, 0, 0); } while (0)
; #define PG8_LDA(dst, b, h) do { _Pragma("unroll") for (int m = 0; m < 4; ++m) _Pragma("unroll") for (int k = 0; k < 2; ++k) dst[m][k] = *(const LAS bf16x8*)(lds + PG8_SA(b, h) + aoff + m * 2048 + k * 1024); } while (0)
; #define PG8_LDB(dst, b, h) do { _Pragma("unroll") for (int n = 0; n < 2; ++n) _Pragma("unroll") for (int k = 0; k < 2; ++k) dst[n][k] = *(const LAS bf16x8*)(lds + PG8_SB(b, h) + boff + n * 2048 + k * 1024); } while (0)
; #define PG8_MMA(ai, bj, At, Bt) do { __builtin_amdgcn_s_setprio(1); _Pragma("unroll") for (int m = 0; m < 4; ++m) _Pragma("unroll") for (int n = 0; n < 2; ++n) _Pragma("unroll") for (int k = 0; k < 2; ++k) \
;         acc[ai][bj][m][n] = __builtin_amdgcn_mfma_f32_16x16x32_bf16(Bt[n][k], At[m][k], acc[ai][bj][m][n], 0, 0, 0); __builtin_amdgcn_s_setprio(0); } while (0)
; #define PG8_WAIT_V(n) asm volatile("s_waitcnt vmcnt(" #n ")" ::: "memory")
; #define PG8_WAIT_L(n) asm volatile("s_waitcnt lgkmcnt(" #n ")" ::: "memory")
; #define PG8_BAR __builtin_amdgcn_s_barrier()
; #define PG8_SCHED __builtin_amdgcn_sched_barrier(0)
; template <class Epi, class Sched, bool ALIGN_EPI = false, bool SP2 = false>
; __device__ __forceinline__ void gemm_phase(LAS unsigned char* lds, const Gemm g, const Sched& S, const Epi& E) {
;     ...
;             PG8_LDB(B0, 1, 0); PG8_LDB(B1, 1, 1); PG8_SCHED; PG8_LDA(At, 1, 0); PG8_STAGE(PG8_SA(0, 1), a2 + hstep, voffA);
;             PG8_WAIT_V(8); PG8_WAIT_L(0); PG8_BAR; PG8_MMA(0, 0, At, B0); PG8_MMA(0, 1, At, B1); PG8_BAR; PG8_SCHED;
;             PG8_LDA(At, 1, 1); PG8_STAGE(PG8_SB(1, 0), b3, voffB); PG8_STAGE(PG8_SB(1, 1), b3 + hstep, voffB); PG8_STAGE(PG8_SA(1, 0), a3, voffA);
;             PG8_WAIT_V(8); PG8_WAIT_L(0); PG8_BAR; PG8_MMA(1, 0, At, B0); PG8_MMA(1, 1, At, B1); PG8_BAR; PG8_SCHED;
	s_add_i32 s65, 0, 0x18000
	v_add_u32_e32 v169, s65, v150
	s_add_i32 s66, 0, 0x1c000
	ds_read_b128 v[170:173], v169
	ds_read_b128 v[178:181], v169 offset:1024
	ds_read_b128 v[182:185], v169 offset:2048
	ds_read_b128 v[190:193], v169 offset:3072
	v_add_u32_e32 v169, s66, v150
	ds_read_b128 v[194:197], v169
	ds_read_b128 v[198:201], v169 offset:1024
	ds_read_b128 v[202:205], v169 offset:2048
	ds_read_b128 v[206:209], v169 offset:3072
	s_add_u32 s44, s44, 0x80000
	s_addc_u32 s45, s45, 0
	s_mov_b32 m0, s47
	ds_read_b128 v[210:213], v152 offset:32768
	ds_read_b128 v[214:217], v152 offset:33792
	ds_read_b128 v[218:221], v152 offset:34816
	ds_read_b128 v[222:225], v152 offset:35840
	ds_read_b128 v[226:229], v152 offset:36864
	ds_read_b128 v[230:233], v152 offset:37888
	ds_read_b128 v[234:237], v152 offset:38912
	ds_read_b128 v[238:241], v152 offset:39936
	global_load_lds_dwordx4 v134, s[44:45]
	s_mov_b32 m0, s48
	s_nop 0
	global_load_lds_dwordx4 v130, s[44:45]
	s_waitcnt vmcnt(8)
	s_waitcnt lgkmcnt(0)
	s_barrier
	s_setprio 1
	s_waitcnt lgkmcnt(0)
	v_mfma_f32_16x16x32_bf16 v[124:127], v[170:173], v[210:213], v[124:127]
	v_mfma_f32_16x16x32_bf16 v[120:123], v[182:185], v[210:213], v[120:123]
	v_mfma_f32_16x16x32_bf16 v[108:111], v[170:173], v[218:221], v[108:111]
	v_mfma_f32_16x16x32_bf16 v[104:107], v[182:185], v[218:221], v[104:107]
	v_mfma_f32_16x16x32_bf16 v[92:95], v[170:173], v[226:229], v[92:95]
	v_mfma_f32_16x16x32_bf16 v[88:91], v[182:185], v[226:229], v[88:91]
	v_mfma_f32_16x16x32_bf16 v[76:79], v[170:173], v[234:237], v[76:79]
	v_mfma_f32_16x16x32_bf16 v[72:75], v[182:185], v[234:237], v[72:75]
	v_mfma_f32_16x16x32_bf16 v[124:127], v[178:181], v[214:217], v[124:127]
	v_mfma_f32_16x16x32_bf16 v[120:123], v[190:193], v[214:217], v[120:123]
	v_mfma_f32_16x16x32_bf16 v[108:111], v[178:181], v[222:225], v[108:111]
	v_mfma_f32_16x16x32_bf16 v[104:107], v[190:193], v[222:225], v[104:107]
	v_mfma_f32_16x16x32_bf16 v[92:95], v[178:181], v[230:233], v[92:95]
	v_mfma_f32_16x16x32_bf16 v[88:91], v[190:193], v[230:233], v[88:91]
	v_mfma_f32_16x16x32_bf16 v[76:79], v[178:181], v[238:241], v[76:79]
	v_mfma_f32_16x16x32_bf16 v[72:75], v[190:193], v[238:241], v[72:75]
	s_setprio 0
	s_setprio 1
	v_mfma_f32_16x16x32_bf16 v[116:119], v[194:197], v[210:213], v[116:119]
	v_mfma_f32_16x16x32_bf16 v[112:115], v[202:205], v[210:213], v[112:115]
	v_mfma_f32_16x16x32_bf16 v[100:103], v[194:197], v[218:221], v[100:103]
	v_mfma_f32_16x16x32_bf16 v[96:99], v[202:205], v[218:221], v[96:99]
	v_mfma_f32_16x16x32_bf16 v[84:87], v[194:197], v[226:229], v[84:87]
	v_mfma_f32_16x16x32_bf16 v[80:83], v[202:205], v[226:229], v[80:83]
	v_mfma_f32_16x16x32_bf16 v[68:71], v[194:197], v[234:237], v[68:71]
	v_mfma_f32_16x16x32_bf16 v[64:67], v[202:205], v[234:237], v[64:67]
	v_mfma_f32_16x16x32_bf16 v[116:119], v[198:201], v[214:217], v[116:119]
	v_mfma_f32_16x16x32_bf16 v[112:115], v[206:209], v[214:217], v[112:115]
	v_mfma_f32_16x16x32_bf16 v[100:103], v[198:201], v[222:225], v[100:103]
	v_mfma_f32_16x16x32_bf16 v[96:99], v[206:209], v[222:225], v[96:99]
	v_mfma_f32_16x16x32_bf16 v[84:87], v[198:201], v[230:233], v[84:87]
	v_mfma_f32_16x16x32_bf16 v[80:83], v[206:209], v[230:233], v[80:83]
	v_mfma_f32_16x16x32_bf16 v[68:71], v[198:201], v[238:241], v[68:71]
	v_mfma_f32_16x16x32_bf16 v[64:67], v[206:209], v[238:241], v[64:67]
	s_setprio 0
	s_barrier
	s_add_i32 s44, s65, s15
	s_mov_b32 m0, s44
	ds_read_b128 v[210:213], v152 offset:49152
	ds_read_b128 v[214:217], v152 offset:50176
	ds_read_b128 v[218:221], v152 offset:51200
	ds_read_b128 v[222:225], v152 offset:52224
	ds_read_b128 v[226:229], v152 offset:53248
	ds_read_b128 v[230:233], v152 offset:54272
	ds_read_b128 v[234:237], v152 offset:55296
	ds_read_b128 v[238:241], v152 offset:56320
	global_load_lds_dwordx4 v132, s[98:99]
	s_add_i32 m0, s44, 0x2000
	s_add_u32 s42, s42, 0x80080
	s_addc_u32 s43, s43, 0
	s_add_i32 s44, s66, s15
	global_load_lds_dwordx4 v128, s[98:99]
	s_mov_b32 m0, s44
	s_nop 0
	global_load_lds_dwordx4 v132, s[42:43]
	s_add_i32 m0, s44, 0x2000
	s_nop 0
	global_load_lds_dwordx4 v128, s[42:43]
	s_mov_b32 m0, s50
	s_nop 0
	global_load_lds_dwordx4 v134, s[100:101]
	s_mov_b32 m0, s51
	s_nop 0
	global_load_lds_dwordx4 v130, s[100:101]
	s_waitcnt vmcnt(8)
	s_waitcnt lgkmcnt(0)
	s_barrier
	s_setprio 1
	s_waitcnt lgkmcnt(0)
	v_mfma_f32_16x16x32_bf16 v[60:63], v[170:173], v[210:213], v[60:63]
	v_mfma_f32_16x16x32_bf16 v[56:59], v[182:185], v[210:213], v[56:59]
	v_mfma_f32_16x16x32_bf16 v[44:47], v[170:173], v[218:221], v[44:47]
	v_mfma_f32_16x16x32_bf16 v[40:43], v[182:185], v[218:221], v[40:43]
	v_mfma_f32_16x16x32_bf16 v[28:31], v[170:173], v[226:229], v[28:31]
	v_mfma_f32_16x16x32_bf16 v[24:27], v[182:185], v[226:229], v[24:27]
	v_mfma_f32_16x16x32_bf16 v[12:15], v[170:173], v[234:237], v[12:15]
	v_mfma_f32_16x16x32_bf16 v[8:11], v[182:185], v[234:237], v[8:11]
	v_mfma_f32_16x16x32_bf16 v[60:63], v[178:181], v[214:217], v[60:63]
	v_mfma_f32_16x16x32_bf16 v[56:59], v[190:193], v[214:217], v[56:59]
	v_mfma_f32_16x16x32_bf16 v[44:47], v[178:181], v[222:225], v[44:47]
	v_mfma_f32_16x16x32_bf16 v[40:43], v[190:193], v[222:225], v[40:43]
	v_mfma_f32_16x16x32_bf16 v[28:31], v[178:181], v[230:233], v[28:31]
	v_mfma_f32_16x16x32_bf16 v[24:27], v[190:193], v[230:233], v[24:27]
	v_mfma_f32_16x16x32_bf16 v[12:15], v[178:181], v[238:241], v[12:15]
	v_mfma_f32_16x16x32_bf16 v[8:11], v[190:193], v[238:241], v[8:11]
	s_setprio 0
	s_setprio 1
	v_mfma_f32_16x16x32_bf16 v[52:55], v[194:197], v[210:213], v[52:55]
	v_mfma_f32_16x16x32_bf16 v[48:51], v[202:205], v[210:213], v[48:51]
	v_mfma_f32_16x16x32_bf16 v[36:39], v[194:197], v[218:221], v[36:39]
	v_mfma_f32_16x16x32_bf16 v[32:35], v[202:205], v[218:221], v[32:35]
	v_mfma_f32_16x16x32_bf16 v[20:23], v[194:197], v[226:229], v[20:23]
	v_mfma_f32_16x16x32_bf16 v[16:19], v[202:205], v[226:229], v[16:19]
	v_mfma_f32_16x16x32_bf16 v[4:7], v[194:197], v[234:237], v[4:7]
	v_mfma_f32_16x16x32_bf16 v[0:3], v[202:205], v[234:237], v[0:3]
	v_mfma_f32_16x16x32_bf16 v[52:55], v[198:201], v[214:217], v[52:55]
	v_mfma_f32_16x16x32_bf16 v[48:51], v[206:209], v[214:217], v[48:51]
	v_mfma_f32_16x16x32_bf16 v[36:39], v[198:201], v[222:225], v[36:39]
	v_mfma_f32_16x16x32_bf16 v[32:35], v[206:209], v[222:225], v[32:35]
	v_mfma_f32_16x16x32_bf16 v[20:23], v[198:201], v[230:233], v[20:23]
	v_mfma_f32_16x16x32_bf16 v[16:19], v[206:209], v[230:233], v[16:19]
	v_mfma_f32_16x16x32_bf16 v[4:7], v[198:201], v[238:241], v[4:7]
	v_mfma_f32_16x16x32_bf16 v[0:3], v[206:209], v[238:241], v[0:3]
	s_setprio 0
	s_barrier
	s_add_i32 s17, s17, 2
	s_add_u32 s40, s40, 0x100
	s_addc_u32 s41, s41, 0
	s_add_u32 s64, s64, 0x100
	s_addc_u32 s16, s16, 0
	s_cmp_gt_u32 s17, 29
	s_cbranch_scc1 .LBB0_713
;     __device__ __forceinline__ Pre pre(const Unit& u, int wr, int fr) const { return load_rows8(ss, u, wr, fr); }
;     __device__ __forceinline__ Pre pre(const Unit& u, int wr, int fr) const { return load_rows8(ss, u, wr, fr); }
; template <class Epi, class Sched, bool ALIGN_EPI = false, bool SP2 = false>
; __device__ __forceinline__ void gemm_phase(LAS unsigned char* lds, const Gemm g, const Sched& S, const Epi& E) {
;     ...
;             const bool last = (t == nt - 2);
;             const char* a1 = cA + (size_t)(t + 1) * kstep;
;             const char* a2 = last ? nA : cA + (size_t)(t + 2) * kstep; const char* b2 = last ? nB : cB + (size_t)(t + 2) * kstep;
;             const char* a3 = a2 + kstep; const char* b3 = b2 + kstep;
;             if (last && has_next) { S.a_ready(nxt); pre_nxt = E.pre(nxt, wr, fr); }
; __device__ __forceinline__ PreRows load_rows8(const float* ss, const Unit& u, int wr, int fr) {
;     PreRows p; const float* b = ss + u.pm * BM + wr * 64 + fr;
; #pragma unroll
;     for (int ai = 0; ai < 2; ++ai)
; #pragma unroll
;         for (int m = 0; m < 4; ++m) p.v[ai * 4 + m] = b[ai * HALF + m * 16];
;     return p;
.LBB0_711:
	s_cmp_eq_u32 s17, 28
	s_cselect_b64 s[42:43], -1, 0
	s_and_b64 s[44:45], s[6:7], s[42:43]
	s_andn2_b64 vcc, exec, s[44:45]
	s_cbranch_vccnz .LBB0_710
	global_load_dword v155, v[146:147], off
	global_load_dword v156, v[146:147], off offset:64
	global_load_dword v157, v[146:147], off offset:128
	global_load_dword v158, v[146:147], off offset:192
	global_load_dword v159, v[146:147], off offset:512
	global_load_dword v161, v[146:147], off offset:576
	global_load_dword v162, v[146:147], off offset:640
	global_load_dword v163, v[146:147], off offset:704
	s_branch .LBB0_710
	s_nop 0
	s_nop 0
	s_nop 0
	s_nop 0
	s_nop 0
	s_nop 0
	s_nop 0
	s_nop 0
	s_nop 0
	s_nop 0
	s_nop 0
	s_nop 0
	s_nop 0
	s_nop 0
	s_nop 0
	s_nop 0
	s_nop 0
	s_nop 0
	s_nop 0
	s_nop 0
	s_nop 0
	s_nop 0
	s_nop 0
	s_nop 0
	s_nop 0

; #define PG8_STAGE(bufoff, gbase, voff) do { _Pragma("unroll") for (int _i = 0; _i < 2; ++_i) \
;         __builtin_amdgcn_global_load_lds((const unsigned*)((const char*)(gbase) + (voff)[_i]), (LAS unsigned*)(lds + (bufoff) + ldsw + _i * 8192), 16, 0, 0); } while (0)
; #define PG8_LDA(dst, b, h) do { _Pragma("unroll") for (int m = 0; m < 4; ++m) _Pragma("unroll") for (int k = 0; k < 2; ++k) dst[m][k] = *(const LAS bf16x8*)(lds + PG8_SA(b, h) + aoff + m * 2048 + k * 1024); } while (0)
; #define PG8_LDB(dst, b, h) do { _Pragma("unroll") for (int n = 0; n < 2; ++n) _Pragma("unroll") for (int k = 0; k < 2; ++k) dst[n][k] = *(const LAS bf16x8*)(lds + PG8_SB(b, h) + boff + n * 2048 + k * 1024); } while (0)
; #define PG8_MMA(ai, bj, At, Bt) do { __builtin_amdgcn_s_setprio(1); _Pragma("unroll") for (int m = 0; m < 4; ++m) _Pragma("unroll") for (int n = 0; n < 2; ++n) _Pragma("unroll") for (int k = 0; k < 2; ++k) \
;         acc[ai][bj][m][n] = __builtin_amdgcn_mfma_f32_16x16x32_bf16(Bt[n][k], At[m][k], acc[ai][bj][m][n], 0, 0, 0); __builtin_amdgcn_s_setprio(0); } while (0)
; #define PG8_WAIT_V(n) asm volatile("s_waitcnt vmcnt(" #n ")" ::: "memory")
; #define PG8_WAIT_L(n) asm volatile("s_waitcnt lgkmcnt(" #n ")" ::: "memory")
; #define PG8_BAR __builtin_amdgcn_s_barrier()
; template <class Epi, class Sched, bool ALIGN_EPI = false, bool SP2 = false>
; __device__ __forceinline__ void gemm_phase(LAS unsigned char* lds, const Gemm g, const Sched& S, const Epi& E) {
;     ...
;             const char* a1 = cA + (size_t)(t + 1) * kstep;
;             const char* a2 = last ? nA : cA + (size_t)(t + 2) * kstep; const char* b2 = last ? nB : cB + (size_t)(t + 2) * kstep;
;             const char* a3 = a2 + kstep; const char* b3 = b2 + kstep;
;             if (last && has_next) { S.a_ready(nxt); pre_nxt = E.pre(nxt, wr, fr); }
;             if constexpr (SP2) {
;             PG8_LDB(B0, 0, 0); PG8_LDB(B1, 0, 1); PG8_SCHED; PG8_LDA(At, 0, 0); PG8_STAGE(PG8_SA(1, 1), a1 + hstep, voffA);
;             PG8_WAIT_V(8); PG8_WAIT_L(0); PG8_BAR; PG8_MMA(0, 0, At, B0); PG8_MMA(0, 1, At, B1); PG8_BAR; PG8_SCHED;
;             PG8_LDA(At, 0, 1); PG8_STAGE(PG8_SB(0, 0), b2, voffB); PG8_STAGE(PG8_SB(0, 1), b2 + hstep, voffB); PG8_STAGE(PG8_SA(0, 0), a2, voffA);
;             PG8_WAIT_V(8); PG8_WAIT_L(0); PG8_BAR; PG8_MMA(1, 0, At, B0); PG8_MMA(1, 1, At, B1); PG8_BAR; PG8_SCHED;
.LBB0_794:
	ds_read_b128 v[128:131], v191
	ds_read_b128 v[132:135], v191 offset:1024
	ds_read_b128 v[136:139], v191 offset:2048
	ds_read_b128 v[140:143], v191 offset:3072
	ds_read_b128 v[144:147], v192
	ds_read_b128 v[148:151], v192 offset:1024
	ds_read_b128 v[168:171], v192 offset:2048
	ds_read_b128 v[172:175], v192 offset:3072
	s_add_u32 s38, s36, 0x100
	s_addc_u32 s39, s37, 0
	s_cmpk_eq_i32 s62, 0x54
	s_cselect_b32 s43, s1, s39
	s_cselect_b32 s42, s0, s38
	s_cselect_b32 s41, s29, s17
	s_cselect_b32 s40, s28, s16
	s_add_i32 m0, s35, 0xc000
	ds_read_b128 v[178:181], v193
	ds_read_b128 v[182:185], v193 offset:1024
	ds_read_b128 v[194:197], v193 offset:2048
	ds_read_b128 v[198:201], v193 offset:3072
	ds_read_b128 v[202:205], v193 offset:4096
	ds_read_b128 v[206:209], v193 offset:5120
	ds_read_b128 v[210:213], v193 offset:6144
	ds_read_b128 v[214:217], v193 offset:7168
	global_load_lds_dwordx4 v160, s[36:37]
	s_add_i32 m0, s35, 0xe000
	s_nop 0
	global_load_lds_dwordx4 v162, s[36:37]
	s_waitcnt vmcnt(8)
	s_waitcnt lgkmcnt(0)
	s_barrier
	s_setprio 1
	s_waitcnt lgkmcnt(0)
	v_mfma_f32_16x16x32_bf16 v[124:127], v[128:131], v[178:181], v[124:127]
	v_mfma_f32_16x16x32_bf16 v[120:123], v[136:139], v[178:181], v[120:123]
	v_mfma_f32_16x16x32_bf16 v[108:111], v[128:131], v[194:197], v[108:111]
	v_mfma_f32_16x16x32_bf16 v[104:107], v[136:139], v[194:197], v[104:107]
	v_mfma_f32_16x16x32_bf16 v[92:95], v[128:131], v[202:205], v[92:95]
	v_mfma_f32_16x16x32_bf16 v[88:91], v[136:139], v[202:205], v[88:91]
	v_mfma_f32_16x16x32_bf16 v[76:79], v[128:131], v[210:213], v[76:79]
	v_mfma_f32_16x16x32_bf16 v[72:75], v[136:139], v[210:213], v[72:75]
	v_mfma_f32_16x16x32_bf16 v[124:127], v[132:135], v[182:185], v[124:127]
	v_mfma_f32_16x16x32_bf16 v[120:123], v[140:143], v[182:185], v[120:123]
	v_mfma_f32_16x16x32_bf16 v[108:111], v[132:135], v[198:201], v[108:111]
	v_mfma_f32_16x16x32_bf16 v[104:107], v[140:143], v[198:201], v[104:107]
	v_mfma_f32_16x16x32_bf16 v[92:95], v[132:135], v[206:209], v[92:95]
	v_mfma_f32_16x16x32_bf16 v[88:91], v[140:143], v[206:209], v[88:91]
	v_mfma_f32_16x16x32_bf16 v[76:79], v[132:135], v[214:217], v[76:79]
	v_mfma_f32_16x16x32_bf16 v[72:75], v[140:143], v[214:217], v[72:75]
	s_setprio 0
	s_setprio 1
	v_mfma_f32_16x16x32_bf16 v[116:119], v[144:147], v[178:181], v[116:119]
	v_mfma_f32_16x16x32_bf16 v[112:115], v[168:171], v[178:181], v[112:115]
	v_mfma_f32_16x16x32_bf16 v[100:103], v[144:147], v[194:197], v[100:103]
	v_mfma_f32_16x16x32_bf16 v[96:99], v[168:171], v[194:197], v[96:99]
	v_mfma_f32_16x16x32_bf16 v[84:87], v[144:147], v[202:205], v[84:87]
	v_mfma_f32_16x16x32_bf16 v[80:83], v[168:171], v[202:205], v[80:83]
	v_mfma_f32_16x16x32_bf16 v[68:71], v[144:147], v[210:213], v[68:71]
	v_mfma_f32_16x16x32_bf16 v[64:67], v[168:171], v[210:213], v[64:67]
	v_mfma_f32_16x16x32_bf16 v[116:119], v[148:151], v[182:185], v[116:119]
	v_mfma_f32_16x16x32_bf16 v[112:115], v[172:175], v[182:185], v[112:115]
	v_mfma_f32_16x16x32_bf16 v[100:103], v[148:151], v[198:201], v[100:103]
	v_mfma_f32_16x16x32_bf16 v[96:99], v[172:175], v[198:201], v[96:99]
	v_mfma_f32_16x16x32_bf16 v[84:87], v[148:151], v[206:209], v[84:87]
	v_mfma_f32_16x16x32_bf16 v[80:83], v[172:175], v[206:209], v[80:83]
	v_mfma_f32_16x16x32_bf16 v[68:71], v[148:151], v[214:217], v[68:71]
	v_mfma_f32_16x16x32_bf16 v[64:67], v[172:175], v[214:217], v[64:67]
	s_setprio 0
	s_barrier
	s_add_u32 s100, s42, 0x80
	s_addc_u32 s101, s43, 0
	s_add_u32 s98, s40, 0x80
	s_addc_u32 s99, s41, 0
	s_add_i32 s36, s50, s15
	s_mov_b32 m0, s36
	ds_read_b128 v[178:181], v193 offset:16384
	ds_read_b128 v[182:185], v193 offset:17408
	ds_read_b128 v[194:197], v193 offset:18432
	ds_read_b128 v[198:201], v193 offset:19456
	ds_read_b128 v[202:205], v193 offset:20480
	ds_read_b128 v[206:209], v193 offset:21504
	ds_read_b128 v[210:213], v193 offset:22528
	ds_read_b128 v[214:217], v193 offset:23552
	global_load_lds_dwordx4 v154, s[40:41]
	s_add_i32 m0, s36, 0x2000
	s_add_u32 s36, s40, 0x160000
	s_addc_u32 s37, s41, 0
	s_add_i32 s63, s51, s15
	global_load_lds_dwordx4 v158, s[40:41]
	s_mov_b32 m0, s63
	s_nop 0
	global_load_lds_dwordx4 v154, s[36:37]
	s_add_i32 m0, s63, 0x2000
	s_nop 0
	global_load_lds_dwordx4 v158, s[36:37]
	s_mov_b32 m0, s35
	s_nop 0
	global_load_lds_dwordx4 v152, s[42:43]
	s_mov_b32 m0, s44
	s_nop 0
	global_load_lds_dwordx4 v156, s[42:43]
	s_waitcnt vmcnt(8)
	s_waitcnt lgkmcnt(0)
	s_barrier
	s_setprio 1
	s_waitcnt lgkmcnt(0)
	v_mfma_f32_16x16x32_bf16 v[60:63], v[128:131], v[178:181], v[60:63]
	v_mfma_f32_16x16x32_bf16 v[56:59], v[136:139], v[178:181], v[56:59]
	v_mfma_f32_16x16x32_bf16 v[44:47], v[128:131], v[194:197], v[44:47]
	v_mfma_f32_16x16x32_bf16 v[40:43], v[136:139], v[194:197], v[40:43]
	v_mfma_f32_16x16x32_bf16 v[28:31], v[128:131], v[202:205], v[28:31]
	v_mfma_f32_16x16x32_bf16 v[24:27], v[136:139], v[202:205], v[24:27]
	v_mfma_f32_16x16x32_bf16 v[12:15], v[128:131], v[210:213], v[12:15]
	v_mfma_f32_16x16x32_bf16 v[8:11], v[136:139], v[210:213], v[8:11]
	v_mfma_f32_16x16x32_bf16 v[60:63], v[132:135], v[182:185], v[60:63]
	v_mfma_f32_16x16x32_bf16 v[56:59], v[140:143], v[182:185], v[56:59]
	v_mfma_f32_16x16x32_bf16 v[44:47], v[132:135], v[198:201], v[44:47]
	v_mfma_f32_16x16x32_bf16 v[40:43], v[140:143], v[198:201], v[40:43]
	v_mfma_f32_16x16x32_bf16 v[28:31], v[132:135], v[206:209], v[28:31]
	v_mfma_f32_16x16x32_bf16 v[24:27], v[140:143], v[206:209], v[24:27]
	v_mfma_f32_16x16x32_bf16 v[12:15], v[132:135], v[214:217], v[12:15]
	v_mfma_f32_16x16x32_bf16 v[8:11], v[140:143], v[214:217], v[8:11]
	s_setprio 0
	s_setprio 1
	v_mfma_f32_16x16x32_bf16 v[52:55], v[144:147], v[178:181], v[52:55]
	v_mfma_f32_16x16x32_bf16 v[48:51], v[168:171], v[178:181], v[48:51]
	v_mfma_f32_16x16x32_bf16 v[36:39], v[144:147], v[194:197], v[36:39]
	v_mfma_f32_16x16x32_bf16 v[32:35], v[168:171], v[194:197], v[32:35]
	v_mfma_f32_16x16x32_bf16 v[20:23], v[144:147], v[202:205], v[20:23]
	v_mfma_f32_16x16x32_bf16 v[16:19], v[168:171], v[202:205], v[16:19]
	v_mfma_f32_16x16x32_bf16 v[4:7], v[144:147], v[210:213], v[4:7]
	v_mfma_f32_16x16x32_bf16 v[0:3], v[168:171], v[210:213], v[0:3]
	v_mfma_f32_16x16x32_bf16 v[52:55], v[148:151], v[182:185], v[52:55]
	v_mfma_f32_16x16x32_bf16 v[48:51], v[172:175], v[182:185], v[48:51]
	v_mfma_f32_16x16x32_bf16 v[36:39], v[148:151], v[198:201], v[36:39]
	v_mfma_f32_16x16x32_bf16 v[32:35], v[172:175], v[198:201], v[32:35]
	v_mfma_f32_16x16x32_bf16 v[20:23], v[148:151], v[206:209], v[20:23]
	v_mfma_f32_16x16x32_bf16 v[16:19], v[172:175], v[206:209], v[16:19]
	v_mfma_f32_16x16x32_bf16 v[4:7], v[148:151], v[214:217], v[4:7]
	v_mfma_f32_16x16x32_bf16 v[0:3], v[172:175], v[214:217], v[0:3]
	s_setprio 0
	s_barrier
; #define PG8_STAGE(bufoff, gbase, voff) do { _Pragma("unroll") for (int _i = 0; _i < 2; ++_i) \
;         __builtin_amdgcn_global_load_lds((const unsigned*)((const char*)(gbase) + (voff)[_i]), (LAS unsigned*)(lds + (bufoff) + ldsw + _i * 8192), 16, 0, 0); } while (0)
; #define PG8_LDA(dst, b, h) do { _Pragma("unroll") for (int m = 0; m < 4; ++m) _Pragma("unroll") for (int k = 0; k < 2; ++k) dst[m][k] = *(const LAS bf16x8*)(lds + PG8_SA(b, h) + aoff + m * 2048 + k * 1024); } while (0)
; #define PG8_LDB(dst, b, h) do { _Pragma("unroll") for (int n = 0; n < 2; ++n) _Pragma("unroll") for (int k = 0; k < 2; ++k) dst[n][k] = *(const LAS bf16x8*)(lds + PG8_SB(b, h) + boff + n * 2048 + k * 1024); } while (0)
; #define PG8_MMA(ai, bj, At, Bt) do { __builtin_amdgcn_s_setprio(1); _Pragma("unroll") for (int m = 0; m < 4; ++m) _Pragma("unroll") for (int n = 0; n < 2; ++n) _Pragma("unroll") for (int k = 0; k < 2; ++k) \
;         acc[ai][bj][m][n] = __builtin_amdgcn_mfma_f32_16x16x32_bf16(Bt[n][k], At[m][k], acc[ai][bj][m][n], 0, 0, 0); __builtin_amdgcn_s_setprio(0); } while (0)
; #define PG8_WAIT_V(n) asm volatile("s_waitcnt vmcnt(" #n ")" ::: "memory")
; #define PG8_WAIT_L(n) asm volatile("s_waitcnt lgkmcnt(" #n ")" ::: "memory")
; #define PG8_BAR __builtin_amdgcn_s_barrier()
; #define PG8_SCHED __builtin_amdgcn_sched_barrier(0)
; template <class Epi, class Sched, bool ALIGN_EPI = false, bool SP2 = false>
; __device__ __forceinline__ void gemm_phase(LAS unsigned char* lds, const Gemm g, const Sched& S, const Epi& E) {
;     ...
;             PG8_LDB(B0, 1, 0); PG8_LDB(B1, 1, 1); PG8_SCHED; PG8_LDA(At, 1, 0); PG8_STAGE(PG8_SA(0, 1), a2 + hstep, voffA);
;             PG8_WAIT_V(8); PG8_WAIT_L(0); PG8_BAR; PG8_MMA(0, 0, At, B0); PG8_MMA(0, 1, At, B1); PG8_BAR; PG8_SCHED;
;             PG8_LDA(At, 1, 1); PG8_STAGE(PG8_SB(1, 0), b3, voffB); PG8_STAGE(PG8_SB(1, 1), b3 + hstep, voffB); PG8_STAGE(PG8_SA(1, 0), a3, voffA);
;             PG8_WAIT_V(8); PG8_WAIT_L(0); PG8_BAR; PG8_MMA(1, 0, At, B0); PG8_MMA(1, 1, At, B1); PG8_BAR; PG8_SCHED;
;     ...
;         if constexpr (ALIGN_EPI) { if (wr == 0) PG8_BAR; }
	s_add_i32 s63, 0, 0x18000
	s_add_i32 s64, 0, 0x1c000
	v_add_u32_e32 v140, s63, v177
	v_add_u32_e32 v172, s64, v177
	ds_read_b128 v[128:131], v140
	ds_read_b128 v[132:135], v140 offset:1024
	ds_read_b128 v[136:139], v140 offset:2048
	ds_read_b128 v[140:143], v140 offset:3072
	ds_read_b128 v[144:147], v172
	ds_read_b128 v[148:151], v172 offset:1024
	ds_read_b128 v[168:171], v172 offset:2048
	ds_read_b128 v[172:175], v172 offset:3072
	s_add_u32 s36, s42, 0x160000
	s_addc_u32 s37, s43, 0
	s_mov_b32 m0, s45
	ds_read_b128 v[178:181], v193 offset:32768
	ds_read_b128 v[182:185], v193 offset:33792
	ds_read_b128 v[194:197], v193 offset:34816
	ds_read_b128 v[198:201], v193 offset:35840
	ds_read_b128 v[202:205], v193 offset:36864
	ds_read_b128 v[206:209], v193 offset:37888
	ds_read_b128 v[210:213], v193 offset:38912
	ds_read_b128 v[214:217], v193 offset:39936
	global_load_lds_dwordx4 v152, s[36:37]
	s_mov_b32 m0, s46
	s_nop 0
	global_load_lds_dwordx4 v156, s[36:37]
	s_waitcnt vmcnt(8)
	s_waitcnt lgkmcnt(0)
	s_barrier
	s_setprio 1
	s_waitcnt lgkmcnt(0)
	v_mfma_f32_16x16x32_bf16 v[124:127], v[128:131], v[178:181], v[124:127]
	v_mfma_f32_16x16x32_bf16 v[120:123], v[136:139], v[178:181], v[120:123]
	v_mfma_f32_16x16x32_bf16 v[108:111], v[128:131], v[194:197], v[108:111]
	v_mfma_f32_16x16x32_bf16 v[104:107], v[136:139], v[194:197], v[104:107]
	v_mfma_f32_16x16x32_bf16 v[92:95], v[128:131], v[202:205], v[92:95]
	v_mfma_f32_16x16x32_bf16 v[88:91], v[136:139], v[202:205], v[88:91]
	v_mfma_f32_16x16x32_bf16 v[76:79], v[128:131], v[210:213], v[76:79]
	v_mfma_f32_16x16x32_bf16 v[72:75], v[136:139], v[210:213], v[72:75]
	v_mfma_f32_16x16x32_bf16 v[124:127], v[132:135], v[182:185], v[124:127]
	v_mfma_f32_16x16x32_bf16 v[120:123], v[140:143], v[182:185], v[120:123]
	v_mfma_f32_16x16x32_bf16 v[108:111], v[132:135], v[198:201], v[108:111]
	v_mfma_f32_16x16x32_bf16 v[104:107], v[140:143], v[198:201], v[104:107]
	v_mfma_f32_16x16x32_bf16 v[92:95], v[132:135], v[206:209], v[92:95]
	v_mfma_f32_16x16x32_bf16 v[88:91], v[140:143], v[206:209], v[88:91]
	v_mfma_f32_16x16x32_bf16 v[76:79], v[132:135], v[214:217], v[76:79]
	v_mfma_f32_16x16x32_bf16 v[72:75], v[140:143], v[214:217], v[72:75]
	s_setprio 0
	s_setprio 1
	v_mfma_f32_16x16x32_bf16 v[116:119], v[144:147], v[178:181], v[116:119]
	v_mfma_f32_16x16x32_bf16 v[112:115], v[168:171], v[178:181], v[112:115]
	v_mfma_f32_16x16x32_bf16 v[100:103], v[144:147], v[194:197], v[100:103]
	v_mfma_f32_16x16x32_bf16 v[96:99], v[168:171], v[194:197], v[96:99]
	v_mfma_f32_16x16x32_bf16 v[84:87], v[144:147], v[202:205], v[84:87]
	v_mfma_f32_16x16x32_bf16 v[80:83], v[168:171], v[202:205], v[80:83]
	v_mfma_f32_16x16x32_bf16 v[68:71], v[144:147], v[210:213], v[68:71]
	v_mfma_f32_16x16x32_bf16 v[64:67], v[168:171], v[210:213], v[64:67]
	v_mfma_f32_16x16x32_bf16 v[116:119], v[148:151], v[182:185], v[116:119]
	v_mfma_f32_16x16x32_bf16 v[112:115], v[172:175], v[182:185], v[112:115]
	v_mfma_f32_16x16x32_bf16 v[100:103], v[148:151], v[198:201], v[100:103]
	v_mfma_f32_16x16x32_bf16 v[96:99], v[172:175], v[198:201], v[96:99]
	v_mfma_f32_16x16x32_bf16 v[84:87], v[148:151], v[206:209], v[84:87]
	v_mfma_f32_16x16x32_bf16 v[80:83], v[172:175], v[206:209], v[80:83]
	v_mfma_f32_16x16x32_bf16 v[68:71], v[148:151], v[214:217], v[68:71]
	v_mfma_f32_16x16x32_bf16 v[64:67], v[172:175], v[214:217], v[64:67]
	s_setprio 0
	s_barrier
	s_add_i32 s36, s63, s15
	s_mov_b32 m0, s36
	ds_read_b128 v[178:181], v193 offset:49152
	ds_read_b128 v[182:185], v193 offset:50176
	ds_read_b128 v[194:197], v193 offset:51200
	ds_read_b128 v[198:201], v193 offset:52224
	ds_read_b128 v[202:205], v193 offset:53248
	ds_read_b128 v[206:209], v193 offset:54272
	ds_read_b128 v[210:213], v193 offset:55296
	ds_read_b128 v[214:217], v193 offset:56320
	global_load_lds_dwordx4 v154, s[98:99]
	s_add_i32 m0, s36, 0x2000
	s_add_u32 s36, s40, 0x160080
	s_addc_u32 s37, s41, 0
	s_add_i32 s40, s64, s15
	global_load_lds_dwordx4 v158, s[98:99]
	s_mov_b32 m0, s40
	s_nop 0
	global_load_lds_dwordx4 v154, s[36:37]
	s_add_i32 m0, s40, 0x2000
	s_nop 0
	global_load_lds_dwordx4 v158, s[36:37]
	s_mov_b32 m0, s48
	s_nop 0
	global_load_lds_dwordx4 v152, s[100:101]
	s_mov_b32 m0, s49
	s_nop 0
	global_load_lds_dwordx4 v156, s[100:101]
	s_waitcnt vmcnt(8)
	s_waitcnt lgkmcnt(0)
	s_barrier
	s_setprio 1
	s_waitcnt lgkmcnt(0)
	v_mfma_f32_16x16x32_bf16 v[60:63], v[128:131], v[178:181], v[60:63]
	v_mfma_f32_16x16x32_bf16 v[56:59], v[136:139], v[178:181], v[56:59]
	v_mfma_f32_16x16x32_bf16 v[44:47], v[128:131], v[194:197], v[44:47]
	v_mfma_f32_16x16x32_bf16 v[40:43], v[136:139], v[194:197], v[40:43]
	v_mfma_f32_16x16x32_bf16 v[28:31], v[128:131], v[202:205], v[28:31]
	v_mfma_f32_16x16x32_bf16 v[24:27], v[136:139], v[202:205], v[24:27]
	v_mfma_f32_16x16x32_bf16 v[12:15], v[128:131], v[210:213], v[12:15]
	v_mfma_f32_16x16x32_bf16 v[8:11], v[136:139], v[210:213], v[8:11]
	v_mfma_f32_16x16x32_bf16 v[60:63], v[132:135], v[182:185], v[60:63]
	v_mfma_f32_16x16x32_bf16 v[56:59], v[140:143], v[182:185], v[56:59]
	v_mfma_f32_16x16x32_bf16 v[44:47], v[132:135], v[198:201], v[44:47]
	v_mfma_f32_16x16x32_bf16 v[40:43], v[140:143], v[198:201], v[40:43]
	v_mfma_f32_16x16x32_bf16 v[28:31], v[132:135], v[206:209], v[28:31]
	v_mfma_f32_16x16x32_bf16 v[24:27], v[140:143], v[206:209], v[24:27]
	v_mfma_f32_16x16x32_bf16 v[12:15], v[132:135], v[214:217], v[12:15]
	v_mfma_f32_16x16x32_bf16 v[8:11], v[140:143], v[214:217], v[8:11]
	s_setprio 0
	s_setprio 1
	v_mfma_f32_16x16x32_bf16 v[52:55], v[144:147], v[178:181], v[52:55]
	v_mfma_f32_16x16x32_bf16 v[48:51], v[168:171], v[178:181], v[48:51]
	v_mfma_f32_16x16x32_bf16 v[36:39], v[144:147], v[194:197], v[36:39]
	v_mfma_f32_16x16x32_bf16 v[32:35], v[168:171], v[194:197], v[32:35]
	v_mfma_f32_16x16x32_bf16 v[20:23], v[144:147], v[202:205], v[20:23]
	v_mfma_f32_16x16x32_bf16 v[16:19], v[168:171], v[202:205], v[16:19]
	v_mfma_f32_16x16x32_bf16 v[4:7], v[144:147], v[210:213], v[4:7]
	v_mfma_f32_16x16x32_bf16 v[0:3], v[168:171], v[210:213], v[0:3]
	v_mfma_f32_16x16x32_bf16 v[52:55], v[148:151], v[182:185], v[52:55]
	v_mfma_f32_16x16x32_bf16 v[48:51], v[172:175], v[182:185], v[48:51]
	v_mfma_f32_16x16x32_bf16 v[36:39], v[148:151], v[198:201], v[36:39]
	v_mfma_f32_16x16x32_bf16 v[32:35], v[172:175], v[198:201], v[32:35]
	v_mfma_f32_16x16x32_bf16 v[20:23], v[148:151], v[206:209], v[20:23]
	v_mfma_f32_16x16x32_bf16 v[16:19], v[172:175], v[206:209], v[16:19]
	v_mfma_f32_16x16x32_bf16 v[4:7], v[148:151], v[214:217], v[4:7]
	v_mfma_f32_16x16x32_bf16 v[0:3], v[172:175], v[214:217], v[0:3]
	s_setprio 0
	s_barrier
	s_add_i32 s62, s62, 2
	s_add_u32 s16, s16, 0x100
	s_addc_u32 s17, s17, 0
	s_cmpk_gt_u32 s62, 0x55
	s_mov_b64 s[36:37], s[38:39]
	s_cbranch_scc0 .LBB0_794
	s_branch .Lsapad3
	s_nop 0
	s_nop 0
	s_nop 0
	s_nop 0
	s_nop 0
	s_nop 0
	s_nop 0
	s_nop 0
	s_nop 0
	s_nop 0
	s_nop 0
	s_nop 0
	s_nop 0
	s_nop 0
	s_nop 0
	s_nop 0
	s_nop 0
	s_nop 0
	s_nop 0
	s_nop 0
	s_nop 0
	s_nop 0
	s_nop 0
	s_nop 0
.Lsapad3:
	s_and_b64 vcc, exec, s[26:27]
	s_cbranch_vccz .LBB0_797
	s_barrier

; __global__ void __launch_bounds__(NWAVES * 64, 2) fwd_kernel(Args args) {
	.amdhsa_kernel _Z10fwd_kernel4Args
		.amdhsa_group_segment_fixed_size 0
		.amdhsa_private_segment_fixed_size 0
		.amdhsa_kernarg_size 400
		.amdhsa_user_sgpr_count 2
		.amdhsa_user_sgpr_dispatch_ptr 0
		.amdhsa_user_sgpr_queue_ptr 0
		.amdhsa_user_sgpr_kernarg_segment_ptr 1
		.amdhsa_user_sgpr_dispatch_id 0
		.amdhsa_user_sgpr_kernarg_preload_length 0
		.amdhsa_user_sgpr_kernarg_preload_offset 0
		.amdhsa_user_sgpr_private_segment_size 0
		.amdhsa_uses_dynamic_stack 0
		.amdhsa_enable_private_segment 0
		.amdhsa_system_sgpr_workgroup_id_x 1
		.amdhsa_system_sgpr_workgroup_id_y 0
		.amdhsa_system_sgpr_workgroup_id_z 0
		.amdhsa_system_sgpr_workgroup_info 0
		.amdhsa_system_vgpr_workitem_id 2
		.amdhsa_next_free_vgpr 253
		.amdhsa_next_free_sgpr 102
		.amdhsa_accum_offset 256
		.amdhsa_reserve_vcc 1
		.amdhsa_float_round_mode_32 0
		.amdhsa_float_round_mode_16_64 0
		.amdhsa_float_denorm_mode_32 3
		.amdhsa_float_denorm_mode_16_64 3
		.amdhsa_dx10_clamp 1
		.amdhsa_ieee_mode 1
		.amdhsa_fp16_overflow 0
		.amdhsa_tg_split 0
		.amdhsa_exception_fp_ieee_invalid_op 0
		.amdhsa_exception_fp_denorm_src 0
		.amdhsa_exception_fp_ieee_div_zero 0
		.amdhsa_exception_fp_ieee_overflow 0
		.amdhsa_exception_fp_ieee_underflow 0
		.amdhsa_exception_fp_ieee_inexact 0
		.amdhsa_exception_int_div_zero 0
	.end_amdhsa_kernel

; __global__ void __launch_bounds__(NWAVES * 64, 2) fwd_kernel(Args args) {
amdhsa.kernels:
  - .agpr_count:     0
    .args:
      - .offset:         0
        .size:           144
        .value_kind:     by_value
      - .offset:         144
        .size:           4
        .value_kind:     hidden_block_count_x
      - .offset:         148
        .size:           4
        .value_kind:     hidden_block_count_y
      - .offset:         152
        .size:           4
        .value_kind:     hidden_block_count_z
      - .offset:         156
        .size:           2
        .value_kind:     hidden_group_size_x
      - .offset:         158
        .size:           2
        .value_kind:     hidden_group_size_y
      - .offset:         160
        .size:           2
        .value_kind:     hidden_group_size_z
      - .offset:         162
        .size:           2
        .value_kind:     hidden_remainder_x
      - .offset:         164
        .size:           2
        .value_kind:     hidden_remainder_y
      - .offset:         166
        .size:           2
        .value_kind:     hidden_remainder_z
      - .offset:         184
        .size:           8
        .value_kind:     hidden_global_offset_x
      - .offset:         192
        .size:           8
        .value_kind:     hidden_global_offset_y
      - .offset:         200
        .size:           8
        .value_kind:     hidden_global_offset_z
      - .offset:         208
        .size:           2
        .value_kind:     hidden_grid_dims
      - .offset:         232
        .size:           8
        .value_kind:     hidden_multigrid_sync_arg
      - .offset:         264
        .size:           4
        .value_kind:     hidden_dynamic_lds_size
    .group_segment_fixed_size: 0
    .kernarg_segment_align: 8
    .kernarg_segment_size: 400
    .language:       OpenCL C
    .language_version:
      - 2
      - 0
    .max_flat_workgroup_size: 512
    .name:           _Z10fwd_kernel4Args
    .private_segment_fixed_size: 0
    .sgpr_count:     108
    .sgpr_spill_count: 3
    .symbol:         _Z10fwd_kernel4Args.kd
    .uniform_work_group_size: 1
    .uses_dynamic_stack: false
    .vgpr_count:     253
    .vgpr_spill_count: 0
    .wavefront_size: 64
